# early L1 invalidate in grid barriers + all per-phase s_setprio flips in the GEMM main loops deleted (A/B of the priority flips)
# speedup vs baseline: 1.0075x; 1.0075x over previous
; #define PG8_STAGE(bufoff, gbase, voff) do { _Pragma("unroll") for (int _i = 0; _i < 2; ++_i) \
;         __builtin_amdgcn_global_load_lds((const unsigned*)((const char*)(gbase) + (voff)[_i]), (LAS unsigned*)(lds + (bufoff) + ldsw + _i * 8192), 16, 0, 0); } while (0)
; #define PG8_LDA(dst, b, h) do { _Pragma("unroll") for (int m = 0; m < 4; ++m) _Pragma("unroll") for (int k = 0; k < 2; ++k) dst[m][k] = *(const LAS bf16x8*)(lds + PG8_SA(b, h) + aoff + m * 2048 + k * 1024); } while (0)
; #define PG8_LDB(dst, b, h) do { _Pragma("unroll") for (int n = 0; n < 2; ++n) _Pragma("unroll") for (int k = 0; k < 2; ++k) dst[n][k] = *(const LAS bf16x8*)(lds + PG8_SB(b, h) + boff + n * 2048 + k * 1024); } while (0)
; #define PG8_MMA(ai, bj, At, Bt) do { __builtin_amdgcn_s_setprio(1); _Pragma("unroll") for (int m = 0; m < 4; ++m) _Pragma("unroll") for (int n = 0; n < 2; ++n) _Pragma("unroll") for (int k = 0; k < 2; ++k) \
;         acc[ai][bj][m][n] = __builtin_amdgcn_mfma_f32_16x16x32_bf16(Bt[n][k], At[m][k], acc[ai][bj][m][n], 0, 0, 0); __builtin_amdgcn_s_setprio(0); } while (0)
; #define PG8_WAIT_V(n) asm volatile("s_waitcnt vmcnt(" #n ")" ::: "memory")
; #define PG8_WAIT_L(n) asm volatile("s_waitcnt lgkmcnt(" #n ")" ::: "memory")
; #define PG8_BAR __builtin_amdgcn_s_barrier()
; #define PG8_SCHED __builtin_amdgcn_sched_barrier(0)
; #define PG8_BAR __builtin_amdgcn_s_barrier()
; template <class Epi, class Sched>
; DI void gemm_phase(LAS unsigned char* lds, const Gemm g, const Sched& S, const Epi& E) {
;     ...
;         for (int t = 0; t < nt; t += 2) {
;             const bool last = (t == nt - 2);
;             const char* a1 = cA + (size_t)(t + 1) * kstep;
;             const char* a2 = last ? nA : cA + (size_t)(t + 2) * kstep; const char* b2 = last ? nB : cB + (size_t)(t + 2) * kstep;
;             const char* a3 = a2 + kstep; const char* b3 = b2 + kstep;
;             PG8_LDB(B0, 0, 0); PG8_LDB(B1, 0, 1); PG8_SCHED; PG8_LDA(At, 0, 0); PG8_STAGE(PG8_SA(1, 1), a1 + hstepA, voffA);
;             PG8_WAIT_V(8); PG8_WAIT_L(0); PG8_BAR; PG8_MMA(0, 0, At, B0); PG8_MMA(0, 1, At, B1); PG8_BAR; PG8_SCHED;
;             PG8_LDA(At, 0, 1); PG8_STAGE(PG8_SB(0, 0), b2, voffB); PG8_STAGE(PG8_SB(0, 1), b2 + hstepB, voffB); PG8_STAGE(PG8_SA(0, 0), a2, voffA);
;             PG8_WAIT_V(8); PG8_WAIT_L(0); PG8_BAR; PG8_MMA(1, 0, At, B0); PG8_MMA(1, 1, At, B1); PG8_BAR; PG8_SCHED;
.LBB0_208:
	s_add_u32 s36, s74, s30
	s_addc_u32 s37, s75, s31
	s_add_u32 s36, s36, 0x100
	s_addc_u32 s37, s37, 0
	s_add_u32 s86, s16, s30
	s_addc_u32 s87, s17, s31
	s_add_i32 s88, 0, 0x10000
	s_cmpk_eq_i32 s30, 0x700
	s_cselect_b32 s39, s28, s37
	s_cselect_b32 s38, s40, s36
	s_cselect_b32 s37, s41, s87
	s_cselect_b32 s36, s77, s86
	s_add_i32 s89, 0, 0x14000
	v_add_u32_e32 v146, s88, v200
	v_add_u32_e32 v180, s89, v200
	ds_read_b128 v[134:137], v146
	ds_read_b128 v[138:141], v146 offset:1024
	ds_read_b128 v[142:145], v146 offset:2048
	ds_read_b128 v[146:149], v146 offset:3072
	ds_read_b128 v[150:153], v180
	ds_read_b128 v[154:157], v180 offset:1024
	ds_read_b128 v[158:161], v180 offset:2048
	ds_read_b128 v[180:183], v180 offset:3072
	v_lshl_add_u64 v[204:205], v[130:131], 0, s[30:31]
	s_add_i32 m0, s52, 0xc000
	ds_read_b128 v[184:187], v208
	ds_read_b128 v[188:191], v208 offset:1024
	ds_read_b128 v[192:195], v208 offset:2048
	ds_read_b128 v[210:213], v208 offset:3072
	ds_read_b128 v[214:217], v208 offset:4096
	ds_read_b128 v[218:221], v208 offset:5120
	ds_read_b128 v[222:225], v208 offset:6144
	ds_read_b128 v[226:229], v208 offset:7168
	global_load_lds_dwordx4 v[204:205], off
	v_lshl_add_u64 v[204:205], v[132:133], 0, s[30:31]
	s_add_i32 m0, s52, 0xe000
	s_nop 0
	global_load_lds_dwordx4 v[204:205], off
	s_waitcnt vmcnt(8)
	s_waitcnt lgkmcnt(0)
	s_barrier
	s_waitcnt lgkmcnt(0)
	v_mfma_f32_16x16x32_bf16 v[126:129], v[134:137], v[184:187], v[126:129]
	v_mfma_f32_16x16x32_bf16 v[122:125], v[142:145], v[184:187], v[122:125]
	v_mfma_f32_16x16x32_bf16 v[118:121], v[134:137], v[192:195], v[118:121]
	v_mfma_f32_16x16x32_bf16 v[114:117], v[142:145], v[192:195], v[114:117]
	v_mfma_f32_16x16x32_bf16 v[110:113], v[134:137], v[214:217], v[110:113]
	v_mfma_f32_16x16x32_bf16 v[106:109], v[142:145], v[214:217], v[106:109]
	v_mfma_f32_16x16x32_bf16 v[102:105], v[134:137], v[222:225], v[102:105]
	v_mfma_f32_16x16x32_bf16 v[98:101], v[142:145], v[222:225], v[98:101]
	v_mfma_f32_16x16x32_bf16 v[126:129], v[138:141], v[188:191], v[126:129]
	v_mfma_f32_16x16x32_bf16 v[122:125], v[146:149], v[188:191], v[122:125]
	v_mfma_f32_16x16x32_bf16 v[118:121], v[138:141], v[210:213], v[118:121]
	v_mfma_f32_16x16x32_bf16 v[114:117], v[146:149], v[210:213], v[114:117]
	v_mfma_f32_16x16x32_bf16 v[110:113], v[138:141], v[218:221], v[110:113]
	v_mfma_f32_16x16x32_bf16 v[106:109], v[146:149], v[218:221], v[106:109]
	v_mfma_f32_16x16x32_bf16 v[102:105], v[138:141], v[226:229], v[102:105]
	v_mfma_f32_16x16x32_bf16 v[98:101], v[146:149], v[226:229], v[98:101]
	v_mfma_f32_16x16x32_bf16 v[94:97], v[150:153], v[184:187], v[94:97]
	v_mfma_f32_16x16x32_bf16 v[90:93], v[158:161], v[184:187], v[90:93]
	v_mfma_f32_16x16x32_bf16 v[86:89], v[150:153], v[192:195], v[86:89]
	v_mfma_f32_16x16x32_bf16 v[82:85], v[158:161], v[192:195], v[82:85]
	v_mfma_f32_16x16x32_bf16 v[78:81], v[150:153], v[214:217], v[78:81]
	v_mfma_f32_16x16x32_bf16 v[74:77], v[158:161], v[214:217], v[74:77]
	v_mfma_f32_16x16x32_bf16 v[70:73], v[150:153], v[222:225], v[70:73]
	v_mfma_f32_16x16x32_bf16 v[66:69], v[158:161], v[222:225], v[66:69]
	v_mfma_f32_16x16x32_bf16 v[94:97], v[154:157], v[188:191], v[94:97]
	v_mfma_f32_16x16x32_bf16 v[90:93], v[180:183], v[188:191], v[90:93]
	v_mfma_f32_16x16x32_bf16 v[86:89], v[154:157], v[210:213], v[86:89]
	v_mfma_f32_16x16x32_bf16 v[82:85], v[180:183], v[210:213], v[82:85]
	v_mfma_f32_16x16x32_bf16 v[78:81], v[154:157], v[218:221], v[78:81]
	v_mfma_f32_16x16x32_bf16 v[74:77], v[180:183], v[218:221], v[74:77]
	v_mfma_f32_16x16x32_bf16 v[70:73], v[154:157], v[226:229], v[70:73]
	v_mfma_f32_16x16x32_bf16 v[66:69], v[180:183], v[226:229], v[66:69]
	s_barrier
	s_add_i32 s86, s88, s51
	v_lshl_add_u64 v[204:205], s[36:37], 0, v[164:165]
	s_mov_b32 m0, s86
	ds_read_b128 v[184:187], v208 offset:16384
	ds_read_b128 v[188:191], v208 offset:17408
	ds_read_b128 v[192:195], v208 offset:18432
	ds_read_b128 v[210:213], v208 offset:19456
	ds_read_b128 v[214:217], v208 offset:20480
	ds_read_b128 v[218:221], v208 offset:21504
	ds_read_b128 v[222:225], v208 offset:22528
	ds_read_b128 v[226:229], v208 offset:23552
	global_load_lds_dwordx4 v[204:205], off
	s_add_i32 m0, s86, 0x2000
	s_add_u32 s86, s36, 0x40000
	v_lshl_add_u64 v[206:207], s[36:37], 0, v[168:169]
	s_addc_u32 s87, s37, 0
	s_add_i32 s88, s89, s51
	global_load_lds_dwordx4 v[206:207], off
	v_lshl_add_u64 v[230:231], s[86:87], 0, v[164:165]
	s_mov_b32 m0, s88
	v_lshl_add_u64 v[232:233], s[38:39], 0, v[166:167]
	global_load_lds_dwordx4 v[230:231], off
	v_lshl_add_u64 v[230:231], s[86:87], 0, v[168:169]
	s_add_i32 m0, s88, 0x2000
	s_nop 0
	global_load_lds_dwordx4 v[230:231], off
	v_lshl_add_u64 v[230:231], s[38:39], 0, v[162:163]
	s_mov_b32 m0, s52
	s_nop 0
	global_load_lds_dwordx4 v[230:231], off
	s_mov_b32 m0, s53
	s_nop 0
	global_load_lds_dwordx4 v[232:233], off
	s_waitcnt vmcnt(8)
	s_waitcnt lgkmcnt(0)
	s_barrier
; #define PG8_STAGE(bufoff, gbase, voff) do { _Pragma("unroll") for (int _i = 0; _i < 2; ++_i) \
;         __builtin_amdgcn_global_load_lds((const unsigned*)((const char*)(gbase) + (voff)[_i]), (LAS unsigned*)(lds + (bufoff) + ldsw + _i * 8192), 16, 0, 0); } while (0)
; #define PG8_LDA(dst, b, h) do { _Pragma("unroll") for (int m = 0; m < 4; ++m) _Pragma("unroll") for (int k = 0; k < 2; ++k) dst[m][k] = *(const LAS bf16x8*)(lds + PG8_SA(b, h) + aoff + m * 2048 + k * 1024); } while (0)
; #define PG8_LDB(dst, b, h) do { _Pragma("unroll") for (int n = 0; n < 2; ++n) _Pragma("unroll") for (int k = 0; k < 2; ++k) dst[n][k] = *(const LAS bf16x8*)(lds + PG8_SB(b, h) + boff + n * 2048 + k * 1024); } while (0)
; #define PG8_MMA(ai, bj, At, Bt) do { __builtin_amdgcn_s_setprio(1); _Pragma("unroll") for (int m = 0; m < 4; ++m) _Pragma("unroll") for (int n = 0; n < 2; ++n) _Pragma("unroll") for (int k = 0; k < 2; ++k) \
;         acc[ai][bj][m][n] = __builtin_amdgcn_mfma_f32_16x16x32_bf16(Bt[n][k], At[m][k], acc[ai][bj][m][n], 0, 0, 0); __builtin_amdgcn_s_setprio(0); } while (0)
; #define PG8_WAIT_V(n) asm volatile("s_waitcnt vmcnt(" #n ")" ::: "memory")
; #define PG8_WAIT_L(n) asm volatile("s_waitcnt lgkmcnt(" #n ")" ::: "memory")
; #define PG8_BAR __builtin_amdgcn_s_barrier()
; #define PG8_SCHED __builtin_amdgcn_sched_barrier(0)
; #define PG8_LDA(dst, b, h) do { _Pragma("unroll") for (int m = 0; m < 4; ++m) _Pragma("unroll") for (int k = 0; k < 2; ++k) dst[m][k] = *(const LAS bf16x8*)(lds + PG8_SA(b, h) + aoff + m * 2048 + k * 1024); } while (0)
; #define PG8_WAIT_V(n) asm volatile("s_waitcnt vmcnt(" #n ")" ::: "memory")
; #define PG8_WAIT_L(n) asm volatile("s_waitcnt lgkmcnt(" #n ")" ::: "memory")
; template <class Epi, class Sched>
; DI void gemm_phase(LAS unsigned char* lds, const Gemm g, const Sched& S, const Epi& E) {
;     ...
;             PG8_WAIT_V(8); PG8_WAIT_L(0); PG8_BAR; PG8_MMA(1, 0, At, B0); PG8_MMA(1, 1, At, B1); PG8_BAR; PG8_SCHED;
;             PG8_LDB(B0, 1, 0); PG8_LDB(B1, 1, 1); PG8_SCHED; PG8_LDA(At, 1, 0); PG8_STAGE(PG8_SA(0, 1), a2 + hstepA, voffA);
;             PG8_WAIT_V(8); PG8_WAIT_L(0); PG8_BAR; PG8_MMA(0, 0, At, B0); PG8_MMA(0, 1, At, B1); PG8_BAR; PG8_SCHED;
;             PG8_LDA(At, 1, 1); PG8_STAGE(PG8_SB(1, 0), b3, voffB); PG8_STAGE(PG8_SB(1, 1), b3 + hstepB, voffB); PG8_STAGE(PG8_SA(1, 0), a3, voffA);
	s_waitcnt lgkmcnt(0)
	v_mfma_f32_16x16x32_bf16 v[62:65], v[134:137], v[184:187], v[62:65]
	v_mfma_f32_16x16x32_bf16 v[58:61], v[142:145], v[184:187], v[58:61]
	v_mfma_f32_16x16x32_bf16 v[54:57], v[134:137], v[192:195], v[54:57]
	v_mfma_f32_16x16x32_bf16 v[50:53], v[142:145], v[192:195], v[50:53]
	v_mfma_f32_16x16x32_bf16 v[46:49], v[134:137], v[214:217], v[46:49]
	v_mfma_f32_16x16x32_bf16 v[42:45], v[142:145], v[214:217], v[42:45]
	v_mfma_f32_16x16x32_bf16 v[38:41], v[134:137], v[222:225], v[38:41]
	v_mfma_f32_16x16x32_bf16 v[34:37], v[142:145], v[222:225], v[34:37]
	v_mfma_f32_16x16x32_bf16 v[62:65], v[138:141], v[188:191], v[62:65]
	v_mfma_f32_16x16x32_bf16 v[58:61], v[146:149], v[188:191], v[58:61]
	v_mfma_f32_16x16x32_bf16 v[54:57], v[138:141], v[210:213], v[54:57]
	v_mfma_f32_16x16x32_bf16 v[50:53], v[146:149], v[210:213], v[50:53]
	v_mfma_f32_16x16x32_bf16 v[46:49], v[138:141], v[218:221], v[46:49]
	v_mfma_f32_16x16x32_bf16 v[42:45], v[146:149], v[218:221], v[42:45]
	v_mfma_f32_16x16x32_bf16 v[38:41], v[138:141], v[226:229], v[38:41]
	v_mfma_f32_16x16x32_bf16 v[34:37], v[146:149], v[226:229], v[34:37]
	v_mfma_f32_16x16x32_bf16 v[30:33], v[150:153], v[184:187], v[30:33]
	v_mfma_f32_16x16x32_bf16 v[26:29], v[158:161], v[184:187], v[26:29]
	v_mfma_f32_16x16x32_bf16 v[22:25], v[150:153], v[192:195], v[22:25]
	v_mfma_f32_16x16x32_bf16 v[18:21], v[158:161], v[192:195], v[18:21]
	v_mfma_f32_16x16x32_bf16 v[14:17], v[150:153], v[214:217], v[14:17]
	v_mfma_f32_16x16x32_bf16 v[10:13], v[158:161], v[214:217], v[10:13]
	v_mfma_f32_16x16x32_bf16 v[6:9], v[150:153], v[222:225], v[6:9]
	v_mfma_f32_16x16x32_bf16 v[2:5], v[158:161], v[222:225], v[2:5]
	v_mfma_f32_16x16x32_bf16 v[30:33], v[154:157], v[188:191], v[30:33]
	v_mfma_f32_16x16x32_bf16 v[26:29], v[180:183], v[188:191], v[26:29]
	v_mfma_f32_16x16x32_bf16 v[22:25], v[154:157], v[210:213], v[22:25]
	v_mfma_f32_16x16x32_bf16 v[18:21], v[180:183], v[210:213], v[18:21]
	v_mfma_f32_16x16x32_bf16 v[14:17], v[154:157], v[218:221], v[14:17]
	v_mfma_f32_16x16x32_bf16 v[10:13], v[180:183], v[218:221], v[10:13]
	v_mfma_f32_16x16x32_bf16 v[6:9], v[154:157], v[226:229], v[6:9]
	v_mfma_f32_16x16x32_bf16 v[2:5], v[180:183], v[226:229], v[2:5]
	s_barrier
	s_add_i32 s86, 0, 0x18000
	s_add_i32 s87, 0, 0x1c000
	v_add_u32_e32 v146, s86, v200
	v_add_u32_e32 v180, s87, v200
	ds_read_b128 v[134:137], v146
	ds_read_b128 v[138:141], v146 offset:1024
	ds_read_b128 v[142:145], v146 offset:2048
	ds_read_b128 v[146:149], v146 offset:3072
	ds_read_b128 v[150:153], v180
	ds_read_b128 v[154:157], v180 offset:1024
	ds_read_b128 v[158:161], v180 offset:2048
	ds_read_b128 v[180:183], v180 offset:3072
	s_add_u32 s38, s38, 0x40000
	s_addc_u32 s39, s39, 0
	s_mov_b32 m0, s65
	v_lshl_add_u64 v[234:235], s[38:39], 0, v[162:163]
	ds_read_b128 v[184:187], v208 offset:32768
	ds_read_b128 v[188:191], v208 offset:33792
	ds_read_b128 v[192:195], v208 offset:34816
	ds_read_b128 v[210:213], v208 offset:35840
	ds_read_b128 v[214:217], v208 offset:36864
	ds_read_b128 v[218:221], v208 offset:37888
	ds_read_b128 v[222:225], v208 offset:38912
	ds_read_b128 v[226:229], v208 offset:39936
	global_load_lds_dwordx4 v[234:235], off
	v_lshl_add_u64 v[234:235], s[38:39], 0, v[166:167]
	s_mov_b32 m0, s67
	s_nop 0
	global_load_lds_dwordx4 v[234:235], off
	s_waitcnt vmcnt(8)
	s_waitcnt lgkmcnt(0)
	s_barrier
	s_waitcnt lgkmcnt(0)
	v_mfma_f32_16x16x32_bf16 v[126:129], v[134:137], v[184:187], v[126:129]
	v_mfma_f32_16x16x32_bf16 v[122:125], v[142:145], v[184:187], v[122:125]
	v_mfma_f32_16x16x32_bf16 v[118:121], v[134:137], v[192:195], v[118:121]
	v_mfma_f32_16x16x32_bf16 v[114:117], v[142:145], v[192:195], v[114:117]
	v_mfma_f32_16x16x32_bf16 v[110:113], v[134:137], v[214:217], v[110:113]
	v_mfma_f32_16x16x32_bf16 v[106:109], v[142:145], v[214:217], v[106:109]
	v_mfma_f32_16x16x32_bf16 v[102:105], v[134:137], v[222:225], v[102:105]
	v_mfma_f32_16x16x32_bf16 v[98:101], v[142:145], v[222:225], v[98:101]
	v_mfma_f32_16x16x32_bf16 v[126:129], v[138:141], v[188:191], v[126:129]
	v_mfma_f32_16x16x32_bf16 v[122:125], v[146:149], v[188:191], v[122:125]
	v_mfma_f32_16x16x32_bf16 v[118:121], v[138:141], v[210:213], v[118:121]
	v_mfma_f32_16x16x32_bf16 v[114:117], v[146:149], v[210:213], v[114:117]
	v_mfma_f32_16x16x32_bf16 v[110:113], v[138:141], v[218:221], v[110:113]
	v_mfma_f32_16x16x32_bf16 v[106:109], v[146:149], v[218:221], v[106:109]
	v_mfma_f32_16x16x32_bf16 v[102:105], v[138:141], v[226:229], v[102:105]
	v_mfma_f32_16x16x32_bf16 v[98:101], v[146:149], v[226:229], v[98:101]
	v_mfma_f32_16x16x32_bf16 v[94:97], v[150:153], v[184:187], v[94:97]
	v_mfma_f32_16x16x32_bf16 v[90:93], v[158:161], v[184:187], v[90:93]
	v_mfma_f32_16x16x32_bf16 v[86:89], v[150:153], v[192:195], v[86:89]
	v_mfma_f32_16x16x32_bf16 v[82:85], v[158:161], v[192:195], v[82:85]
	v_mfma_f32_16x16x32_bf16 v[78:81], v[150:153], v[214:217], v[78:81]
	v_mfma_f32_16x16x32_bf16 v[74:77], v[158:161], v[214:217], v[74:77]
	v_mfma_f32_16x16x32_bf16 v[70:73], v[150:153], v[222:225], v[70:73]
	v_mfma_f32_16x16x32_bf16 v[66:69], v[158:161], v[222:225], v[66:69]
	v_mfma_f32_16x16x32_bf16 v[94:97], v[154:157], v[188:191], v[94:97]
	v_mfma_f32_16x16x32_bf16 v[90:93], v[180:183], v[188:191], v[90:93]
	v_mfma_f32_16x16x32_bf16 v[86:89], v[154:157], v[210:213], v[86:89]
	v_mfma_f32_16x16x32_bf16 v[82:85], v[180:183], v[210:213], v[82:85]
	v_mfma_f32_16x16x32_bf16 v[78:81], v[154:157], v[218:221], v[78:81]
	v_mfma_f32_16x16x32_bf16 v[74:77], v[180:183], v[218:221], v[74:77]
	v_mfma_f32_16x16x32_bf16 v[70:73], v[154:157], v[226:229], v[70:73]
	v_mfma_f32_16x16x32_bf16 v[66:69], v[180:183], v[226:229], v[66:69]
	s_barrier
; #define PG8_STAGE(bufoff, gbase, voff) do { _Pragma("unroll") for (int _i = 0; _i < 2; ++_i) \
;         __builtin_amdgcn_global_load_lds((const unsigned*)((const char*)(gbase) + (voff)[_i]), (LAS unsigned*)(lds + (bufoff) + ldsw + _i * 8192), 16, 0, 0); } while (0)
; #define PG8_LDA(dst, b, h) do { _Pragma("unroll") for (int m = 0; m < 4; ++m) _Pragma("unroll") for (int k = 0; k < 2; ++k) dst[m][k] = *(const LAS bf16x8*)(lds + PG8_SA(b, h) + aoff + m * 2048 + k * 1024); } while (0)
; #define PG8_MMA(ai, bj, At, Bt) do { __builtin_amdgcn_s_setprio(1); _Pragma("unroll") for (int m = 0; m < 4; ++m) _Pragma("unroll") for (int n = 0; n < 2; ++n) _Pragma("unroll") for (int k = 0; k < 2; ++k) \
;         acc[ai][bj][m][n] = __builtin_amdgcn_mfma_f32_16x16x32_bf16(Bt[n][k], At[m][k], acc[ai][bj][m][n], 0, 0, 0); __builtin_amdgcn_s_setprio(0); } while (0)
; #define PG8_WAIT_V(n) asm volatile("s_waitcnt vmcnt(" #n ")" ::: "memory")
; #define PG8_WAIT_L(n) asm volatile("s_waitcnt lgkmcnt(" #n ")" ::: "memory")
; #define PG8_BAR __builtin_amdgcn_s_barrier()
; #define PG8_SCHED __builtin_amdgcn_sched_barrier(0)
; #define PG8_LDA(dst, b, h) do { _Pragma("unroll") for (int m = 0; m < 4; ++m) _Pragma("unroll") for (int k = 0; k < 2; ++k) dst[m][k] = *(const LAS bf16x8*)(lds + PG8_SA(b, h) + aoff + m * 2048 + k * 1024); } while (0)
; #define PG8_MMA(ai, bj, At, Bt) do { __builtin_amdgcn_s_setprio(1); _Pragma("unroll") for (int m = 0; m < 4; ++m) _Pragma("unroll") for (int n = 0; n < 2; ++n) _Pragma("unroll") for (int k = 0; k < 2; ++k) \
;         acc[ai][bj][m][n] = __builtin_amdgcn_mfma_f32_16x16x32_bf16(Bt[n][k], At[m][k], acc[ai][bj][m][n], 0, 0, 0); __builtin_amdgcn_s_setprio(0); } while (0)
; #define PG8_WAIT_V(n) asm volatile("s_waitcnt vmcnt(" #n ")" ::: "memory")
; #define PG8_WAIT_L(n) asm volatile("s_waitcnt lgkmcnt(" #n ")" ::: "memory")
; #define PG8_BAR __builtin_amdgcn_s_barrier()
; #define PG8_SCHED __builtin_amdgcn_sched_barrier(0)
; template <class Epi, class Sched>
; DI void gemm_phase(LAS unsigned char* lds, const Gemm g, const Sched& S, const Epi& E) {
;     ...
;             PG8_LDA(At, 1, 1); PG8_STAGE(PG8_SB(1, 0), b3, voffB); PG8_STAGE(PG8_SB(1, 1), b3 + hstepB, voffB); PG8_STAGE(PG8_SA(1, 0), a3, voffA);
;             PG8_WAIT_V(8); PG8_WAIT_L(0); PG8_BAR; PG8_MMA(1, 0, At, B0); PG8_MMA(1, 1, At, B1); PG8_BAR; PG8_SCHED;
;         }
	s_add_i32 s38, s86, s51
	v_lshl_add_u64 v[204:205], v[204:205], 0, s[26:27]
	s_mov_b32 m0, s38
	ds_read_b128 v[184:187], v208 offset:49152
	ds_read_b128 v[188:191], v208 offset:50176
	ds_read_b128 v[192:195], v208 offset:51200
	ds_read_b128 v[210:213], v208 offset:52224
	ds_read_b128 v[214:217], v208 offset:53248
	ds_read_b128 v[218:221], v208 offset:54272
	ds_read_b128 v[222:225], v208 offset:55296
	ds_read_b128 v[226:229], v208 offset:56320
	global_load_lds_dwordx4 v[204:205], off
	s_add_i32 m0, s38, 0x2000
	s_add_u32 s36, s36, 0x40080
	v_lshl_add_u64 v[204:205], v[206:207], 0, s[26:27]
	s_addc_u32 s37, s37, 0
	s_add_i32 s38, s87, s51
	global_load_lds_dwordx4 v[204:205], off
	v_lshl_add_u64 v[204:205], s[36:37], 0, v[164:165]
	s_mov_b32 m0, s38
	s_nop 0
	global_load_lds_dwordx4 v[204:205], off
	v_lshl_add_u64 v[204:205], s[36:37], 0, v[168:169]
	s_add_i32 m0, s38, 0x2000
	s_nop 0
	global_load_lds_dwordx4 v[204:205], off
	v_lshl_add_u64 v[204:205], v[230:231], 0, s[26:27]
	s_mov_b32 m0, s12
	s_nop 0
	global_load_lds_dwordx4 v[204:205], off
	v_lshl_add_u64 v[204:205], v[232:233], 0, s[26:27]
	s_mov_b32 m0, s13
	s_nop 0
	global_load_lds_dwordx4 v[204:205], off
	s_waitcnt vmcnt(8)
	s_waitcnt lgkmcnt(0)
	s_barrier
	s_waitcnt lgkmcnt(0)
	v_mfma_f32_16x16x32_bf16 v[62:65], v[134:137], v[184:187], v[62:65]
	v_mfma_f32_16x16x32_bf16 v[58:61], v[142:145], v[184:187], v[58:61]
	v_mfma_f32_16x16x32_bf16 v[54:57], v[134:137], v[192:195], v[54:57]
	v_mfma_f32_16x16x32_bf16 v[50:53], v[142:145], v[192:195], v[50:53]
	v_mfma_f32_16x16x32_bf16 v[46:49], v[134:137], v[214:217], v[46:49]
	v_mfma_f32_16x16x32_bf16 v[42:45], v[142:145], v[214:217], v[42:45]
	v_mfma_f32_16x16x32_bf16 v[38:41], v[134:137], v[222:225], v[38:41]
	v_mfma_f32_16x16x32_bf16 v[34:37], v[142:145], v[222:225], v[34:37]
	v_mfma_f32_16x16x32_bf16 v[62:65], v[138:141], v[188:191], v[62:65]
	v_mfma_f32_16x16x32_bf16 v[58:61], v[146:149], v[188:191], v[58:61]
	v_mfma_f32_16x16x32_bf16 v[54:57], v[138:141], v[210:213], v[54:57]
	v_mfma_f32_16x16x32_bf16 v[50:53], v[146:149], v[210:213], v[50:53]
	v_mfma_f32_16x16x32_bf16 v[46:49], v[138:141], v[218:221], v[46:49]
	v_mfma_f32_16x16x32_bf16 v[42:45], v[146:149], v[218:221], v[42:45]
	v_mfma_f32_16x16x32_bf16 v[38:41], v[138:141], v[226:229], v[38:41]
	v_mfma_f32_16x16x32_bf16 v[34:37], v[146:149], v[226:229], v[34:37]
	v_mfma_f32_16x16x32_bf16 v[30:33], v[150:153], v[184:187], v[30:33]
	v_mfma_f32_16x16x32_bf16 v[26:29], v[158:161], v[184:187], v[26:29]
	v_mfma_f32_16x16x32_bf16 v[22:25], v[150:153], v[192:195], v[22:25]
	v_mfma_f32_16x16x32_bf16 v[18:21], v[158:161], v[192:195], v[18:21]
	v_mfma_f32_16x16x32_bf16 v[14:17], v[150:153], v[214:217], v[14:17]
	v_mfma_f32_16x16x32_bf16 v[10:13], v[158:161], v[214:217], v[10:13]
	v_mfma_f32_16x16x32_bf16 v[6:9], v[150:153], v[222:225], v[6:9]
	v_mfma_f32_16x16x32_bf16 v[2:5], v[158:161], v[222:225], v[2:5]
	v_mfma_f32_16x16x32_bf16 v[30:33], v[154:157], v[188:191], v[30:33]
	v_mfma_f32_16x16x32_bf16 v[26:29], v[180:183], v[188:191], v[26:29]
	v_mfma_f32_16x16x32_bf16 v[22:25], v[154:157], v[210:213], v[22:25]
	v_mfma_f32_16x16x32_bf16 v[18:21], v[180:183], v[210:213], v[18:21]
	v_mfma_f32_16x16x32_bf16 v[14:17], v[154:157], v[218:221], v[14:17]
	v_mfma_f32_16x16x32_bf16 v[10:13], v[180:183], v[218:221], v[10:13]
	v_mfma_f32_16x16x32_bf16 v[6:9], v[154:157], v[226:229], v[6:9]
	v_mfma_f32_16x16x32_bf16 v[2:5], v[180:183], v[226:229], v[2:5]
	s_barrier
	s_add_i32 s79, s79, 2
	s_add_u32 s30, s30, 0x100
	s_addc_u32 s31, s31, 0
	s_cmp_gt_u32 s79, 13
	s_cbranch_scc0 .LBB0_208
	s_and_b64 vcc, exec, s[70:71]
	s_cbranch_vccz .LBB0_211
	s_barrier

; #define PG8_STAGE(bufoff, gbase, voff) do { _Pragma("unroll") for (int _i = 0; _i < 2; ++_i) \
;         __builtin_amdgcn_global_load_lds((const unsigned*)((const char*)(gbase) + (voff)[_i]), (LAS unsigned*)(lds + (bufoff) + ldsw + _i * 8192), 16, 0, 0); } while (0)
; #define PG8_LDA(dst, b, h) do { _Pragma("unroll") for (int m = 0; m < 4; ++m) _Pragma("unroll") for (int k = 0; k < 2; ++k) dst[m][k] = *(const LAS bf16x8*)(lds + PG8_SA(b, h) + aoff + m * 2048 + k * 1024); } while (0)
; #define PG8_LDB(dst, b, h) do { _Pragma("unroll") for (int n = 0; n < 2; ++n) _Pragma("unroll") for (int k = 0; k < 2; ++k) dst[n][k] = *(const LAS bf16x8*)(lds + PG8_SB(b, h) + boff + n * 2048 + k * 1024); } while (0)
; #define PG8_MMA(ai, bj, At, Bt) do { __builtin_amdgcn_s_setprio(1); _Pragma("unroll") for (int m = 0; m < 4; ++m) _Pragma("unroll") for (int n = 0; n < 2; ++n) _Pragma("unroll") for (int k = 0; k < 2; ++k) \
;         acc[ai][bj][m][n] = __builtin_amdgcn_mfma_f32_16x16x32_bf16(Bt[n][k], At[m][k], acc[ai][bj][m][n], 0, 0, 0); __builtin_amdgcn_s_setprio(0); } while (0)
; #define PG8_WAIT_V(n) asm volatile("s_waitcnt vmcnt(" #n ")" ::: "memory")
; #define PG8_WAIT_L(n) asm volatile("s_waitcnt lgkmcnt(" #n ")" ::: "memory")
; #define PG8_BAR __builtin_amdgcn_s_barrier()
; #define PG8_SCHED __builtin_amdgcn_sched_barrier(0)
; #define PG8_BAR __builtin_amdgcn_s_barrier()
; template <class Epi, class Sched>
; DI void gemm_phase(LAS unsigned char* lds, const Gemm g, const Sched& S, const Epi& E) {
;     ...
;         for (int t = 0; t < nt; t += 2) {
;             const bool last = (t == nt - 2);
;             const char* a1 = cA + (size_t)(t + 1) * kstep;
;             const char* a2 = last ? nA : cA + (size_t)(t + 2) * kstep; const char* b2 = last ? nB : cB + (size_t)(t + 2) * kstep;
;             const char* a3 = a2 + kstep; const char* b3 = b2 + kstep;
;             PG8_LDB(B0, 0, 0); PG8_LDB(B1, 0, 1); PG8_SCHED; PG8_LDA(At, 0, 0); PG8_STAGE(PG8_SA(1, 1), a1 + hstepA, voffA);
;             PG8_WAIT_V(8); PG8_WAIT_L(0); PG8_BAR; PG8_MMA(0, 0, At, B0); PG8_MMA(0, 1, At, B1); PG8_BAR; PG8_SCHED;
;             PG8_LDA(At, 0, 1); PG8_STAGE(PG8_SB(0, 0), b2, voffB); PG8_STAGE(PG8_SB(0, 1), b2 + hstepB, voffB); PG8_STAGE(PG8_SA(0, 0), a2, voffA);
;             PG8_WAIT_V(8); PG8_WAIT_L(0); PG8_BAR; PG8_MMA(1, 0, At, B0); PG8_MMA(1, 1, At, B1); PG8_BAR; PG8_SCHED;
.LBB0_371:
	s_add_u32 s36, s70, 0xfffc0080
	s_addc_u32 s37, s71, -1
	s_add_i32 s83, 0, 0x10000
	s_cmp_eq_u32 s82, 12
	s_cselect_b32 s39, s40, s37
	s_cselect_b32 s38, s41, s36
	v_add_u32_e32 v0, s83, v143
	s_cselect_b32 s37, s45, s81
	s_cselect_b32 s36, s51, s63
	s_add_i32 s86, 0, 0x14000
	ds_read_b128 v[150:153], v0
	ds_read_b128 v[154:157], v0 offset:1024
	ds_read_b128 v[158:161], v0 offset:2048
	ds_read_b128 v[162:165], v0 offset:3072
	v_add_u32_e32 v0, s86, v143
	ds_read_b128 v[166:169], v0
	ds_read_b128 v[170:173], v0 offset:1024
	ds_read_b128 v[174:177], v0 offset:2048
	ds_read_b128 v[178:181], v0 offset:3072
	v_lshl_add_u64 v[194:195], s[70:71], 0, v[138:139]
	s_add_i32 m0, s17, 0xc000
	ds_read_b128 v[182:185], v148
	ds_read_b128 v[186:189], v148 offset:1024
	ds_read_b128 v[190:193], v148 offset:2048
	ds_read_b128 v[198:201], v148 offset:3072
	ds_read_b128 v[208:211], v148 offset:4096
	ds_read_b128 v[212:215], v148 offset:5120
	ds_read_b128 v[216:219], v148 offset:6144
	ds_read_b128 v[220:223], v148 offset:7168
	global_load_lds_dwordx4 v[194:195], off
	v_lshl_add_u64 v[194:195], s[70:71], 0, v[140:141]
	s_add_i32 m0, s17, 0xe000
	s_nop 0
	global_load_lds_dwordx4 v[194:195], off
	s_waitcnt vmcnt(8)
	s_waitcnt lgkmcnt(0)
	s_barrier
	s_waitcnt lgkmcnt(0)
	v_mfma_f32_16x16x32_bf16 v[126:129], v[150:153], v[182:185], v[126:129]
	v_mfma_f32_16x16x32_bf16 v[122:125], v[158:161], v[182:185], v[122:125]
	v_mfma_f32_16x16x32_bf16 v[118:121], v[150:153], v[190:193], v[118:121]
	v_mfma_f32_16x16x32_bf16 v[114:117], v[158:161], v[190:193], v[114:117]
	v_mfma_f32_16x16x32_bf16 v[102:105], v[150:153], v[208:211], v[102:105]
	v_mfma_f32_16x16x32_bf16 v[98:101], v[158:161], v[208:211], v[98:101]
	v_mfma_f32_16x16x32_bf16 v[86:89], v[150:153], v[216:219], v[86:89]
	v_mfma_f32_16x16x32_bf16 v[82:85], v[158:161], v[216:219], v[82:85]
	v_mfma_f32_16x16x32_bf16 v[126:129], v[154:157], v[186:189], v[126:129]
	v_mfma_f32_16x16x32_bf16 v[122:125], v[162:165], v[186:189], v[122:125]
	v_mfma_f32_16x16x32_bf16 v[118:121], v[154:157], v[198:201], v[118:121]
	v_mfma_f32_16x16x32_bf16 v[114:117], v[162:165], v[198:201], v[114:117]
	v_mfma_f32_16x16x32_bf16 v[102:105], v[154:157], v[212:215], v[102:105]
	v_mfma_f32_16x16x32_bf16 v[98:101], v[162:165], v[212:215], v[98:101]
	v_mfma_f32_16x16x32_bf16 v[86:89], v[154:157], v[220:223], v[86:89]
	v_mfma_f32_16x16x32_bf16 v[82:85], v[162:165], v[220:223], v[82:85]
	v_mfma_f32_16x16x32_bf16 v[110:113], v[166:169], v[182:185], v[110:113]
	v_mfma_f32_16x16x32_bf16 v[106:109], v[174:177], v[182:185], v[106:109]
	v_mfma_f32_16x16x32_bf16 v[94:97], v[166:169], v[190:193], v[94:97]
	v_mfma_f32_16x16x32_bf16 v[90:93], v[174:177], v[190:193], v[90:93]
	v_mfma_f32_16x16x32_bf16 v[78:81], v[166:169], v[208:211], v[78:81]
	v_mfma_f32_16x16x32_bf16 v[74:77], v[174:177], v[208:211], v[74:77]
	v_mfma_f32_16x16x32_bf16 v[70:73], v[166:169], v[216:219], v[70:73]
	v_mfma_f32_16x16x32_bf16 v[66:69], v[174:177], v[216:219], v[66:69]
	v_mfma_f32_16x16x32_bf16 v[110:113], v[170:173], v[186:189], v[110:113]
	v_mfma_f32_16x16x32_bf16 v[106:109], v[178:181], v[186:189], v[106:109]
	v_mfma_f32_16x16x32_bf16 v[94:97], v[170:173], v[198:201], v[94:97]
	v_mfma_f32_16x16x32_bf16 v[90:93], v[178:181], v[198:201], v[90:93]
	v_mfma_f32_16x16x32_bf16 v[78:81], v[170:173], v[212:215], v[78:81]
	v_mfma_f32_16x16x32_bf16 v[74:77], v[178:181], v[212:215], v[74:77]
	v_mfma_f32_16x16x32_bf16 v[70:73], v[170:173], v[220:223], v[70:73]
	v_mfma_f32_16x16x32_bf16 v[66:69], v[178:181], v[220:223], v[66:69]
	s_barrier
	s_add_i32 s83, s83, s16
	v_lshl_add_u64 v[194:195], s[36:37], 0, v[134:135]
	s_mov_b32 m0, s83
	ds_read_b128 v[182:185], v148 offset:16384
	ds_read_b128 v[186:189], v148 offset:17408
	ds_read_b128 v[190:193], v148 offset:18432
	ds_read_b128 v[198:201], v148 offset:19456
	ds_read_b128 v[208:211], v148 offset:20480
	ds_read_b128 v[212:215], v148 offset:21504
	ds_read_b128 v[216:219], v148 offset:22528
	ds_read_b128 v[220:223], v148 offset:23552
	global_load_lds_dwordx4 v[194:195], off
	s_add_i32 m0, s83, 0x2000
	s_add_u32 s84, s36, 0x40000
	v_lshl_add_u64 v[204:205], s[36:37], 0, v[130:131]
	s_addc_u32 s85, s37, 0
	s_add_i32 s83, s86, s16
	global_load_lds_dwordx4 v[204:205], off
	v_lshl_add_u64 v[206:207], s[84:85], 0, v[134:135]
	s_mov_b32 m0, s83
	v_lshl_add_u64 v[224:225], s[38:39], 0, v[132:133]
	global_load_lds_dwordx4 v[206:207], off
	v_lshl_add_u64 v[206:207], s[84:85], 0, v[130:131]
	s_add_i32 m0, s83, 0x2000
	s_nop 0
	global_load_lds_dwordx4 v[206:207], off
	v_lshl_add_u64 v[206:207], s[38:39], 0, v[136:137]
	s_mov_b32 m0, s17
	s_nop 0
	global_load_lds_dwordx4 v[206:207], off
	s_mov_b32 m0, s25
	s_nop 0
	global_load_lds_dwordx4 v[224:225], off
	s_waitcnt vmcnt(8)
	s_waitcnt lgkmcnt(0)
	s_barrier
; #define PG8_STAGE(bufoff, gbase, voff) do { _Pragma("unroll") for (int _i = 0; _i < 2; ++_i) \
;         __builtin_amdgcn_global_load_lds((const unsigned*)((const char*)(gbase) + (voff)[_i]), (LAS unsigned*)(lds + (bufoff) + ldsw + _i * 8192), 16, 0, 0); } while (0)
; #define PG8_LDA(dst, b, h) do { _Pragma("unroll") for (int m = 0; m < 4; ++m) _Pragma("unroll") for (int k = 0; k < 2; ++k) dst[m][k] = *(const LAS bf16x8*)(lds + PG8_SA(b, h) + aoff + m * 2048 + k * 1024); } while (0)
; #define PG8_LDB(dst, b, h) do { _Pragma("unroll") for (int n = 0; n < 2; ++n) _Pragma("unroll") for (int k = 0; k < 2; ++k) dst[n][k] = *(const LAS bf16x8*)(lds + PG8_SB(b, h) + boff + n * 2048 + k * 1024); } while (0)
; #define PG8_MMA(ai, bj, At, Bt) do { __builtin_amdgcn_s_setprio(1); _Pragma("unroll") for (int m = 0; m < 4; ++m) _Pragma("unroll") for (int n = 0; n < 2; ++n) _Pragma("unroll") for (int k = 0; k < 2; ++k) \
;         acc[ai][bj][m][n] = __builtin_amdgcn_mfma_f32_16x16x32_bf16(Bt[n][k], At[m][k], acc[ai][bj][m][n], 0, 0, 0); __builtin_amdgcn_s_setprio(0); } while (0)
; #define PG8_WAIT_V(n) asm volatile("s_waitcnt vmcnt(" #n ")" ::: "memory")
; #define PG8_WAIT_L(n) asm volatile("s_waitcnt lgkmcnt(" #n ")" ::: "memory")
; #define PG8_BAR __builtin_amdgcn_s_barrier()
; #define PG8_SCHED __builtin_amdgcn_sched_barrier(0)
; #define PG8_LDA(dst, b, h) do { _Pragma("unroll") for (int m = 0; m < 4; ++m) _Pragma("unroll") for (int k = 0; k < 2; ++k) dst[m][k] = *(const LAS bf16x8*)(lds + PG8_SA(b, h) + aoff + m * 2048 + k * 1024); } while (0)
; #define PG8_WAIT_V(n) asm volatile("s_waitcnt vmcnt(" #n ")" ::: "memory")
; #define PG8_WAIT_L(n) asm volatile("s_waitcnt lgkmcnt(" #n ")" ::: "memory")
; template <class Epi, class Sched>
; DI void gemm_phase(LAS unsigned char* lds, const Gemm g, const Sched& S, const Epi& E) {
;     ...
;             PG8_WAIT_V(8); PG8_WAIT_L(0); PG8_BAR; PG8_MMA(1, 0, At, B0); PG8_MMA(1, 1, At, B1); PG8_BAR; PG8_SCHED;
;             PG8_LDB(B0, 1, 0); PG8_LDB(B1, 1, 1); PG8_SCHED; PG8_LDA(At, 1, 0); PG8_STAGE(PG8_SA(0, 1), a2 + hstepA, voffA);
;             PG8_WAIT_V(8); PG8_WAIT_L(0); PG8_BAR; PG8_MMA(0, 0, At, B0); PG8_MMA(0, 1, At, B1); PG8_BAR; PG8_SCHED;
;             PG8_LDA(At, 1, 1); PG8_STAGE(PG8_SB(1, 0), b3, voffB); PG8_STAGE(PG8_SB(1, 1), b3 + hstepB, voffB); PG8_STAGE(PG8_SA(1, 0), a3, voffA);
	s_waitcnt lgkmcnt(0)
	v_mfma_f32_16x16x32_bf16 v[62:65], v[150:153], v[182:185], v[62:65]
	v_mfma_f32_16x16x32_bf16 v[58:61], v[158:161], v[182:185], v[58:61]
	v_mfma_f32_16x16x32_bf16 v[54:57], v[150:153], v[190:193], v[54:57]
	v_mfma_f32_16x16x32_bf16 v[50:53], v[158:161], v[190:193], v[50:53]
	v_mfma_f32_16x16x32_bf16 v[38:41], v[150:153], v[208:211], v[38:41]
	v_mfma_f32_16x16x32_bf16 v[34:37], v[158:161], v[208:211], v[34:37]
	v_mfma_f32_16x16x32_bf16 v[22:25], v[150:153], v[216:219], v[22:25]
	v_mfma_f32_16x16x32_bf16 v[18:21], v[158:161], v[216:219], v[18:21]
	v_mfma_f32_16x16x32_bf16 v[62:65], v[154:157], v[186:189], v[62:65]
	v_mfma_f32_16x16x32_bf16 v[58:61], v[162:165], v[186:189], v[58:61]
	v_mfma_f32_16x16x32_bf16 v[54:57], v[154:157], v[198:201], v[54:57]
	v_mfma_f32_16x16x32_bf16 v[50:53], v[162:165], v[198:201], v[50:53]
	v_mfma_f32_16x16x32_bf16 v[38:41], v[154:157], v[212:215], v[38:41]
	v_mfma_f32_16x16x32_bf16 v[34:37], v[162:165], v[212:215], v[34:37]
	v_mfma_f32_16x16x32_bf16 v[22:25], v[154:157], v[220:223], v[22:25]
	v_mfma_f32_16x16x32_bf16 v[18:21], v[162:165], v[220:223], v[18:21]
	v_mfma_f32_16x16x32_bf16 v[46:49], v[166:169], v[182:185], v[46:49]
	v_mfma_f32_16x16x32_bf16 v[42:45], v[174:177], v[182:185], v[42:45]
	v_mfma_f32_16x16x32_bf16 v[30:33], v[166:169], v[190:193], v[30:33]
	v_mfma_f32_16x16x32_bf16 v[26:29], v[174:177], v[190:193], v[26:29]
	v_mfma_f32_16x16x32_bf16 v[14:17], v[166:169], v[208:211], v[14:17]
	v_mfma_f32_16x16x32_bf16 v[10:13], v[174:177], v[208:211], v[10:13]
	v_mfma_f32_16x16x32_bf16 v[6:9], v[166:169], v[216:219], v[6:9]
	v_mfma_f32_16x16x32_bf16 v[2:5], v[174:177], v[216:219], v[2:5]
	v_mfma_f32_16x16x32_bf16 v[46:49], v[170:173], v[186:189], v[46:49]
	v_mfma_f32_16x16x32_bf16 v[42:45], v[178:181], v[186:189], v[42:45]
	v_mfma_f32_16x16x32_bf16 v[30:33], v[170:173], v[198:201], v[30:33]
	v_mfma_f32_16x16x32_bf16 v[26:29], v[178:181], v[198:201], v[26:29]
	v_mfma_f32_16x16x32_bf16 v[14:17], v[170:173], v[212:215], v[14:17]
	v_mfma_f32_16x16x32_bf16 v[10:13], v[178:181], v[212:215], v[10:13]
	v_mfma_f32_16x16x32_bf16 v[6:9], v[170:173], v[220:223], v[6:9]
	v_mfma_f32_16x16x32_bf16 v[2:5], v[178:181], v[220:223], v[2:5]
	s_barrier
	s_add_i32 s83, 0, 0x18000
	v_add_u32_e32 v0, s83, v143
	s_add_i32 s84, 0, 0x1c000
	ds_read_b128 v[150:153], v0
	ds_read_b128 v[154:157], v0 offset:1024
	ds_read_b128 v[158:161], v0 offset:2048
	ds_read_b128 v[162:165], v0 offset:3072
	v_add_u32_e32 v0, s84, v143
	ds_read_b128 v[166:169], v0
	ds_read_b128 v[170:173], v0 offset:1024
	ds_read_b128 v[174:177], v0 offset:2048
	ds_read_b128 v[178:181], v0 offset:3072
	s_add_u32 s38, s38, 0x40000
	s_addc_u32 s39, s39, 0
	s_mov_b32 m0, s28
	v_lshl_add_u64 v[226:227], s[38:39], 0, v[136:137]
	ds_read_b128 v[182:185], v148 offset:32768
	ds_read_b128 v[186:189], v148 offset:33792
	ds_read_b128 v[190:193], v148 offset:34816
	ds_read_b128 v[198:201], v148 offset:35840
	ds_read_b128 v[208:211], v148 offset:36864
	ds_read_b128 v[212:215], v148 offset:37888
	ds_read_b128 v[216:219], v148 offset:38912
	ds_read_b128 v[220:223], v148 offset:39936
	global_load_lds_dwordx4 v[226:227], off
	v_lshl_add_u64 v[226:227], s[38:39], 0, v[132:133]
	s_mov_b32 m0, s72
	s_nop 0
	global_load_lds_dwordx4 v[226:227], off
	s_waitcnt vmcnt(8)
	s_waitcnt lgkmcnt(0)
	s_barrier
	s_waitcnt lgkmcnt(0)
	v_mfma_f32_16x16x32_bf16 v[126:129], v[150:153], v[182:185], v[126:129]
	v_mfma_f32_16x16x32_bf16 v[122:125], v[158:161], v[182:185], v[122:125]
	v_mfma_f32_16x16x32_bf16 v[118:121], v[150:153], v[190:193], v[118:121]
	v_mfma_f32_16x16x32_bf16 v[114:117], v[158:161], v[190:193], v[114:117]
	v_mfma_f32_16x16x32_bf16 v[102:105], v[150:153], v[208:211], v[102:105]
	v_mfma_f32_16x16x32_bf16 v[98:101], v[158:161], v[208:211], v[98:101]
	v_mfma_f32_16x16x32_bf16 v[86:89], v[150:153], v[216:219], v[86:89]
	v_mfma_f32_16x16x32_bf16 v[82:85], v[158:161], v[216:219], v[82:85]
	v_mfma_f32_16x16x32_bf16 v[126:129], v[154:157], v[186:189], v[126:129]
	v_mfma_f32_16x16x32_bf16 v[122:125], v[162:165], v[186:189], v[122:125]
	v_mfma_f32_16x16x32_bf16 v[118:121], v[154:157], v[198:201], v[118:121]
	v_mfma_f32_16x16x32_bf16 v[114:117], v[162:165], v[198:201], v[114:117]
	v_mfma_f32_16x16x32_bf16 v[102:105], v[154:157], v[212:215], v[102:105]
	v_mfma_f32_16x16x32_bf16 v[98:101], v[162:165], v[212:215], v[98:101]
	v_mfma_f32_16x16x32_bf16 v[86:89], v[154:157], v[220:223], v[86:89]
	v_mfma_f32_16x16x32_bf16 v[82:85], v[162:165], v[220:223], v[82:85]
	v_mfma_f32_16x16x32_bf16 v[110:113], v[166:169], v[182:185], v[110:113]
	v_mfma_f32_16x16x32_bf16 v[106:109], v[174:177], v[182:185], v[106:109]
	v_mfma_f32_16x16x32_bf16 v[94:97], v[166:169], v[190:193], v[94:97]
	v_mfma_f32_16x16x32_bf16 v[90:93], v[174:177], v[190:193], v[90:93]
	v_mfma_f32_16x16x32_bf16 v[78:81], v[166:169], v[208:211], v[78:81]
	v_mfma_f32_16x16x32_bf16 v[74:77], v[174:177], v[208:211], v[74:77]
	v_mfma_f32_16x16x32_bf16 v[70:73], v[166:169], v[216:219], v[70:73]
	v_mfma_f32_16x16x32_bf16 v[66:69], v[174:177], v[216:219], v[66:69]
	v_mfma_f32_16x16x32_bf16 v[110:113], v[170:173], v[186:189], v[110:113]
	v_mfma_f32_16x16x32_bf16 v[106:109], v[178:181], v[186:189], v[106:109]
	v_mfma_f32_16x16x32_bf16 v[94:97], v[170:173], v[198:201], v[94:97]
	v_mfma_f32_16x16x32_bf16 v[90:93], v[178:181], v[198:201], v[90:93]
	v_mfma_f32_16x16x32_bf16 v[78:81], v[170:173], v[212:215], v[78:81]
	v_mfma_f32_16x16x32_bf16 v[74:77], v[178:181], v[212:215], v[74:77]
	v_mfma_f32_16x16x32_bf16 v[70:73], v[170:173], v[220:223], v[70:73]
	v_mfma_f32_16x16x32_bf16 v[66:69], v[178:181], v[220:223], v[66:69]
	s_barrier
; #define PG8_STAGE(bufoff, gbase, voff) do { _Pragma("unroll") for (int _i = 0; _i < 2; ++_i) \
;         __builtin_amdgcn_global_load_lds((const unsigned*)((const char*)(gbase) + (voff)[_i]), (LAS unsigned*)(lds + (bufoff) + ldsw + _i * 8192), 16, 0, 0); } while (0)
; #define PG8_LDA(dst, b, h) do { _Pragma("unroll") for (int m = 0; m < 4; ++m) _Pragma("unroll") for (int k = 0; k < 2; ++k) dst[m][k] = *(const LAS bf16x8*)(lds + PG8_SA(b, h) + aoff + m * 2048 + k * 1024); } while (0)
; #define PG8_MMA(ai, bj, At, Bt) do { __builtin_amdgcn_s_setprio(1); _Pragma("unroll") for (int m = 0; m < 4; ++m) _Pragma("unroll") for (int n = 0; n < 2; ++n) _Pragma("unroll") for (int k = 0; k < 2; ++k) \
;         acc[ai][bj][m][n] = __builtin_amdgcn_mfma_f32_16x16x32_bf16(Bt[n][k], At[m][k], acc[ai][bj][m][n], 0, 0, 0); __builtin_amdgcn_s_setprio(0); } while (0)
; #define PG8_WAIT_V(n) asm volatile("s_waitcnt vmcnt(" #n ")" ::: "memory")
; #define PG8_WAIT_L(n) asm volatile("s_waitcnt lgkmcnt(" #n ")" ::: "memory")
; #define PG8_BAR __builtin_amdgcn_s_barrier()
; #define PG8_SCHED __builtin_amdgcn_sched_barrier(0)
; #define PG8_LDA(dst, b, h) do { _Pragma("unroll") for (int m = 0; m < 4; ++m) _Pragma("unroll") for (int k = 0; k < 2; ++k) dst[m][k] = *(const LAS bf16x8*)(lds + PG8_SA(b, h) + aoff + m * 2048 + k * 1024); } while (0)
; #define PG8_MMA(ai, bj, At, Bt) do { __builtin_amdgcn_s_setprio(1); _Pragma("unroll") for (int m = 0; m < 4; ++m) _Pragma("unroll") for (int n = 0; n < 2; ++n) _Pragma("unroll") for (int k = 0; k < 2; ++k) \
;         acc[ai][bj][m][n] = __builtin_amdgcn_mfma_f32_16x16x32_bf16(Bt[n][k], At[m][k], acc[ai][bj][m][n], 0, 0, 0); __builtin_amdgcn_s_setprio(0); } while (0)
; #define PG8_WAIT_V(n) asm volatile("s_waitcnt vmcnt(" #n ")" ::: "memory")
; #define PG8_WAIT_L(n) asm volatile("s_waitcnt lgkmcnt(" #n ")" ::: "memory")
; #define PG8_BAR __builtin_amdgcn_s_barrier()
; #define PG8_SCHED __builtin_amdgcn_sched_barrier(0)
; template <class Epi, class Sched>
; DI void gemm_phase(LAS unsigned char* lds, const Gemm g, const Sched& S, const Epi& E) {
;     ...
;             PG8_LDA(At, 1, 1); PG8_STAGE(PG8_SB(1, 0), b3, voffB); PG8_STAGE(PG8_SB(1, 1), b3 + hstepB, voffB); PG8_STAGE(PG8_SA(1, 0), a3, voffA);
;             PG8_WAIT_V(8); PG8_WAIT_L(0); PG8_BAR; PG8_MMA(1, 0, At, B0); PG8_MMA(1, 1, At, B1); PG8_BAR; PG8_SCHED;
;         }
	s_add_i32 s38, s83, s16
	v_lshl_add_u64 v[194:195], v[194:195], 0, s[26:27]
	s_mov_b32 m0, s38
	ds_read_b128 v[182:185], v148 offset:49152
	ds_read_b128 v[186:189], v148 offset:50176
	ds_read_b128 v[190:193], v148 offset:51200
	ds_read_b128 v[198:201], v148 offset:52224
	ds_read_b128 v[208:211], v148 offset:53248
	ds_read_b128 v[212:215], v148 offset:54272
	ds_read_b128 v[216:219], v148 offset:55296
	ds_read_b128 v[220:223], v148 offset:56320
	global_load_lds_dwordx4 v[194:195], off
	s_add_i32 m0, s38, 0x2000
	s_add_u32 s36, s36, 0x40080
	v_lshl_add_u64 v[194:195], v[204:205], 0, s[26:27]
	s_addc_u32 s37, s37, 0
	s_add_i32 s38, s84, s16
	global_load_lds_dwordx4 v[194:195], off
	v_lshl_add_u64 v[194:195], s[36:37], 0, v[134:135]
	s_mov_b32 m0, s38
	s_nop 0
	global_load_lds_dwordx4 v[194:195], off
	v_lshl_add_u64 v[194:195], s[36:37], 0, v[130:131]
	s_add_i32 m0, s38, 0x2000
	s_nop 0
	global_load_lds_dwordx4 v[194:195], off
	v_lshl_add_u64 v[194:195], v[206:207], 0, s[26:27]
	s_mov_b32 m0, s75
	s_nop 0
	global_load_lds_dwordx4 v[194:195], off
	v_lshl_add_u64 v[194:195], v[224:225], 0, s[26:27]
	s_mov_b32 m0, s76
	s_nop 0
	global_load_lds_dwordx4 v[194:195], off
	s_waitcnt vmcnt(8)
	s_waitcnt lgkmcnt(0)
	s_barrier
	s_waitcnt lgkmcnt(0)
	v_mfma_f32_16x16x32_bf16 v[62:65], v[150:153], v[182:185], v[62:65]
	v_mfma_f32_16x16x32_bf16 v[58:61], v[158:161], v[182:185], v[58:61]
	v_mfma_f32_16x16x32_bf16 v[54:57], v[150:153], v[190:193], v[54:57]
	v_mfma_f32_16x16x32_bf16 v[50:53], v[158:161], v[190:193], v[50:53]
	v_mfma_f32_16x16x32_bf16 v[38:41], v[150:153], v[208:211], v[38:41]
	v_mfma_f32_16x16x32_bf16 v[34:37], v[158:161], v[208:211], v[34:37]
	v_mfma_f32_16x16x32_bf16 v[22:25], v[150:153], v[216:219], v[22:25]
	v_mfma_f32_16x16x32_bf16 v[18:21], v[158:161], v[216:219], v[18:21]
	v_mfma_f32_16x16x32_bf16 v[62:65], v[154:157], v[186:189], v[62:65]
	v_mfma_f32_16x16x32_bf16 v[58:61], v[162:165], v[186:189], v[58:61]
	v_mfma_f32_16x16x32_bf16 v[54:57], v[154:157], v[198:201], v[54:57]
	v_mfma_f32_16x16x32_bf16 v[50:53], v[162:165], v[198:201], v[50:53]
	v_mfma_f32_16x16x32_bf16 v[38:41], v[154:157], v[212:215], v[38:41]
	v_mfma_f32_16x16x32_bf16 v[34:37], v[162:165], v[212:215], v[34:37]
	v_mfma_f32_16x16x32_bf16 v[22:25], v[154:157], v[220:223], v[22:25]
	v_mfma_f32_16x16x32_bf16 v[18:21], v[162:165], v[220:223], v[18:21]
	v_mfma_f32_16x16x32_bf16 v[46:49], v[166:169], v[182:185], v[46:49]
	v_mfma_f32_16x16x32_bf16 v[42:45], v[174:177], v[182:185], v[42:45]
	v_mfma_f32_16x16x32_bf16 v[30:33], v[166:169], v[190:193], v[30:33]
	v_mfma_f32_16x16x32_bf16 v[26:29], v[174:177], v[190:193], v[26:29]
	v_mfma_f32_16x16x32_bf16 v[14:17], v[166:169], v[208:211], v[14:17]
	v_mfma_f32_16x16x32_bf16 v[10:13], v[174:177], v[208:211], v[10:13]
	v_mfma_f32_16x16x32_bf16 v[6:9], v[166:169], v[216:219], v[6:9]
	v_mfma_f32_16x16x32_bf16 v[2:5], v[174:177], v[216:219], v[2:5]
	v_mfma_f32_16x16x32_bf16 v[46:49], v[170:173], v[186:189], v[46:49]
	v_mfma_f32_16x16x32_bf16 v[42:45], v[178:181], v[186:189], v[42:45]
	v_mfma_f32_16x16x32_bf16 v[30:33], v[170:173], v[198:201], v[30:33]
	v_mfma_f32_16x16x32_bf16 v[26:29], v[178:181], v[198:201], v[26:29]
	v_mfma_f32_16x16x32_bf16 v[14:17], v[170:173], v[212:215], v[14:17]
	v_mfma_f32_16x16x32_bf16 v[10:13], v[178:181], v[212:215], v[10:13]
	v_mfma_f32_16x16x32_bf16 v[6:9], v[170:173], v[220:223], v[6:9]
	v_mfma_f32_16x16x32_bf16 v[2:5], v[178:181], v[220:223], v[2:5]
	s_barrier
	s_add_i32 s82, s82, 2
	s_add_u32 s70, s70, 0x100
	s_addc_u32 s71, s71, 0
	s_add_u32 s63, s63, 0x100
	s_addc_u32 s81, s81, 0
	s_cmp_gt_u32 s82, 13
	s_cbranch_scc0 .LBB0_371
	s_and_b64 vcc, exec, s[30:31]
	s_cbranch_vccz .LBB0_374
	s_barrier

; #define PG8_STAGE(bufoff, gbase, voff) do { _Pragma("unroll") for (int _i = 0; _i < 2; ++_i) \
;         __builtin_amdgcn_global_load_lds((const unsigned*)((const char*)(gbase) + (voff)[_i]), (LAS unsigned*)(lds + (bufoff) + ldsw + _i * 8192), 16, 0, 0); } while (0)
; #define PG8_LDA(dst, b, h) do { _Pragma("unroll") for (int m = 0; m < 4; ++m) _Pragma("unroll") for (int k = 0; k < 2; ++k) dst[m][k] = *(const LAS bf16x8*)(lds + PG8_SA(b, h) + aoff + m * 2048 + k * 1024); } while (0)
; #define PG8_LDB(dst, b, h) do { _Pragma("unroll") for (int n = 0; n < 2; ++n) _Pragma("unroll") for (int k = 0; k < 2; ++k) dst[n][k] = *(const LAS bf16x8*)(lds + PG8_SB(b, h) + boff + n * 2048 + k * 1024); } while (0)
; #define PG8_MMA(ai, bj, At, Bt) do { __builtin_amdgcn_s_setprio(1); _Pragma("unroll") for (int m = 0; m < 4; ++m) _Pragma("unroll") for (int n = 0; n < 2; ++n) _Pragma("unroll") for (int k = 0; k < 2; ++k) \
;         acc[ai][bj][m][n] = __builtin_amdgcn_mfma_f32_16x16x32_bf16(Bt[n][k], At[m][k], acc[ai][bj][m][n], 0, 0, 0); __builtin_amdgcn_s_setprio(0); } while (0)
; #define PG8_WAIT_V(n) asm volatile("s_waitcnt vmcnt(" #n ")" ::: "memory")
; #define PG8_WAIT_L(n) asm volatile("s_waitcnt lgkmcnt(" #n ")" ::: "memory")
; #define PG8_BAR __builtin_amdgcn_s_barrier()
; #define PG8_SCHED __builtin_amdgcn_sched_barrier(0)
; #define PG8_BAR __builtin_amdgcn_s_barrier()
; template <class Epi, class Sched>
; DI void gemm_phase(LAS unsigned char* lds, const Gemm g, const Sched& S, const Epi& E) {
;     ...
;         for (int t = 0; t < nt; t += 2) {
;             const bool last = (t == nt - 2);
;             const char* a1 = cA + (size_t)(t + 1) * kstep;
;             const char* a2 = last ? nA : cA + (size_t)(t + 2) * kstep; const char* b2 = last ? nB : cB + (size_t)(t + 2) * kstep;
;             const char* a3 = a2 + kstep; const char* b3 = b2 + kstep;
;             PG8_LDB(B0, 0, 0); PG8_LDB(B1, 0, 1); PG8_SCHED; PG8_LDA(At, 0, 0); PG8_STAGE(PG8_SA(1, 1), a1 + hstepA, voffA);
;             PG8_WAIT_V(8); PG8_WAIT_L(0); PG8_BAR; PG8_MMA(0, 0, At, B0); PG8_MMA(0, 1, At, B1); PG8_BAR; PG8_SCHED;
;             PG8_LDA(At, 0, 1); PG8_STAGE(PG8_SB(0, 0), b2, voffB); PG8_STAGE(PG8_SB(0, 1), b2 + hstepB, voffB); PG8_STAGE(PG8_SA(0, 0), a2, voffA);
;             PG8_WAIT_V(8); PG8_WAIT_L(0); PG8_BAR; PG8_MMA(1, 0, At, B0); PG8_MMA(1, 1, At, B1); PG8_BAR; PG8_SCHED;
.LBB0_441:
	s_add_u32 s38, s62, 0x100
	s_addc_u32 s39, s63, 0
	s_add_i32 s81, 0, 0x10000
	v_add_u32_e32 v81, s81, v79
	ds_read_b128 v[82:85], v81
	ds_read_b128 v[86:89], v81 offset:1024
	ds_read_b128 v[90:93], v81 offset:2048
	ds_read_b128 v[94:97], v81 offset:3072
	s_cmp_eq_u32 s80, 4
	s_cselect_b32 s41, s37, s39
	s_cselect_b32 s40, s36, s38
	s_cselect_b32 s65, s51, s79
	s_cselect_b32 s64, s68, s69
	v_lshl_add_u64 v[130:131], s[62:63], 0, v[74:75]
	s_add_i32 m0, s17, 0xc000
	ds_read_b128 v[98:101], v80
	ds_read_b128 v[102:105], v80 offset:1024
	ds_read_b128 v[106:109], v80 offset:2048
	ds_read_b128 v[110:113], v80 offset:3072
	ds_read_b128 v[114:117], v80 offset:4096
	ds_read_b128 v[118:121], v80 offset:5120
	ds_read_b128 v[122:125], v80 offset:6144
	ds_read_b128 v[126:129], v80 offset:7168
	global_load_lds_dwordx4 v[130:131], off
	v_lshl_add_u64 v[130:131], s[62:63], 0, v[76:77]
	s_add_i32 m0, s17, 0xe000
	s_nop 0
	global_load_lds_dwordx4 v[130:131], off
	s_waitcnt vmcnt(8)
	s_waitcnt lgkmcnt(0)
	s_barrier
	s_waitcnt lgkmcnt(0)
	v_mfma_f32_16x16x32_bf16 v[62:65], v[82:85], v[98:101], v[62:65]
	v_mfma_f32_16x16x32_bf16 v[58:61], v[90:93], v[98:101], v[58:61]
	v_mfma_f32_16x16x32_bf16 v[54:57], v[82:85], v[106:109], v[54:57]
	v_mfma_f32_16x16x32_bf16 v[50:53], v[90:93], v[106:109], v[50:53]
	v_mfma_f32_16x16x32_bf16 v[46:49], v[82:85], v[114:117], v[46:49]
	v_mfma_f32_16x16x32_bf16 v[42:45], v[90:93], v[114:117], v[42:45]
	v_mfma_f32_16x16x32_bf16 v[38:41], v[82:85], v[122:125], v[38:41]
	v_mfma_f32_16x16x32_bf16 v[34:37], v[90:93], v[122:125], v[34:37]
	v_mfma_f32_16x16x32_bf16 v[62:65], v[86:89], v[102:105], v[62:65]
	v_mfma_f32_16x16x32_bf16 v[58:61], v[94:97], v[102:105], v[58:61]
	v_mfma_f32_16x16x32_bf16 v[54:57], v[86:89], v[110:113], v[54:57]
	v_mfma_f32_16x16x32_bf16 v[50:53], v[94:97], v[110:113], v[50:53]
	v_mfma_f32_16x16x32_bf16 v[46:49], v[86:89], v[118:121], v[46:49]
	v_mfma_f32_16x16x32_bf16 v[42:45], v[94:97], v[118:121], v[42:45]
	v_mfma_f32_16x16x32_bf16 v[38:41], v[86:89], v[126:129], v[38:41]
	v_mfma_f32_16x16x32_bf16 v[34:37], v[94:97], v[126:129], v[34:37]
	s_barrier
	s_add_i32 s62, s81, s16
	v_lshl_add_u64 v[130:131], s[64:65], 0, v[0:1]
	s_mov_b32 m0, s62
	ds_read_b128 v[98:101], v80 offset:16384
	ds_read_b128 v[102:105], v80 offset:17408
	ds_read_b128 v[106:109], v80 offset:18432
	ds_read_b128 v[110:113], v80 offset:19456
	ds_read_b128 v[114:117], v80 offset:20480
	ds_read_b128 v[118:121], v80 offset:21504
	ds_read_b128 v[122:125], v80 offset:22528
	ds_read_b128 v[126:129], v80 offset:23552
	global_load_lds_dwordx4 v[130:131], off
	s_add_i32 m0, s62, 0x2000
	s_add_u32 s62, s64, 0x20000
	v_lshl_add_u64 v[132:133], s[64:65], 0, v[66:67]
	s_addc_u32 s63, s65, 0
	global_load_lds_dwordx4 v[132:133], off
	v_lshl_add_u64 v[134:135], s[62:63], 0, v[0:1]
	s_mov_b32 m0, s25
	v_lshl_add_u64 v[136:137], s[40:41], 0, v[68:69]
	global_load_lds_dwordx4 v[134:135], off
	v_lshl_add_u64 v[134:135], s[62:63], 0, v[66:67]
	s_mov_b32 m0, s28
	s_nop 0
	global_load_lds_dwordx4 v[134:135], off
	v_lshl_add_u64 v[134:135], s[40:41], 0, v[70:71]
	s_mov_b32 m0, s17
	s_nop 0
	global_load_lds_dwordx4 v[134:135], off
	s_mov_b32 m0, s66
	s_nop 0
	global_load_lds_dwordx4 v[136:137], off
	s_waitcnt vmcnt(8)
	s_waitcnt lgkmcnt(0)
	s_barrier
	s_waitcnt lgkmcnt(0)
	v_mfma_f32_16x16x32_bf16 v[30:33], v[82:85], v[98:101], v[30:33]
	v_mfma_f32_16x16x32_bf16 v[26:29], v[90:93], v[98:101], v[26:29]
	v_mfma_f32_16x16x32_bf16 v[22:25], v[82:85], v[106:109], v[22:25]
	v_mfma_f32_16x16x32_bf16 v[18:21], v[90:93], v[106:109], v[18:21]
	v_mfma_f32_16x16x32_bf16 v[14:17], v[82:85], v[114:117], v[14:17]
	v_mfma_f32_16x16x32_bf16 v[10:13], v[90:93], v[114:117], v[10:13]
	v_mfma_f32_16x16x32_bf16 v[6:9], v[82:85], v[122:125], v[6:9]
	v_mfma_f32_16x16x32_bf16 v[2:5], v[90:93], v[122:125], v[2:5]
	v_mfma_f32_16x16x32_bf16 v[30:33], v[86:89], v[102:105], v[30:33]
	v_mfma_f32_16x16x32_bf16 v[26:29], v[94:97], v[102:105], v[26:29]
	v_mfma_f32_16x16x32_bf16 v[22:25], v[86:89], v[110:113], v[22:25]
	v_mfma_f32_16x16x32_bf16 v[18:21], v[94:97], v[110:113], v[18:21]
	v_mfma_f32_16x16x32_bf16 v[14:17], v[86:89], v[118:121], v[14:17]
	v_mfma_f32_16x16x32_bf16 v[10:13], v[94:97], v[118:121], v[10:13]
	v_mfma_f32_16x16x32_bf16 v[6:9], v[86:89], v[126:129], v[6:9]
	v_mfma_f32_16x16x32_bf16 v[2:5], v[94:97], v[126:129], v[2:5]
	s_barrier
; #define PG8_STAGE(bufoff, gbase, voff) do { _Pragma("unroll") for (int _i = 0; _i < 2; ++_i) \
;         __builtin_amdgcn_global_load_lds((const unsigned*)((const char*)(gbase) + (voff)[_i]), (LAS unsigned*)(lds + (bufoff) + ldsw + _i * 8192), 16, 0, 0); } while (0)
; #define PG8_LDA(dst, b, h) do { _Pragma("unroll") for (int m = 0; m < 4; ++m) _Pragma("unroll") for (int k = 0; k < 2; ++k) dst[m][k] = *(const LAS bf16x8*)(lds + PG8_SA(b, h) + aoff + m * 2048 + k * 1024); } while (0)
; #define PG8_LDB(dst, b, h) do { _Pragma("unroll") for (int n = 0; n < 2; ++n) _Pragma("unroll") for (int k = 0; k < 2; ++k) dst[n][k] = *(const LAS bf16x8*)(lds + PG8_SB(b, h) + boff + n * 2048 + k * 1024); } while (0)
; #define PG8_MMA(ai, bj, At, Bt) do { __builtin_amdgcn_s_setprio(1); _Pragma("unroll") for (int m = 0; m < 4; ++m) _Pragma("unroll") for (int n = 0; n < 2; ++n) _Pragma("unroll") for (int k = 0; k < 2; ++k) \
;         acc[ai][bj][m][n] = __builtin_amdgcn_mfma_f32_16x16x32_bf16(Bt[n][k], At[m][k], acc[ai][bj][m][n], 0, 0, 0); __builtin_amdgcn_s_setprio(0); } while (0)
; #define PG8_WAIT_V(n) asm volatile("s_waitcnt vmcnt(" #n ")" ::: "memory")
; #define PG8_WAIT_L(n) asm volatile("s_waitcnt lgkmcnt(" #n ")" ::: "memory")
; #define PG8_BAR __builtin_amdgcn_s_barrier()
; #define PG8_SCHED __builtin_amdgcn_sched_barrier(0)
; #define PG8_LDA(dst, b, h) do { _Pragma("unroll") for (int m = 0; m < 4; ++m) _Pragma("unroll") for (int k = 0; k < 2; ++k) dst[m][k] = *(const LAS bf16x8*)(lds + PG8_SA(b, h) + aoff + m * 2048 + k * 1024); } while (0)
; #define PG8_BAR __builtin_amdgcn_s_barrier()
; template <class Epi, class Sched>
; DI void gemm_phase(LAS unsigned char* lds, const Gemm g, const Sched& S, const Epi& E) {
;     ...
;             PG8_WAIT_V(8); PG8_WAIT_L(0); PG8_BAR; PG8_MMA(1, 0, At, B0); PG8_MMA(1, 1, At, B1); PG8_BAR; PG8_SCHED;
;             PG8_LDB(B0, 1, 0); PG8_LDB(B1, 1, 1); PG8_SCHED; PG8_LDA(At, 1, 0); PG8_STAGE(PG8_SA(0, 1), a2 + hstepA, voffA);
;             PG8_WAIT_V(8); PG8_WAIT_L(0); PG8_BAR; PG8_MMA(0, 0, At, B0); PG8_MMA(0, 1, At, B1); PG8_BAR; PG8_SCHED;
;             PG8_LDA(At, 1, 1); PG8_STAGE(PG8_SB(1, 0), b3, voffB); PG8_STAGE(PG8_SB(1, 1), b3 + hstepB, voffB); PG8_STAGE(PG8_SA(1, 0), a3, voffA);
;             PG8_WAIT_V(8); PG8_WAIT_L(0); PG8_BAR; PG8_MMA(1, 0, At, B0); PG8_MMA(1, 1, At, B1); PG8_BAR; PG8_SCHED;
;         }
	s_add_i32 s62, 0, 0x18000
	v_add_u32_e32 v81, s62, v79
	ds_read_b128 v[82:85], v81
	ds_read_b128 v[86:89], v81 offset:1024
	ds_read_b128 v[90:93], v81 offset:2048
	ds_read_b128 v[94:97], v81 offset:3072
	s_add_u32 s40, s40, 0x28000
	s_addc_u32 s41, s41, 0
	s_mov_b32 m0, s67
	v_lshl_add_u64 v[138:139], s[40:41], 0, v[70:71]
	ds_read_b128 v[98:101], v80 offset:32768
	ds_read_b128 v[102:105], v80 offset:33792
	ds_read_b128 v[106:109], v80 offset:34816
	ds_read_b128 v[110:113], v80 offset:35840
	ds_read_b128 v[114:117], v80 offset:36864
	ds_read_b128 v[118:121], v80 offset:37888
	ds_read_b128 v[122:125], v80 offset:38912
	ds_read_b128 v[126:129], v80 offset:39936
	global_load_lds_dwordx4 v[138:139], off
	v_lshl_add_u64 v[138:139], s[40:41], 0, v[68:69]
	s_mov_b32 m0, s70
	s_nop 0
	global_load_lds_dwordx4 v[138:139], off
	s_waitcnt vmcnt(8)
	s_waitcnt lgkmcnt(0)
	s_barrier
	s_waitcnt lgkmcnt(0)
	v_mfma_f32_16x16x32_bf16 v[62:65], v[82:85], v[98:101], v[62:65]
	v_mfma_f32_16x16x32_bf16 v[58:61], v[90:93], v[98:101], v[58:61]
	v_mfma_f32_16x16x32_bf16 v[54:57], v[82:85], v[106:109], v[54:57]
	v_mfma_f32_16x16x32_bf16 v[50:53], v[90:93], v[106:109], v[50:53]
	v_mfma_f32_16x16x32_bf16 v[46:49], v[82:85], v[114:117], v[46:49]
	v_mfma_f32_16x16x32_bf16 v[42:45], v[90:93], v[114:117], v[42:45]
	v_mfma_f32_16x16x32_bf16 v[38:41], v[82:85], v[122:125], v[38:41]
	v_mfma_f32_16x16x32_bf16 v[34:37], v[90:93], v[122:125], v[34:37]
	v_mfma_f32_16x16x32_bf16 v[62:65], v[86:89], v[102:105], v[62:65]
	v_mfma_f32_16x16x32_bf16 v[58:61], v[94:97], v[102:105], v[58:61]
	v_mfma_f32_16x16x32_bf16 v[54:57], v[86:89], v[110:113], v[54:57]
	v_mfma_f32_16x16x32_bf16 v[50:53], v[94:97], v[110:113], v[50:53]
	v_mfma_f32_16x16x32_bf16 v[46:49], v[86:89], v[118:121], v[46:49]
	v_mfma_f32_16x16x32_bf16 v[42:45], v[94:97], v[118:121], v[42:45]
	v_mfma_f32_16x16x32_bf16 v[38:41], v[86:89], v[126:129], v[38:41]
	v_mfma_f32_16x16x32_bf16 v[34:37], v[94:97], v[126:129], v[34:37]
	s_barrier
	s_add_i32 s40, s62, s16
	v_lshl_add_u64 v[130:131], v[130:131], 0, s[26:27]
	s_mov_b32 m0, s40
	ds_read_b128 v[98:101], v80 offset:49152
	ds_read_b128 v[102:105], v80 offset:50176
	ds_read_b128 v[106:109], v80 offset:51200
	ds_read_b128 v[110:113], v80 offset:52224
	ds_read_b128 v[114:117], v80 offset:53248
	ds_read_b128 v[118:121], v80 offset:54272
	ds_read_b128 v[122:125], v80 offset:55296
	ds_read_b128 v[126:129], v80 offset:56320
	global_load_lds_dwordx4 v[130:131], off
	s_add_i32 m0, s40, 0x2000
	s_add_u32 s40, s64, 0x20080
	v_lshl_add_u64 v[130:131], v[132:133], 0, s[26:27]
	s_addc_u32 s41, s65, 0
	global_load_lds_dwordx4 v[130:131], off
	v_lshl_add_u64 v[130:131], s[40:41], 0, v[0:1]
	s_mov_b32 m0, s73
	s_nop 0
	global_load_lds_dwordx4 v[130:131], off
	v_lshl_add_u64 v[130:131], s[40:41], 0, v[66:67]
	s_mov_b32 m0, s74
	s_nop 0
	global_load_lds_dwordx4 v[130:131], off
	v_lshl_add_u64 v[130:131], v[134:135], 0, s[26:27]
	s_mov_b32 m0, s71
	s_nop 0
	global_load_lds_dwordx4 v[130:131], off
	v_lshl_add_u64 v[130:131], v[136:137], 0, s[26:27]
	s_mov_b32 m0, s72
	s_nop 0
	global_load_lds_dwordx4 v[130:131], off
	s_waitcnt vmcnt(8)
	s_waitcnt lgkmcnt(0)
	s_barrier
	s_waitcnt lgkmcnt(0)
	v_mfma_f32_16x16x32_bf16 v[30:33], v[82:85], v[98:101], v[30:33]
	v_mfma_f32_16x16x32_bf16 v[26:29], v[90:93], v[98:101], v[26:29]
	v_mfma_f32_16x16x32_bf16 v[22:25], v[82:85], v[106:109], v[22:25]
	v_mfma_f32_16x16x32_bf16 v[18:21], v[90:93], v[106:109], v[18:21]
	v_mfma_f32_16x16x32_bf16 v[14:17], v[82:85], v[114:117], v[14:17]
	v_mfma_f32_16x16x32_bf16 v[10:13], v[90:93], v[114:117], v[10:13]
	v_mfma_f32_16x16x32_bf16 v[6:9], v[82:85], v[122:125], v[6:9]
	v_mfma_f32_16x16x32_bf16 v[2:5], v[90:93], v[122:125], v[2:5]
	v_mfma_f32_16x16x32_bf16 v[30:33], v[86:89], v[102:105], v[30:33]
	v_mfma_f32_16x16x32_bf16 v[26:29], v[94:97], v[102:105], v[26:29]
	v_mfma_f32_16x16x32_bf16 v[22:25], v[86:89], v[110:113], v[22:25]
	v_mfma_f32_16x16x32_bf16 v[18:21], v[94:97], v[110:113], v[18:21]
	v_mfma_f32_16x16x32_bf16 v[14:17], v[86:89], v[118:121], v[14:17]
	v_mfma_f32_16x16x32_bf16 v[10:13], v[94:97], v[118:121], v[10:13]
	v_mfma_f32_16x16x32_bf16 v[6:9], v[86:89], v[126:129], v[6:9]
	v_mfma_f32_16x16x32_bf16 v[2:5], v[94:97], v[126:129], v[2:5]
	s_barrier
	s_add_i32 s80, s80, 2
	s_add_u32 s69, s69, 0x100
	s_addc_u32 s79, s79, 0
	s_cmp_gt_u32 s80, 5
	s_mov_b64 s[62:63], s[38:39]
	s_cbranch_scc0 .LBB0_441
	s_and_b64 vcc, exec, s[44:45]
	s_cbranch_vccz .LBB0_444
	s_barrier

; #define PG8_STAGE(bufoff, gbase, voff) do { _Pragma("unroll") for (int _i = 0; _i < 2; ++_i) \
;         __builtin_amdgcn_global_load_lds((const unsigned*)((const char*)(gbase) + (voff)[_i]), (LAS unsigned*)(lds + (bufoff) + ldsw + _i * 8192), 16, 0, 0); } while (0)
; #define PG8_LDA(dst, b, h) do { _Pragma("unroll") for (int m = 0; m < 4; ++m) _Pragma("unroll") for (int k = 0; k < 2; ++k) dst[m][k] = *(const LAS bf16x8*)(lds + PG8_SA(b, h) + aoff + m * 2048 + k * 1024); } while (0)
; #define PG8_LDB(dst, b, h) do { _Pragma("unroll") for (int n = 0; n < 2; ++n) _Pragma("unroll") for (int k = 0; k < 2; ++k) dst[n][k] = *(const LAS bf16x8*)(lds + PG8_SB(b, h) + boff + n * 2048 + k * 1024); } while (0)
; #define PG8_MMA(ai, bj, At, Bt) do { __builtin_amdgcn_s_setprio(1); _Pragma("unroll") for (int m = 0; m < 4; ++m) _Pragma("unroll") for (int n = 0; n < 2; ++n) _Pragma("unroll") for (int k = 0; k < 2; ++k) \
;         acc[ai][bj][m][n] = __builtin_amdgcn_mfma_f32_16x16x32_bf16(Bt[n][k], At[m][k], acc[ai][bj][m][n], 0, 0, 0); __builtin_amdgcn_s_setprio(0); } while (0)
; #define PG8_WAIT_V(n) asm volatile("s_waitcnt vmcnt(" #n ")" ::: "memory")
; #define PG8_WAIT_L(n) asm volatile("s_waitcnt lgkmcnt(" #n ")" ::: "memory")
; #define PG8_BAR __builtin_amdgcn_s_barrier()
; #define PG8_SCHED __builtin_amdgcn_sched_barrier(0)
; #define PG8_BAR __builtin_amdgcn_s_barrier()
; template <class Epi, class Sched>
; DI void gemm_phase(LAS unsigned char* lds, const Gemm g, const Sched& S, const Epi& E) {
;     ...
;         for (int t = 0; t < nt; t += 2) {
;             const bool last = (t == nt - 2);
;             const char* a1 = cA + (size_t)(t + 1) * kstep;
;             const char* a2 = last ? nA : cA + (size_t)(t + 2) * kstep; const char* b2 = last ? nB : cB + (size_t)(t + 2) * kstep;
;             const char* a3 = a2 + kstep; const char* b3 = b2 + kstep;
;             PG8_LDB(B0, 0, 0); PG8_LDB(B1, 0, 1); PG8_SCHED; PG8_LDA(At, 0, 0); PG8_STAGE(PG8_SA(1, 1), a1 + hstepA, voffA);
;             PG8_WAIT_V(8); PG8_WAIT_L(0); PG8_BAR; PG8_MMA(0, 0, At, B0); PG8_MMA(0, 1, At, B1); PG8_BAR; PG8_SCHED;
;             PG8_LDA(At, 0, 1); PG8_STAGE(PG8_SB(0, 0), b2, voffB); PG8_STAGE(PG8_SB(0, 1), b2 + hstepB, voffB); PG8_STAGE(PG8_SA(0, 0), a2, voffA);
;             PG8_WAIT_V(8); PG8_WAIT_L(0); PG8_BAR; PG8_MMA(1, 0, At, B0); PG8_MMA(1, 1, At, B1); PG8_BAR; PG8_SCHED;
.LBB0_571:
	s_add_u32 s36, s30, 0x100
	s_addc_u32 s37, s31, 0
	s_add_i32 s80, 0, 0x10000
	s_cmp_eq_u32 s79, 6
	s_cselect_b32 s45, s67, s37
	s_cselect_b32 s44, s66, s36
	v_add_u32_e32 v149, s80, v142
	s_cselect_b32 s39, s69, s78
	s_cselect_b32 s38, s68, s71
	s_add_i32 s81, 0, 0x14000
	ds_read_b128 v[150:153], v149
	ds_read_b128 v[154:157], v149 offset:1024
	ds_read_b128 v[158:161], v149 offset:2048
	ds_read_b128 v[162:165], v149 offset:3072
	v_add_u32_e32 v149, s81, v142
	ds_read_b128 v[166:169], v149
	ds_read_b128 v[170:173], v149 offset:1024
	ds_read_b128 v[174:177], v149 offset:2048
	ds_read_b128 v[178:181], v149 offset:3072
	v_lshl_add_u64 v[194:195], s[30:31], 0, v[138:139]
	s_add_i32 m0, s12, 0xc000
	ds_read_b128 v[182:185], v148
	ds_read_b128 v[186:189], v148 offset:1024
	ds_read_b128 v[190:193], v148 offset:2048
	ds_read_b128 v[198:201], v148 offset:3072
	ds_read_b128 v[208:211], v148 offset:4096
	ds_read_b128 v[212:215], v148 offset:5120
	ds_read_b128 v[216:219], v148 offset:6144
	ds_read_b128 v[220:223], v148 offset:7168
	global_load_lds_dwordx4 v[194:195], off
	v_lshl_add_u64 v[194:195], s[30:31], 0, v[140:141]
	s_add_i32 m0, s12, 0xe000
	s_nop 0
	global_load_lds_dwordx4 v[194:195], off
	s_waitcnt vmcnt(8)
	s_waitcnt lgkmcnt(0)
	s_barrier
	s_waitcnt lgkmcnt(0)
	v_mfma_f32_16x16x32_bf16 v[126:129], v[150:153], v[182:185], v[126:129]
	v_mfma_f32_16x16x32_bf16 v[122:125], v[158:161], v[182:185], v[122:125]
	v_mfma_f32_16x16x32_bf16 v[110:113], v[150:153], v[190:193], v[110:113]
	v_mfma_f32_16x16x32_bf16 v[106:109], v[158:161], v[190:193], v[106:109]
	v_mfma_f32_16x16x32_bf16 v[94:97], v[150:153], v[208:211], v[94:97]
	v_mfma_f32_16x16x32_bf16 v[90:93], v[158:161], v[208:211], v[90:93]
	v_mfma_f32_16x16x32_bf16 v[78:81], v[150:153], v[216:219], v[78:81]
	v_mfma_f32_16x16x32_bf16 v[74:77], v[158:161], v[216:219], v[74:77]
	v_mfma_f32_16x16x32_bf16 v[126:129], v[154:157], v[186:189], v[126:129]
	v_mfma_f32_16x16x32_bf16 v[122:125], v[162:165], v[186:189], v[122:125]
	v_mfma_f32_16x16x32_bf16 v[110:113], v[154:157], v[198:201], v[110:113]
	v_mfma_f32_16x16x32_bf16 v[106:109], v[162:165], v[198:201], v[106:109]
	v_mfma_f32_16x16x32_bf16 v[94:97], v[154:157], v[212:215], v[94:97]
	v_mfma_f32_16x16x32_bf16 v[90:93], v[162:165], v[212:215], v[90:93]
	v_mfma_f32_16x16x32_bf16 v[78:81], v[154:157], v[220:223], v[78:81]
	v_mfma_f32_16x16x32_bf16 v[74:77], v[162:165], v[220:223], v[74:77]
	v_mfma_f32_16x16x32_bf16 v[118:121], v[166:169], v[182:185], v[118:121]
	v_mfma_f32_16x16x32_bf16 v[114:117], v[174:177], v[182:185], v[114:117]
	v_mfma_f32_16x16x32_bf16 v[102:105], v[166:169], v[190:193], v[102:105]
	v_mfma_f32_16x16x32_bf16 v[98:101], v[174:177], v[190:193], v[98:101]
	v_mfma_f32_16x16x32_bf16 v[86:89], v[166:169], v[208:211], v[86:89]
	v_mfma_f32_16x16x32_bf16 v[82:85], v[174:177], v[208:211], v[82:85]
	v_mfma_f32_16x16x32_bf16 v[70:73], v[166:169], v[216:219], v[70:73]
	v_mfma_f32_16x16x32_bf16 v[66:69], v[174:177], v[216:219], v[66:69]
	v_mfma_f32_16x16x32_bf16 v[118:121], v[170:173], v[186:189], v[118:121]
	v_mfma_f32_16x16x32_bf16 v[114:117], v[178:181], v[186:189], v[114:117]
	v_mfma_f32_16x16x32_bf16 v[102:105], v[170:173], v[198:201], v[102:105]
	v_mfma_f32_16x16x32_bf16 v[98:101], v[178:181], v[198:201], v[98:101]
	v_mfma_f32_16x16x32_bf16 v[86:89], v[170:173], v[212:215], v[86:89]
	v_mfma_f32_16x16x32_bf16 v[82:85], v[178:181], v[212:215], v[82:85]
	v_mfma_f32_16x16x32_bf16 v[70:73], v[170:173], v[220:223], v[70:73]
	v_mfma_f32_16x16x32_bf16 v[66:69], v[178:181], v[220:223], v[66:69]
	s_barrier
	s_add_i32 s30, s80, s50
	v_lshl_add_u64 v[194:195], s[38:39], 0, v[134:135]
	s_mov_b32 m0, s30
	ds_read_b128 v[182:185], v148 offset:16384
	ds_read_b128 v[186:189], v148 offset:17408
	ds_read_b128 v[190:193], v148 offset:18432
	ds_read_b128 v[198:201], v148 offset:19456
	ds_read_b128 v[208:211], v148 offset:20480
	ds_read_b128 v[212:215], v148 offset:21504
	ds_read_b128 v[216:219], v148 offset:22528
	ds_read_b128 v[220:223], v148 offset:23552
	global_load_lds_dwordx4 v[194:195], off
	s_add_i32 m0, s30, 0x2000
	s_add_u32 s30, s38, 0x28000
	v_lshl_add_u64 v[204:205], s[38:39], 0, v[130:131]
	s_addc_u32 s31, s39, 0
	s_add_i32 s80, s81, s50
	global_load_lds_dwordx4 v[204:205], off
	v_lshl_add_u64 v[206:207], s[30:31], 0, v[134:135]
	s_mov_b32 m0, s80
	v_lshl_add_u64 v[224:225], s[44:45], 0, v[132:133]
	global_load_lds_dwordx4 v[206:207], off
	v_lshl_add_u64 v[206:207], s[30:31], 0, v[130:131]
	s_add_i32 m0, s80, 0x2000
	s_nop 0
	global_load_lds_dwordx4 v[206:207], off
	v_lshl_add_u64 v[206:207], s[44:45], 0, v[136:137]
	s_mov_b32 m0, s12
	s_nop 0
	global_load_lds_dwordx4 v[206:207], off
	s_mov_b32 m0, s13
	s_nop 0
	global_load_lds_dwordx4 v[224:225], off
	s_waitcnt vmcnt(8)
	s_waitcnt lgkmcnt(0)
	s_barrier
; #define PG8_STAGE(bufoff, gbase, voff) do { _Pragma("unroll") for (int _i = 0; _i < 2; ++_i) \
;         __builtin_amdgcn_global_load_lds((const unsigned*)((const char*)(gbase) + (voff)[_i]), (LAS unsigned*)(lds + (bufoff) + ldsw + _i * 8192), 16, 0, 0); } while (0)
; #define PG8_LDA(dst, b, h) do { _Pragma("unroll") for (int m = 0; m < 4; ++m) _Pragma("unroll") for (int k = 0; k < 2; ++k) dst[m][k] = *(const LAS bf16x8*)(lds + PG8_SA(b, h) + aoff + m * 2048 + k * 1024); } while (0)
; #define PG8_LDB(dst, b, h) do { _Pragma("unroll") for (int n = 0; n < 2; ++n) _Pragma("unroll") for (int k = 0; k < 2; ++k) dst[n][k] = *(const LAS bf16x8*)(lds + PG8_SB(b, h) + boff + n * 2048 + k * 1024); } while (0)
; #define PG8_MMA(ai, bj, At, Bt) do { __builtin_amdgcn_s_setprio(1); _Pragma("unroll") for (int m = 0; m < 4; ++m) _Pragma("unroll") for (int n = 0; n < 2; ++n) _Pragma("unroll") for (int k = 0; k < 2; ++k) \
;         acc[ai][bj][m][n] = __builtin_amdgcn_mfma_f32_16x16x32_bf16(Bt[n][k], At[m][k], acc[ai][bj][m][n], 0, 0, 0); __builtin_amdgcn_s_setprio(0); } while (0)
; #define PG8_WAIT_V(n) asm volatile("s_waitcnt vmcnt(" #n ")" ::: "memory")
; #define PG8_WAIT_L(n) asm volatile("s_waitcnt lgkmcnt(" #n ")" ::: "memory")
; #define PG8_BAR __builtin_amdgcn_s_barrier()
; #define PG8_SCHED __builtin_amdgcn_sched_barrier(0)
; #define PG8_LDA(dst, b, h) do { _Pragma("unroll") for (int m = 0; m < 4; ++m) _Pragma("unroll") for (int k = 0; k < 2; ++k) dst[m][k] = *(const LAS bf16x8*)(lds + PG8_SA(b, h) + aoff + m * 2048 + k * 1024); } while (0)
; #define PG8_WAIT_V(n) asm volatile("s_waitcnt vmcnt(" #n ")" ::: "memory")
; #define PG8_WAIT_L(n) asm volatile("s_waitcnt lgkmcnt(" #n ")" ::: "memory")
; template <class Epi, class Sched>
; DI void gemm_phase(LAS unsigned char* lds, const Gemm g, const Sched& S, const Epi& E) {
;     ...
;             PG8_WAIT_V(8); PG8_WAIT_L(0); PG8_BAR; PG8_MMA(1, 0, At, B0); PG8_MMA(1, 1, At, B1); PG8_BAR; PG8_SCHED;
;             PG8_LDB(B0, 1, 0); PG8_LDB(B1, 1, 1); PG8_SCHED; PG8_LDA(At, 1, 0); PG8_STAGE(PG8_SA(0, 1), a2 + hstepA, voffA);
;             PG8_WAIT_V(8); PG8_WAIT_L(0); PG8_BAR; PG8_MMA(0, 0, At, B0); PG8_MMA(0, 1, At, B1); PG8_BAR; PG8_SCHED;
;             PG8_LDA(At, 1, 1); PG8_STAGE(PG8_SB(1, 0), b3, voffB); PG8_STAGE(PG8_SB(1, 1), b3 + hstepB, voffB); PG8_STAGE(PG8_SA(1, 0), a3, voffA);
	s_waitcnt lgkmcnt(0)
	v_mfma_f32_16x16x32_bf16 v[62:65], v[150:153], v[182:185], v[62:65]
	v_mfma_f32_16x16x32_bf16 v[58:61], v[158:161], v[182:185], v[58:61]
	v_mfma_f32_16x16x32_bf16 v[46:49], v[150:153], v[190:193], v[46:49]
	v_mfma_f32_16x16x32_bf16 v[42:45], v[158:161], v[190:193], v[42:45]
	v_mfma_f32_16x16x32_bf16 v[30:33], v[150:153], v[208:211], v[30:33]
	v_mfma_f32_16x16x32_bf16 v[26:29], v[158:161], v[208:211], v[26:29]
	v_mfma_f32_16x16x32_bf16 v[14:17], v[150:153], v[216:219], v[14:17]
	v_mfma_f32_16x16x32_bf16 v[10:13], v[158:161], v[216:219], v[10:13]
	v_mfma_f32_16x16x32_bf16 v[62:65], v[154:157], v[186:189], v[62:65]
	v_mfma_f32_16x16x32_bf16 v[58:61], v[162:165], v[186:189], v[58:61]
	v_mfma_f32_16x16x32_bf16 v[46:49], v[154:157], v[198:201], v[46:49]
	v_mfma_f32_16x16x32_bf16 v[42:45], v[162:165], v[198:201], v[42:45]
	v_mfma_f32_16x16x32_bf16 v[30:33], v[154:157], v[212:215], v[30:33]
	v_mfma_f32_16x16x32_bf16 v[26:29], v[162:165], v[212:215], v[26:29]
	v_mfma_f32_16x16x32_bf16 v[14:17], v[154:157], v[220:223], v[14:17]
	v_mfma_f32_16x16x32_bf16 v[10:13], v[162:165], v[220:223], v[10:13]
	v_mfma_f32_16x16x32_bf16 v[54:57], v[166:169], v[182:185], v[54:57]
	v_mfma_f32_16x16x32_bf16 v[50:53], v[174:177], v[182:185], v[50:53]
	v_mfma_f32_16x16x32_bf16 v[38:41], v[166:169], v[190:193], v[38:41]
	v_mfma_f32_16x16x32_bf16 v[34:37], v[174:177], v[190:193], v[34:37]
	v_mfma_f32_16x16x32_bf16 v[22:25], v[166:169], v[208:211], v[22:25]
	v_mfma_f32_16x16x32_bf16 v[18:21], v[174:177], v[208:211], v[18:21]
	v_mfma_f32_16x16x32_bf16 v[6:9], v[166:169], v[216:219], v[6:9]
	v_mfma_f32_16x16x32_bf16 v[2:5], v[174:177], v[216:219], v[2:5]
	v_mfma_f32_16x16x32_bf16 v[54:57], v[170:173], v[186:189], v[54:57]
	v_mfma_f32_16x16x32_bf16 v[50:53], v[178:181], v[186:189], v[50:53]
	v_mfma_f32_16x16x32_bf16 v[38:41], v[170:173], v[198:201], v[38:41]
	v_mfma_f32_16x16x32_bf16 v[34:37], v[178:181], v[198:201], v[34:37]
	v_mfma_f32_16x16x32_bf16 v[22:25], v[170:173], v[212:215], v[22:25]
	v_mfma_f32_16x16x32_bf16 v[18:21], v[178:181], v[212:215], v[18:21]
	v_mfma_f32_16x16x32_bf16 v[6:9], v[170:173], v[220:223], v[6:9]
	v_mfma_f32_16x16x32_bf16 v[2:5], v[178:181], v[220:223], v[2:5]
	s_barrier
	s_add_i32 s80, 0, 0x18000
	v_add_u32_e32 v149, s80, v142
	s_add_i32 s81, 0, 0x1c000
	ds_read_b128 v[150:153], v149
	ds_read_b128 v[154:157], v149 offset:1024
	ds_read_b128 v[158:161], v149 offset:2048
	ds_read_b128 v[162:165], v149 offset:3072
	v_add_u32_e32 v149, s81, v142
	ds_read_b128 v[166:169], v149
	ds_read_b128 v[170:173], v149 offset:1024
	ds_read_b128 v[174:177], v149 offset:2048
	ds_read_b128 v[178:181], v149 offset:3072
	s_add_u32 s30, s44, 0x28000
	s_addc_u32 s31, s45, 0
	s_mov_b32 m0, s51
	v_lshl_add_u64 v[226:227], s[30:31], 0, v[136:137]
	ds_read_b128 v[182:185], v148 offset:32768
	ds_read_b128 v[186:189], v148 offset:33792
	ds_read_b128 v[190:193], v148 offset:34816
	ds_read_b128 v[198:201], v148 offset:35840
	ds_read_b128 v[208:211], v148 offset:36864
	ds_read_b128 v[212:215], v148 offset:37888
	ds_read_b128 v[216:219], v148 offset:38912
	ds_read_b128 v[220:223], v148 offset:39936
	global_load_lds_dwordx4 v[226:227], off
	v_lshl_add_u64 v[226:227], s[30:31], 0, v[132:133]
	s_mov_b32 m0, s72
	s_nop 0
	global_load_lds_dwordx4 v[226:227], off
	s_waitcnt vmcnt(8)
	s_waitcnt lgkmcnt(0)
	s_barrier
	s_waitcnt lgkmcnt(0)
	v_mfma_f32_16x16x32_bf16 v[126:129], v[150:153], v[182:185], v[126:129]
	v_mfma_f32_16x16x32_bf16 v[122:125], v[158:161], v[182:185], v[122:125]
	v_mfma_f32_16x16x32_bf16 v[110:113], v[150:153], v[190:193], v[110:113]
	v_mfma_f32_16x16x32_bf16 v[106:109], v[158:161], v[190:193], v[106:109]
	v_mfma_f32_16x16x32_bf16 v[94:97], v[150:153], v[208:211], v[94:97]
	v_mfma_f32_16x16x32_bf16 v[90:93], v[158:161], v[208:211], v[90:93]
	v_mfma_f32_16x16x32_bf16 v[78:81], v[150:153], v[216:219], v[78:81]
	v_mfma_f32_16x16x32_bf16 v[74:77], v[158:161], v[216:219], v[74:77]
	v_mfma_f32_16x16x32_bf16 v[126:129], v[154:157], v[186:189], v[126:129]
	v_mfma_f32_16x16x32_bf16 v[122:125], v[162:165], v[186:189], v[122:125]
	v_mfma_f32_16x16x32_bf16 v[110:113], v[154:157], v[198:201], v[110:113]
	v_mfma_f32_16x16x32_bf16 v[106:109], v[162:165], v[198:201], v[106:109]
	v_mfma_f32_16x16x32_bf16 v[94:97], v[154:157], v[212:215], v[94:97]
	v_mfma_f32_16x16x32_bf16 v[90:93], v[162:165], v[212:215], v[90:93]
	v_mfma_f32_16x16x32_bf16 v[78:81], v[154:157], v[220:223], v[78:81]
	v_mfma_f32_16x16x32_bf16 v[74:77], v[162:165], v[220:223], v[74:77]
	v_mfma_f32_16x16x32_bf16 v[118:121], v[166:169], v[182:185], v[118:121]
	v_mfma_f32_16x16x32_bf16 v[114:117], v[174:177], v[182:185], v[114:117]
	v_mfma_f32_16x16x32_bf16 v[102:105], v[166:169], v[190:193], v[102:105]
	v_mfma_f32_16x16x32_bf16 v[98:101], v[174:177], v[190:193], v[98:101]
	v_mfma_f32_16x16x32_bf16 v[86:89], v[166:169], v[208:211], v[86:89]
	v_mfma_f32_16x16x32_bf16 v[82:85], v[174:177], v[208:211], v[82:85]
	v_mfma_f32_16x16x32_bf16 v[70:73], v[166:169], v[216:219], v[70:73]
	v_mfma_f32_16x16x32_bf16 v[66:69], v[174:177], v[216:219], v[66:69]
	v_mfma_f32_16x16x32_bf16 v[118:121], v[170:173], v[186:189], v[118:121]
	v_mfma_f32_16x16x32_bf16 v[114:117], v[178:181], v[186:189], v[114:117]
	v_mfma_f32_16x16x32_bf16 v[102:105], v[170:173], v[198:201], v[102:105]
	v_mfma_f32_16x16x32_bf16 v[98:101], v[178:181], v[198:201], v[98:101]
	v_mfma_f32_16x16x32_bf16 v[86:89], v[170:173], v[212:215], v[86:89]
	v_mfma_f32_16x16x32_bf16 v[82:85], v[178:181], v[212:215], v[82:85]
	v_mfma_f32_16x16x32_bf16 v[70:73], v[170:173], v[220:223], v[70:73]
	v_mfma_f32_16x16x32_bf16 v[66:69], v[178:181], v[220:223], v[66:69]
	s_barrier
; #define PG8_STAGE(bufoff, gbase, voff) do { _Pragma("unroll") for (int _i = 0; _i < 2; ++_i) \
;         __builtin_amdgcn_global_load_lds((const unsigned*)((const char*)(gbase) + (voff)[_i]), (LAS unsigned*)(lds + (bufoff) + ldsw + _i * 8192), 16, 0, 0); } while (0)
; #define PG8_LDA(dst, b, h) do { _Pragma("unroll") for (int m = 0; m < 4; ++m) _Pragma("unroll") for (int k = 0; k < 2; ++k) dst[m][k] = *(const LAS bf16x8*)(lds + PG8_SA(b, h) + aoff + m * 2048 + k * 1024); } while (0)
; #define PG8_MMA(ai, bj, At, Bt) do { __builtin_amdgcn_s_setprio(1); _Pragma("unroll") for (int m = 0; m < 4; ++m) _Pragma("unroll") for (int n = 0; n < 2; ++n) _Pragma("unroll") for (int k = 0; k < 2; ++k) \
;         acc[ai][bj][m][n] = __builtin_amdgcn_mfma_f32_16x16x32_bf16(Bt[n][k], At[m][k], acc[ai][bj][m][n], 0, 0, 0); __builtin_amdgcn_s_setprio(0); } while (0)
; #define PG8_WAIT_V(n) asm volatile("s_waitcnt vmcnt(" #n ")" ::: "memory")
; #define PG8_WAIT_L(n) asm volatile("s_waitcnt lgkmcnt(" #n ")" ::: "memory")
; #define PG8_BAR __builtin_amdgcn_s_barrier()
; #define PG8_SCHED __builtin_amdgcn_sched_barrier(0)
; #define PG8_LDA(dst, b, h) do { _Pragma("unroll") for (int m = 0; m < 4; ++m) _Pragma("unroll") for (int k = 0; k < 2; ++k) dst[m][k] = *(const LAS bf16x8*)(lds + PG8_SA(b, h) + aoff + m * 2048 + k * 1024); } while (0)
; #define PG8_MMA(ai, bj, At, Bt) do { __builtin_amdgcn_s_setprio(1); _Pragma("unroll") for (int m = 0; m < 4; ++m) _Pragma("unroll") for (int n = 0; n < 2; ++n) _Pragma("unroll") for (int k = 0; k < 2; ++k) \
;         acc[ai][bj][m][n] = __builtin_amdgcn_mfma_f32_16x16x32_bf16(Bt[n][k], At[m][k], acc[ai][bj][m][n], 0, 0, 0); __builtin_amdgcn_s_setprio(0); } while (0)
; #define PG8_WAIT_V(n) asm volatile("s_waitcnt vmcnt(" #n ")" ::: "memory")
; #define PG8_WAIT_L(n) asm volatile("s_waitcnt lgkmcnt(" #n ")" ::: "memory")
; #define PG8_BAR __builtin_amdgcn_s_barrier()
; #define PG8_SCHED __builtin_amdgcn_sched_barrier(0)
; template <class Epi, class Sched>
; DI void gemm_phase(LAS unsigned char* lds, const Gemm g, const Sched& S, const Epi& E) {
;     ...
;             PG8_LDA(At, 1, 1); PG8_STAGE(PG8_SB(1, 0), b3, voffB); PG8_STAGE(PG8_SB(1, 1), b3 + hstepB, voffB); PG8_STAGE(PG8_SA(1, 0), a3, voffA);
;             PG8_WAIT_V(8); PG8_WAIT_L(0); PG8_BAR; PG8_MMA(1, 0, At, B0); PG8_MMA(1, 1, At, B1); PG8_BAR; PG8_SCHED;
;         }
	s_add_i32 s30, s80, s50
	v_lshl_add_u64 v[194:195], v[194:195], 0, s[26:27]
	s_mov_b32 m0, s30
	ds_read_b128 v[182:185], v148 offset:49152
	ds_read_b128 v[186:189], v148 offset:50176
	ds_read_b128 v[190:193], v148 offset:51200
	ds_read_b128 v[198:201], v148 offset:52224
	ds_read_b128 v[208:211], v148 offset:53248
	ds_read_b128 v[212:215], v148 offset:54272
	ds_read_b128 v[216:219], v148 offset:55296
	ds_read_b128 v[220:223], v148 offset:56320
	global_load_lds_dwordx4 v[194:195], off
	s_add_i32 m0, s30, 0x2000
	s_add_u32 s30, s38, 0x28080
	v_lshl_add_u64 v[194:195], v[204:205], 0, s[26:27]
	s_addc_u32 s31, s39, 0
	s_add_i32 s38, s81, s50
	global_load_lds_dwordx4 v[194:195], off
	v_lshl_add_u64 v[194:195], s[30:31], 0, v[134:135]
	s_mov_b32 m0, s38
	s_nop 0
	global_load_lds_dwordx4 v[194:195], off
	v_lshl_add_u64 v[194:195], s[30:31], 0, v[130:131]
	s_add_i32 m0, s38, 0x2000
	s_nop 0
	global_load_lds_dwordx4 v[194:195], off
	v_lshl_add_u64 v[194:195], v[206:207], 0, s[26:27]
	s_mov_b32 m0, s74
	s_nop 0
	global_load_lds_dwordx4 v[194:195], off
	v_lshl_add_u64 v[194:195], v[224:225], 0, s[26:27]
	s_mov_b32 m0, s75
	s_nop 0
	global_load_lds_dwordx4 v[194:195], off
	s_waitcnt vmcnt(8)
	s_waitcnt lgkmcnt(0)
	s_barrier
	s_waitcnt lgkmcnt(0)
	v_mfma_f32_16x16x32_bf16 v[62:65], v[150:153], v[182:185], v[62:65]
	v_mfma_f32_16x16x32_bf16 v[58:61], v[158:161], v[182:185], v[58:61]
	v_mfma_f32_16x16x32_bf16 v[46:49], v[150:153], v[190:193], v[46:49]
	v_mfma_f32_16x16x32_bf16 v[42:45], v[158:161], v[190:193], v[42:45]
	v_mfma_f32_16x16x32_bf16 v[30:33], v[150:153], v[208:211], v[30:33]
	v_mfma_f32_16x16x32_bf16 v[26:29], v[158:161], v[208:211], v[26:29]
	v_mfma_f32_16x16x32_bf16 v[14:17], v[150:153], v[216:219], v[14:17]
	v_mfma_f32_16x16x32_bf16 v[10:13], v[158:161], v[216:219], v[10:13]
	v_mfma_f32_16x16x32_bf16 v[62:65], v[154:157], v[186:189], v[62:65]
	v_mfma_f32_16x16x32_bf16 v[58:61], v[162:165], v[186:189], v[58:61]
	v_mfma_f32_16x16x32_bf16 v[46:49], v[154:157], v[198:201], v[46:49]
	v_mfma_f32_16x16x32_bf16 v[42:45], v[162:165], v[198:201], v[42:45]
	v_mfma_f32_16x16x32_bf16 v[30:33], v[154:157], v[212:215], v[30:33]
	v_mfma_f32_16x16x32_bf16 v[26:29], v[162:165], v[212:215], v[26:29]
	v_mfma_f32_16x16x32_bf16 v[14:17], v[154:157], v[220:223], v[14:17]
	v_mfma_f32_16x16x32_bf16 v[10:13], v[162:165], v[220:223], v[10:13]
	v_mfma_f32_16x16x32_bf16 v[54:57], v[166:169], v[182:185], v[54:57]
	v_mfma_f32_16x16x32_bf16 v[50:53], v[174:177], v[182:185], v[50:53]
	v_mfma_f32_16x16x32_bf16 v[38:41], v[166:169], v[190:193], v[38:41]
	v_mfma_f32_16x16x32_bf16 v[34:37], v[174:177], v[190:193], v[34:37]
	v_mfma_f32_16x16x32_bf16 v[22:25], v[166:169], v[208:211], v[22:25]
	v_mfma_f32_16x16x32_bf16 v[18:21], v[174:177], v[208:211], v[18:21]
	v_mfma_f32_16x16x32_bf16 v[6:9], v[166:169], v[216:219], v[6:9]
	v_mfma_f32_16x16x32_bf16 v[2:5], v[174:177], v[216:219], v[2:5]
	v_mfma_f32_16x16x32_bf16 v[54:57], v[170:173], v[186:189], v[54:57]
	v_mfma_f32_16x16x32_bf16 v[50:53], v[178:181], v[186:189], v[50:53]
	v_mfma_f32_16x16x32_bf16 v[38:41], v[170:173], v[198:201], v[38:41]
	v_mfma_f32_16x16x32_bf16 v[34:37], v[178:181], v[198:201], v[34:37]
	v_mfma_f32_16x16x32_bf16 v[22:25], v[170:173], v[212:215], v[22:25]
	v_mfma_f32_16x16x32_bf16 v[18:21], v[178:181], v[212:215], v[18:21]
	v_mfma_f32_16x16x32_bf16 v[6:9], v[170:173], v[220:223], v[6:9]
	v_mfma_f32_16x16x32_bf16 v[2:5], v[178:181], v[220:223], v[2:5]
	s_barrier
	s_add_i32 s79, s79, 2
	s_add_u32 s71, s71, 0x100
	s_addc_u32 s78, s78, 0
	s_cmp_gt_u32 s79, 7
	s_mov_b64 s[30:31], s[36:37]
	s_cbranch_scc0 .LBB0_571
	s_and_b64 vcc, exec, s[64:65]
	s_cbranch_vccz .LBB0_574
	s_barrier

; #define PG8_STAGE(bufoff, gbase, voff) do { _Pragma("unroll") for (int _i = 0; _i < 2; ++_i) \
;         __builtin_amdgcn_global_load_lds((const unsigned*)((const char*)(gbase) + (voff)[_i]), (LAS unsigned*)(lds + (bufoff) + ldsw + _i * 8192), 16, 0, 0); } while (0)
; #define PG8_LDA(dst, b, h) do { _Pragma("unroll") for (int m = 0; m < 4; ++m) _Pragma("unroll") for (int k = 0; k < 2; ++k) dst[m][k] = *(const LAS bf16x8*)(lds + PG8_SA(b, h) + aoff + m * 2048 + k * 1024); } while (0)
; #define PG8_LDB(dst, b, h) do { _Pragma("unroll") for (int n = 0; n < 2; ++n) _Pragma("unroll") for (int k = 0; k < 2; ++k) dst[n][k] = *(const LAS bf16x8*)(lds + PG8_SB(b, h) + boff + n * 2048 + k * 1024); } while (0)
; #define PG8_MMA(ai, bj, At, Bt) do { __builtin_amdgcn_s_setprio(1); _Pragma("unroll") for (int m = 0; m < 4; ++m) _Pragma("unroll") for (int n = 0; n < 2; ++n) _Pragma("unroll") for (int k = 0; k < 2; ++k) \
;         acc[ai][bj][m][n] = __builtin_amdgcn_mfma_f32_16x16x32_bf16(Bt[n][k], At[m][k], acc[ai][bj][m][n], 0, 0, 0); __builtin_amdgcn_s_setprio(0); } while (0)
; #define PG8_WAIT_V(n) asm volatile("s_waitcnt vmcnt(" #n ")" ::: "memory")
; #define PG8_WAIT_L(n) asm volatile("s_waitcnt lgkmcnt(" #n ")" ::: "memory")
; #define PG8_BAR __builtin_amdgcn_s_barrier()
; #define PG8_SCHED __builtin_amdgcn_sched_barrier(0)
; #define PG8_BAR __builtin_amdgcn_s_barrier()
; template <class Epi, class Sched>
; DI void gemm_phase(LAS unsigned char* lds, const Gemm g, const Sched& S, const Epi& E) {
;     ...
;         for (int t = 0; t < nt; t += 2) {
;             const bool last = (t == nt - 2);
;             const char* a1 = cA + (size_t)(t + 1) * kstep;
;             const char* a2 = last ? nA : cA + (size_t)(t + 2) * kstep; const char* b2 = last ? nB : cB + (size_t)(t + 2) * kstep;
;             const char* a3 = a2 + kstep; const char* b3 = b2 + kstep;
;             PG8_LDB(B0, 0, 0); PG8_LDB(B1, 0, 1); PG8_SCHED; PG8_LDA(At, 0, 0); PG8_STAGE(PG8_SA(1, 1), a1 + hstepA, voffA);
;             PG8_WAIT_V(8); PG8_WAIT_L(0); PG8_BAR; PG8_MMA(0, 0, At, B0); PG8_MMA(0, 1, At, B1); PG8_BAR; PG8_SCHED;
;             PG8_LDA(At, 0, 1); PG8_STAGE(PG8_SB(0, 0), b2, voffB); PG8_STAGE(PG8_SB(0, 1), b2 + hstepB, voffB); PG8_STAGE(PG8_SA(0, 0), a2, voffA);
;             PG8_WAIT_V(8); PG8_WAIT_L(0); PG8_BAR; PG8_MMA(1, 0, At, B0); PG8_MMA(1, 1, At, B1); PG8_BAR; PG8_SCHED;
.LBB0_643:
	s_add_u32 s36, s30, 0xfffe0080
	s_addc_u32 s37, s31, -1
	s_add_i32 s79, 0, 0x10000
	s_cmp_eq_u32 s78, 4
	s_cselect_b32 s39, s69, s37
	s_cselect_b32 s38, s74, s36
	v_add_u32_e32 v140, s79, v143
	s_cselect_b32 s37, s67, s77
	s_cselect_b32 s36, s75, s76
	s_add_i32 s82, 0, 0x14000
	ds_read_b128 v[146:149], v140
	ds_read_b128 v[150:153], v140 offset:1024
	ds_read_b128 v[154:157], v140 offset:2048
	ds_read_b128 v[158:161], v140 offset:3072
	v_add_u32_e32 v140, s82, v143
	ds_read_b128 v[162:165], v140
	ds_read_b128 v[166:169], v140 offset:1024
	ds_read_b128 v[170:173], v140 offset:2048
	ds_read_b128 v[174:177], v140 offset:3072
	v_lshl_add_u64 v[140:141], s[30:31], 0, v[136:137]
	s_add_i32 m0, s17, 0xc000
	ds_read_b128 v[178:181], v145
	ds_read_b128 v[182:185], v145 offset:1024
	ds_read_b128 v[186:189], v145 offset:2048
	ds_read_b128 v[190:193], v145 offset:3072
	ds_read_b128 v[198:201], v145 offset:4096
	ds_read_b128 v[208:211], v145 offset:5120
	ds_read_b128 v[212:215], v145 offset:6144
	ds_read_b128 v[216:219], v145 offset:7168
	global_load_lds_dwordx4 v[140:141], off
	v_lshl_add_u64 v[140:141], s[30:31], 0, v[138:139]
	s_add_i32 m0, s17, 0xe000
	s_nop 0
	global_load_lds_dwordx4 v[140:141], off
	s_waitcnt vmcnt(8)
	s_waitcnt lgkmcnt(0)
	s_barrier
	s_waitcnt lgkmcnt(0)
	v_mfma_f32_16x16x32_bf16 v[126:129], v[146:149], v[178:181], v[126:129]
	v_mfma_f32_16x16x32_bf16 v[122:125], v[154:157], v[178:181], v[122:125]
	v_mfma_f32_16x16x32_bf16 v[110:113], v[146:149], v[186:189], v[110:113]
	v_mfma_f32_16x16x32_bf16 v[106:109], v[154:157], v[186:189], v[106:109]
	v_mfma_f32_16x16x32_bf16 v[94:97], v[146:149], v[198:201], v[94:97]
	v_mfma_f32_16x16x32_bf16 v[90:93], v[154:157], v[198:201], v[90:93]
	v_mfma_f32_16x16x32_bf16 v[78:81], v[146:149], v[212:215], v[78:81]
	v_mfma_f32_16x16x32_bf16 v[74:77], v[154:157], v[212:215], v[74:77]
	v_mfma_f32_16x16x32_bf16 v[126:129], v[150:153], v[182:185], v[126:129]
	v_mfma_f32_16x16x32_bf16 v[122:125], v[158:161], v[182:185], v[122:125]
	v_mfma_f32_16x16x32_bf16 v[110:113], v[150:153], v[190:193], v[110:113]
	v_mfma_f32_16x16x32_bf16 v[106:109], v[158:161], v[190:193], v[106:109]
	v_mfma_f32_16x16x32_bf16 v[94:97], v[150:153], v[208:211], v[94:97]
	v_mfma_f32_16x16x32_bf16 v[90:93], v[158:161], v[208:211], v[90:93]
	v_mfma_f32_16x16x32_bf16 v[78:81], v[150:153], v[216:219], v[78:81]
	v_mfma_f32_16x16x32_bf16 v[74:77], v[158:161], v[216:219], v[74:77]
	v_mfma_f32_16x16x32_bf16 v[118:121], v[162:165], v[178:181], v[118:121]
	v_mfma_f32_16x16x32_bf16 v[114:117], v[170:173], v[178:181], v[114:117]
	v_mfma_f32_16x16x32_bf16 v[102:105], v[162:165], v[186:189], v[102:105]
	v_mfma_f32_16x16x32_bf16 v[98:101], v[170:173], v[186:189], v[98:101]
	v_mfma_f32_16x16x32_bf16 v[86:89], v[162:165], v[198:201], v[86:89]
	v_mfma_f32_16x16x32_bf16 v[82:85], v[170:173], v[198:201], v[82:85]
	v_mfma_f32_16x16x32_bf16 v[70:73], v[162:165], v[212:215], v[70:73]
	v_mfma_f32_16x16x32_bf16 v[66:69], v[170:173], v[212:215], v[66:69]
	v_mfma_f32_16x16x32_bf16 v[118:121], v[166:169], v[182:185], v[118:121]
	v_mfma_f32_16x16x32_bf16 v[114:117], v[174:177], v[182:185], v[114:117]
	v_mfma_f32_16x16x32_bf16 v[102:105], v[166:169], v[190:193], v[102:105]
	v_mfma_f32_16x16x32_bf16 v[98:101], v[174:177], v[190:193], v[98:101]
	v_mfma_f32_16x16x32_bf16 v[86:89], v[166:169], v[208:211], v[86:89]
	v_mfma_f32_16x16x32_bf16 v[82:85], v[174:177], v[208:211], v[82:85]
	v_mfma_f32_16x16x32_bf16 v[70:73], v[166:169], v[216:219], v[70:73]
	v_mfma_f32_16x16x32_bf16 v[66:69], v[174:177], v[216:219], v[66:69]
	s_barrier
	s_add_i32 s79, s79, s16
	v_lshl_add_u64 v[140:141], s[36:37], 0, v[0:1]
	s_mov_b32 m0, s79
	ds_read_b128 v[178:181], v145 offset:16384
	ds_read_b128 v[182:185], v145 offset:17408
	ds_read_b128 v[186:189], v145 offset:18432
	ds_read_b128 v[190:193], v145 offset:19456
	ds_read_b128 v[198:201], v145 offset:20480
	ds_read_b128 v[208:211], v145 offset:21504
	ds_read_b128 v[212:215], v145 offset:22528
	ds_read_b128 v[216:219], v145 offset:23552
	global_load_lds_dwordx4 v[140:141], off
	s_add_i32 m0, s79, 0x2000
	s_add_u32 s80, s36, 0x20000
	v_lshl_add_u64 v[194:195], s[36:37], 0, v[130:131]
	s_addc_u32 s81, s37, 0
	s_add_i32 s79, s82, s16
	global_load_lds_dwordx4 v[194:195], off
	v_lshl_add_u64 v[204:205], s[80:81], 0, v[0:1]
	s_mov_b32 m0, s79
	v_lshl_add_u64 v[206:207], s[38:39], 0, v[132:133]
	global_load_lds_dwordx4 v[204:205], off
	v_lshl_add_u64 v[204:205], s[80:81], 0, v[130:131]
	s_add_i32 m0, s79, 0x2000
	s_nop 0
	global_load_lds_dwordx4 v[204:205], off
	v_lshl_add_u64 v[204:205], s[38:39], 0, v[134:135]
	s_mov_b32 m0, s17
	s_nop 0
	global_load_lds_dwordx4 v[204:205], off
	s_mov_b32 m0, s25
	s_nop 0
	global_load_lds_dwordx4 v[206:207], off
	s_waitcnt vmcnt(8)
	s_waitcnt lgkmcnt(0)
	s_barrier
; #define PG8_STAGE(bufoff, gbase, voff) do { _Pragma("unroll") for (int _i = 0; _i < 2; ++_i) \
;         __builtin_amdgcn_global_load_lds((const unsigned*)((const char*)(gbase) + (voff)[_i]), (LAS unsigned*)(lds + (bufoff) + ldsw + _i * 8192), 16, 0, 0); } while (0)
; #define PG8_LDA(dst, b, h) do { _Pragma("unroll") for (int m = 0; m < 4; ++m) _Pragma("unroll") for (int k = 0; k < 2; ++k) dst[m][k] = *(const LAS bf16x8*)(lds + PG8_SA(b, h) + aoff + m * 2048 + k * 1024); } while (0)
; #define PG8_LDB(dst, b, h) do { _Pragma("unroll") for (int n = 0; n < 2; ++n) _Pragma("unroll") for (int k = 0; k < 2; ++k) dst[n][k] = *(const LAS bf16x8*)(lds + PG8_SB(b, h) + boff + n * 2048 + k * 1024); } while (0)
; #define PG8_MMA(ai, bj, At, Bt) do { __builtin_amdgcn_s_setprio(1); _Pragma("unroll") for (int m = 0; m < 4; ++m) _Pragma("unroll") for (int n = 0; n < 2; ++n) _Pragma("unroll") for (int k = 0; k < 2; ++k) \
;         acc[ai][bj][m][n] = __builtin_amdgcn_mfma_f32_16x16x32_bf16(Bt[n][k], At[m][k], acc[ai][bj][m][n], 0, 0, 0); __builtin_amdgcn_s_setprio(0); } while (0)
; #define PG8_WAIT_V(n) asm volatile("s_waitcnt vmcnt(" #n ")" ::: "memory")
; #define PG8_WAIT_L(n) asm volatile("s_waitcnt lgkmcnt(" #n ")" ::: "memory")
; #define PG8_BAR __builtin_amdgcn_s_barrier()
; #define PG8_SCHED __builtin_amdgcn_sched_barrier(0)
; #define PG8_LDA(dst, b, h) do { _Pragma("unroll") for (int m = 0; m < 4; ++m) _Pragma("unroll") for (int k = 0; k < 2; ++k) dst[m][k] = *(const LAS bf16x8*)(lds + PG8_SA(b, h) + aoff + m * 2048 + k * 1024); } while (0)
; #define PG8_WAIT_V(n) asm volatile("s_waitcnt vmcnt(" #n ")" ::: "memory")
; #define PG8_WAIT_L(n) asm volatile("s_waitcnt lgkmcnt(" #n ")" ::: "memory")
; template <class Epi, class Sched>
; DI void gemm_phase(LAS unsigned char* lds, const Gemm g, const Sched& S, const Epi& E) {
;     ...
;             PG8_WAIT_V(8); PG8_WAIT_L(0); PG8_BAR; PG8_MMA(1, 0, At, B0); PG8_MMA(1, 1, At, B1); PG8_BAR; PG8_SCHED;
;             PG8_LDB(B0, 1, 0); PG8_LDB(B1, 1, 1); PG8_SCHED; PG8_LDA(At, 1, 0); PG8_STAGE(PG8_SA(0, 1), a2 + hstepA, voffA);
;             PG8_WAIT_V(8); PG8_WAIT_L(0); PG8_BAR; PG8_MMA(0, 0, At, B0); PG8_MMA(0, 1, At, B1); PG8_BAR; PG8_SCHED;
;             PG8_LDA(At, 1, 1); PG8_STAGE(PG8_SB(1, 0), b3, voffB); PG8_STAGE(PG8_SB(1, 1), b3 + hstepB, voffB); PG8_STAGE(PG8_SA(1, 0), a3, voffA);
	s_waitcnt lgkmcnt(0)
	v_mfma_f32_16x16x32_bf16 v[62:65], v[146:149], v[178:181], v[62:65]
	v_mfma_f32_16x16x32_bf16 v[58:61], v[154:157], v[178:181], v[58:61]
	v_mfma_f32_16x16x32_bf16 v[46:49], v[146:149], v[186:189], v[46:49]
	v_mfma_f32_16x16x32_bf16 v[42:45], v[154:157], v[186:189], v[42:45]
	v_mfma_f32_16x16x32_bf16 v[30:33], v[146:149], v[198:201], v[30:33]
	v_mfma_f32_16x16x32_bf16 v[26:29], v[154:157], v[198:201], v[26:29]
	v_mfma_f32_16x16x32_bf16 v[14:17], v[146:149], v[212:215], v[14:17]
	v_mfma_f32_16x16x32_bf16 v[10:13], v[154:157], v[212:215], v[10:13]
	v_mfma_f32_16x16x32_bf16 v[62:65], v[150:153], v[182:185], v[62:65]
	v_mfma_f32_16x16x32_bf16 v[58:61], v[158:161], v[182:185], v[58:61]
	v_mfma_f32_16x16x32_bf16 v[46:49], v[150:153], v[190:193], v[46:49]
	v_mfma_f32_16x16x32_bf16 v[42:45], v[158:161], v[190:193], v[42:45]
	v_mfma_f32_16x16x32_bf16 v[30:33], v[150:153], v[208:211], v[30:33]
	v_mfma_f32_16x16x32_bf16 v[26:29], v[158:161], v[208:211], v[26:29]
	v_mfma_f32_16x16x32_bf16 v[14:17], v[150:153], v[216:219], v[14:17]
	v_mfma_f32_16x16x32_bf16 v[10:13], v[158:161], v[216:219], v[10:13]
	v_mfma_f32_16x16x32_bf16 v[54:57], v[162:165], v[178:181], v[54:57]
	v_mfma_f32_16x16x32_bf16 v[50:53], v[170:173], v[178:181], v[50:53]
	v_mfma_f32_16x16x32_bf16 v[38:41], v[162:165], v[186:189], v[38:41]
	v_mfma_f32_16x16x32_bf16 v[34:37], v[170:173], v[186:189], v[34:37]
	v_mfma_f32_16x16x32_bf16 v[22:25], v[162:165], v[198:201], v[22:25]
	v_mfma_f32_16x16x32_bf16 v[18:21], v[170:173], v[198:201], v[18:21]
	v_mfma_f32_16x16x32_bf16 v[6:9], v[162:165], v[212:215], v[6:9]
	v_mfma_f32_16x16x32_bf16 v[2:5], v[170:173], v[212:215], v[2:5]
	v_mfma_f32_16x16x32_bf16 v[54:57], v[166:169], v[182:185], v[54:57]
	v_mfma_f32_16x16x32_bf16 v[50:53], v[174:177], v[182:185], v[50:53]
	v_mfma_f32_16x16x32_bf16 v[38:41], v[166:169], v[190:193], v[38:41]
	v_mfma_f32_16x16x32_bf16 v[34:37], v[174:177], v[190:193], v[34:37]
	v_mfma_f32_16x16x32_bf16 v[22:25], v[166:169], v[208:211], v[22:25]
	v_mfma_f32_16x16x32_bf16 v[18:21], v[174:177], v[208:211], v[18:21]
	v_mfma_f32_16x16x32_bf16 v[6:9], v[166:169], v[216:219], v[6:9]
	v_mfma_f32_16x16x32_bf16 v[2:5], v[174:177], v[216:219], v[2:5]
	s_barrier
	s_add_i32 s79, 0, 0x18000
	s_add_i32 s80, 0, 0x1c000
	v_add_u32_e32 v158, s79, v143
	v_add_u32_e32 v174, s80, v143
	ds_read_b128 v[146:149], v158
	ds_read_b128 v[150:153], v158 offset:1024
	ds_read_b128 v[154:157], v158 offset:2048
	ds_read_b128 v[158:161], v158 offset:3072
	ds_read_b128 v[162:165], v174
	ds_read_b128 v[166:169], v174 offset:1024
	ds_read_b128 v[170:173], v174 offset:2048
	ds_read_b128 v[174:177], v174 offset:3072
	s_add_u32 s38, s38, 0x20000
	s_addc_u32 s39, s39, 0
	s_mov_b32 m0, s28
	v_lshl_add_u64 v[220:221], s[38:39], 0, v[134:135]
	ds_read_b128 v[178:181], v145 offset:32768
	ds_read_b128 v[182:185], v145 offset:33792
	ds_read_b128 v[186:189], v145 offset:34816
	ds_read_b128 v[190:193], v145 offset:35840
	ds_read_b128 v[198:201], v145 offset:36864
	ds_read_b128 v[208:211], v145 offset:37888
	ds_read_b128 v[212:215], v145 offset:38912
	ds_read_b128 v[216:219], v145 offset:39936
	global_load_lds_dwordx4 v[220:221], off
	v_lshl_add_u64 v[220:221], s[38:39], 0, v[132:133]
	s_mov_b32 m0, s40
	s_nop 0
	global_load_lds_dwordx4 v[220:221], off
	s_waitcnt vmcnt(8)
	s_waitcnt lgkmcnt(0)
	s_barrier
	s_waitcnt lgkmcnt(0)
	v_mfma_f32_16x16x32_bf16 v[126:129], v[146:149], v[178:181], v[126:129]
	v_mfma_f32_16x16x32_bf16 v[122:125], v[154:157], v[178:181], v[122:125]
	v_mfma_f32_16x16x32_bf16 v[110:113], v[146:149], v[186:189], v[110:113]
	v_mfma_f32_16x16x32_bf16 v[106:109], v[154:157], v[186:189], v[106:109]
	v_mfma_f32_16x16x32_bf16 v[94:97], v[146:149], v[198:201], v[94:97]
	v_mfma_f32_16x16x32_bf16 v[90:93], v[154:157], v[198:201], v[90:93]
	v_mfma_f32_16x16x32_bf16 v[78:81], v[146:149], v[212:215], v[78:81]
	v_mfma_f32_16x16x32_bf16 v[74:77], v[154:157], v[212:215], v[74:77]
	v_mfma_f32_16x16x32_bf16 v[126:129], v[150:153], v[182:185], v[126:129]
	v_mfma_f32_16x16x32_bf16 v[122:125], v[158:161], v[182:185], v[122:125]
	v_mfma_f32_16x16x32_bf16 v[110:113], v[150:153], v[190:193], v[110:113]
	v_mfma_f32_16x16x32_bf16 v[106:109], v[158:161], v[190:193], v[106:109]
	v_mfma_f32_16x16x32_bf16 v[94:97], v[150:153], v[208:211], v[94:97]
	v_mfma_f32_16x16x32_bf16 v[90:93], v[158:161], v[208:211], v[90:93]
	v_mfma_f32_16x16x32_bf16 v[78:81], v[150:153], v[216:219], v[78:81]
	v_mfma_f32_16x16x32_bf16 v[74:77], v[158:161], v[216:219], v[74:77]
	v_mfma_f32_16x16x32_bf16 v[118:121], v[162:165], v[178:181], v[118:121]
	v_mfma_f32_16x16x32_bf16 v[114:117], v[170:173], v[178:181], v[114:117]
	v_mfma_f32_16x16x32_bf16 v[102:105], v[162:165], v[186:189], v[102:105]
	v_mfma_f32_16x16x32_bf16 v[98:101], v[170:173], v[186:189], v[98:101]
	v_mfma_f32_16x16x32_bf16 v[86:89], v[162:165], v[198:201], v[86:89]
	v_mfma_f32_16x16x32_bf16 v[82:85], v[170:173], v[198:201], v[82:85]
	v_mfma_f32_16x16x32_bf16 v[70:73], v[162:165], v[212:215], v[70:73]
	v_mfma_f32_16x16x32_bf16 v[66:69], v[170:173], v[212:215], v[66:69]
	v_mfma_f32_16x16x32_bf16 v[118:121], v[166:169], v[182:185], v[118:121]
	v_mfma_f32_16x16x32_bf16 v[114:117], v[174:177], v[182:185], v[114:117]
	v_mfma_f32_16x16x32_bf16 v[102:105], v[166:169], v[190:193], v[102:105]
	v_mfma_f32_16x16x32_bf16 v[98:101], v[174:177], v[190:193], v[98:101]
	v_mfma_f32_16x16x32_bf16 v[86:89], v[166:169], v[208:211], v[86:89]
	v_mfma_f32_16x16x32_bf16 v[82:85], v[174:177], v[208:211], v[82:85]
	v_mfma_f32_16x16x32_bf16 v[70:73], v[166:169], v[216:219], v[70:73]
	v_mfma_f32_16x16x32_bf16 v[66:69], v[174:177], v[216:219], v[66:69]
	s_barrier
; #define PG8_STAGE(bufoff, gbase, voff) do { _Pragma("unroll") for (int _i = 0; _i < 2; ++_i) \
;         __builtin_amdgcn_global_load_lds((const unsigned*)((const char*)(gbase) + (voff)[_i]), (LAS unsigned*)(lds + (bufoff) + ldsw + _i * 8192), 16, 0, 0); } while (0)
; #define PG8_LDA(dst, b, h) do { _Pragma("unroll") for (int m = 0; m < 4; ++m) _Pragma("unroll") for (int k = 0; k < 2; ++k) dst[m][k] = *(const LAS bf16x8*)(lds + PG8_SA(b, h) + aoff + m * 2048 + k * 1024); } while (0)
; #define PG8_MMA(ai, bj, At, Bt) do { __builtin_amdgcn_s_setprio(1); _Pragma("unroll") for (int m = 0; m < 4; ++m) _Pragma("unroll") for (int n = 0; n < 2; ++n) _Pragma("unroll") for (int k = 0; k < 2; ++k) \
;         acc[ai][bj][m][n] = __builtin_amdgcn_mfma_f32_16x16x32_bf16(Bt[n][k], At[m][k], acc[ai][bj][m][n], 0, 0, 0); __builtin_amdgcn_s_setprio(0); } while (0)
; #define PG8_WAIT_V(n) asm volatile("s_waitcnt vmcnt(" #n ")" ::: "memory")
; #define PG8_WAIT_L(n) asm volatile("s_waitcnt lgkmcnt(" #n ")" ::: "memory")
; #define PG8_BAR __builtin_amdgcn_s_barrier()
; #define PG8_SCHED __builtin_amdgcn_sched_barrier(0)
; #define PG8_LDA(dst, b, h) do { _Pragma("unroll") for (int m = 0; m < 4; ++m) _Pragma("unroll") for (int k = 0; k < 2; ++k) dst[m][k] = *(const LAS bf16x8*)(lds + PG8_SA(b, h) + aoff + m * 2048 + k * 1024); } while (0)
; #define PG8_MMA(ai, bj, At, Bt) do { __builtin_amdgcn_s_setprio(1); _Pragma("unroll") for (int m = 0; m < 4; ++m) _Pragma("unroll") for (int n = 0; n < 2; ++n) _Pragma("unroll") for (int k = 0; k < 2; ++k) \
;         acc[ai][bj][m][n] = __builtin_amdgcn_mfma_f32_16x16x32_bf16(Bt[n][k], At[m][k], acc[ai][bj][m][n], 0, 0, 0); __builtin_amdgcn_s_setprio(0); } while (0)
; #define PG8_WAIT_V(n) asm volatile("s_waitcnt vmcnt(" #n ")" ::: "memory")
; #define PG8_WAIT_L(n) asm volatile("s_waitcnt lgkmcnt(" #n ")" ::: "memory")
; #define PG8_BAR __builtin_amdgcn_s_barrier()
; #define PG8_SCHED __builtin_amdgcn_sched_barrier(0)
; template <class Epi, class Sched>
; DI void gemm_phase(LAS unsigned char* lds, const Gemm g, const Sched& S, const Epi& E) {
;     ...
;             PG8_LDA(At, 1, 1); PG8_STAGE(PG8_SB(1, 0), b3, voffB); PG8_STAGE(PG8_SB(1, 1), b3 + hstepB, voffB); PG8_STAGE(PG8_SA(1, 0), a3, voffA);
;             PG8_WAIT_V(8); PG8_WAIT_L(0); PG8_BAR; PG8_MMA(1, 0, At, B0); PG8_MMA(1, 1, At, B1); PG8_BAR; PG8_SCHED;
;         }
	s_add_i32 s38, s79, s16
	v_lshl_add_u64 v[140:141], v[140:141], 0, s[26:27]
	s_mov_b32 m0, s38
	ds_read_b128 v[178:181], v145 offset:49152
	ds_read_b128 v[182:185], v145 offset:50176
	ds_read_b128 v[186:189], v145 offset:51200
	ds_read_b128 v[190:193], v145 offset:52224
	ds_read_b128 v[198:201], v145 offset:53248
	ds_read_b128 v[208:211], v145 offset:54272
	ds_read_b128 v[212:215], v145 offset:55296
	ds_read_b128 v[216:219], v145 offset:56320
	global_load_lds_dwordx4 v[140:141], off
	s_add_i32 m0, s38, 0x2000
	s_add_u32 s36, s36, 0x20080
	v_lshl_add_u64 v[140:141], v[194:195], 0, s[26:27]
	s_addc_u32 s37, s37, 0
	s_add_i32 s38, s80, s16
	global_load_lds_dwordx4 v[140:141], off
	v_lshl_add_u64 v[140:141], s[36:37], 0, v[0:1]
	s_mov_b32 m0, s38
	s_nop 0
	global_load_lds_dwordx4 v[140:141], off
	v_lshl_add_u64 v[140:141], s[36:37], 0, v[130:131]
	s_add_i32 m0, s38, 0x2000
	s_nop 0
	global_load_lds_dwordx4 v[140:141], off
	v_lshl_add_u64 v[140:141], v[204:205], 0, s[26:27]
	s_mov_b32 m0, s41
	s_nop 0
	global_load_lds_dwordx4 v[140:141], off
	v_lshl_add_u64 v[140:141], v[206:207], 0, s[26:27]
	s_mov_b32 m0, s44
	s_nop 0
	global_load_lds_dwordx4 v[140:141], off
	s_waitcnt vmcnt(8)
	s_waitcnt lgkmcnt(0)
	s_barrier
	s_waitcnt lgkmcnt(0)
	v_mfma_f32_16x16x32_bf16 v[62:65], v[146:149], v[178:181], v[62:65]
	v_mfma_f32_16x16x32_bf16 v[58:61], v[154:157], v[178:181], v[58:61]
	v_mfma_f32_16x16x32_bf16 v[46:49], v[146:149], v[186:189], v[46:49]
	v_mfma_f32_16x16x32_bf16 v[42:45], v[154:157], v[186:189], v[42:45]
	v_mfma_f32_16x16x32_bf16 v[30:33], v[146:149], v[198:201], v[30:33]
	v_mfma_f32_16x16x32_bf16 v[26:29], v[154:157], v[198:201], v[26:29]
	v_mfma_f32_16x16x32_bf16 v[14:17], v[146:149], v[212:215], v[14:17]
	v_mfma_f32_16x16x32_bf16 v[10:13], v[154:157], v[212:215], v[10:13]
	v_mfma_f32_16x16x32_bf16 v[62:65], v[150:153], v[182:185], v[62:65]
	v_mfma_f32_16x16x32_bf16 v[58:61], v[158:161], v[182:185], v[58:61]
	v_mfma_f32_16x16x32_bf16 v[46:49], v[150:153], v[190:193], v[46:49]
	v_mfma_f32_16x16x32_bf16 v[42:45], v[158:161], v[190:193], v[42:45]
	v_mfma_f32_16x16x32_bf16 v[30:33], v[150:153], v[208:211], v[30:33]
	v_mfma_f32_16x16x32_bf16 v[26:29], v[158:161], v[208:211], v[26:29]
	v_mfma_f32_16x16x32_bf16 v[14:17], v[150:153], v[216:219], v[14:17]
	v_mfma_f32_16x16x32_bf16 v[10:13], v[158:161], v[216:219], v[10:13]
	v_mfma_f32_16x16x32_bf16 v[54:57], v[162:165], v[178:181], v[54:57]
	v_mfma_f32_16x16x32_bf16 v[50:53], v[170:173], v[178:181], v[50:53]
	v_mfma_f32_16x16x32_bf16 v[38:41], v[162:165], v[186:189], v[38:41]
	v_mfma_f32_16x16x32_bf16 v[34:37], v[170:173], v[186:189], v[34:37]
	v_mfma_f32_16x16x32_bf16 v[22:25], v[162:165], v[198:201], v[22:25]
	v_mfma_f32_16x16x32_bf16 v[18:21], v[170:173], v[198:201], v[18:21]
	v_mfma_f32_16x16x32_bf16 v[6:9], v[162:165], v[212:215], v[6:9]
	v_mfma_f32_16x16x32_bf16 v[2:5], v[170:173], v[212:215], v[2:5]
	v_mfma_f32_16x16x32_bf16 v[54:57], v[166:169], v[182:185], v[54:57]
	v_mfma_f32_16x16x32_bf16 v[50:53], v[174:177], v[182:185], v[50:53]
	v_mfma_f32_16x16x32_bf16 v[38:41], v[166:169], v[190:193], v[38:41]
	v_mfma_f32_16x16x32_bf16 v[34:37], v[174:177], v[190:193], v[34:37]
	v_mfma_f32_16x16x32_bf16 v[22:25], v[166:169], v[208:211], v[22:25]
	v_mfma_f32_16x16x32_bf16 v[18:21], v[174:177], v[208:211], v[18:21]
	v_mfma_f32_16x16x32_bf16 v[6:9], v[166:169], v[216:219], v[6:9]
	v_mfma_f32_16x16x32_bf16 v[2:5], v[174:177], v[216:219], v[2:5]
	s_barrier
	s_add_i32 s78, s78, 2
	s_add_u32 s30, s30, 0x100
	s_addc_u32 s31, s31, 0
	s_add_u32 s76, s76, 0x100
	s_addc_u32 s77, s77, 0
	s_cmp_gt_u32 s78, 5
	s_cbranch_scc0 .LBB0_643
	s_and_b64 vcc, exec, s[64:65]
	s_cbranch_vccz .LBB0_646
	s_barrier

; #define PG8_LDA(dst, b, h) do { _Pragma("unroll") for (int m = 0; m < 4; ++m) _Pragma("unroll") for (int k = 0; k < 2; ++k) dst[m][k] = *(const LAS bf16x8*)(lds + PG8_SA(b, h) + aoff + m * 2048 + k * 1024); } while (0)
; #define PG8_LDB(dst, b, h) do { _Pragma("unroll") for (int n = 0; n < 2; ++n) _Pragma("unroll") for (int k = 0; k < 2; ++k) dst[n][k] = *(const LAS bf16x8*)(lds + PG8_SB(b, h) + boff + n * 2048 + k * 1024); } while (0)
; #define PG8_MMA(ai, bj, At, Bt) do { __builtin_amdgcn_s_setprio(1); _Pragma("unroll") for (int m = 0; m < 4; ++m) _Pragma("unroll") for (int n = 0; n < 2; ++n) _Pragma("unroll") for (int k = 0; k < 2; ++k) \
;         acc[ai][bj][m][n] = __builtin_amdgcn_mfma_f32_16x16x32_bf16(Bt[n][k], At[m][k], acc[ai][bj][m][n], 0, 0, 0); __builtin_amdgcn_s_setprio(0); } while (0)
; #define PG8_WAIT_V(n) asm volatile("s_waitcnt vmcnt(" #n ")" ::: "memory")
; #define PG8_WAIT_L(n) asm volatile("s_waitcnt lgkmcnt(" #n ")" ::: "memory")
; #define PG8_BAR __builtin_amdgcn_s_barrier()
; #define PG8_SCHED __builtin_amdgcn_sched_barrier(0)
; #define GM_STAGE(bufoff, gbase, R2, ld_) do { _Pragma("unroll") for (int _i = 0; _i < 2; ++_i) \
;         __builtin_amdgcn_global_load_lds((const unsigned*)((const char*)(gbase) + (size_t)_i * 128 * (size_t)(ld_) + ((R2) * (unsigned)(ld_) + C2)), (LAS unsigned*)(lds + (bufoff) + ldsw + _i * 8192), 16, 0, 0); } while (0)
; #define PG8_LDA(dst, b, h) do { _Pragma("unroll") for (int m = 0; m < 4; ++m) _Pragma("unroll") for (int k = 0; k < 2; ++k) dst[m][k] = *(const LAS bf16x8*)(lds + PG8_SA(b, h) + aoff + m * 2048 + k * 1024); } while (0)
; #define PG8_LDB(dst, b, h) do { _Pragma("unroll") for (int n = 0; n < 2; ++n) _Pragma("unroll") for (int k = 0; k < 2; ++k) dst[n][k] = *(const LAS bf16x8*)(lds + PG8_SB(b, h) + boff + n * 2048 + k * 1024); } while (0)
; #define PG8_WAIT_V(n) asm volatile("s_waitcnt vmcnt(" #n ")" ::: "memory")
; DI void gemm_phase_gm(LAS unsigned char* lds, const GmArgs ga, const SchedGM& S) {
;     ...
;             PG8_LDB(B0, 0, 0); PG8_LDB(B1, 0, 1); PG8_SCHED; PG8_LDA(At, 0, 0); GM_STAGE(PG8_SA(1, 1), a1 + hsc, RA2, ldc_);
;             PG8_WAIT_V(8); PG8_WAIT_L(0); PG8_BAR; PG8_MMA(0, 0, At, B0); PG8_MMA(0, 1, At, B1); PG8_BAR; PG8_SCHED;
;             PG8_LDA(At, 0, 1); GM_STAGE(PG8_SB(0, 0), b2, RB2, ld2); GM_STAGE(PG8_SB(0, 1), b2 + hs2, RB2, ld2); GM_STAGE(PG8_SA(0, 0), a2, RA2, ld2);
.LBB0_842:
	s_add_u32 s13, s64, s30
	s_addc_u32 s14, s65, s31
	s_add_u32 s15, s62, s30
	s_addc_u32 s16, s63, s31
	s_add_i32 s17, 0, 0x10000
	s_add_i32 s75, 0, 0x14000
	v_add_u32_e32 v146, s17, v245
	v_add_u32_e32 v162, s75, v245
	ds_read_b128 v[134:137], v146
	ds_read_b128 v[138:141], v146 offset:1024
	ds_read_b128 v[142:145], v146 offset:2048
	ds_read_b128 v[146:149], v146 offset:3072
	ds_read_b128 v[150:153], v162
	ds_read_b128 v[154:157], v162 offset:1024
	ds_read_b128 v[158:161], v162 offset:2048
	ds_read_b128 v[162:165], v162 offset:3072
	s_add_i32 m0, s53, 0xc000
	s_add_i32 s28, s53, 0xe000
	s_cmp_eq_u32 s93, s12
	s_cselect_b32 s39, s81, s16
	s_cselect_b32 s38, s80, s15
	s_cselect_b32 s37, s69, s14
	s_cselect_b32 s36, s68, s13
	s_cselect_b32 s13, s89, s77
	s_cselect_b32 s83, s88, s76
	v_lshl_add_u64 v[194:195], s[64:65], 0, v[130:131]
	ds_read_b128 v[166:169], v208
	ds_read_b128 v[170:173], v208 offset:1024
	ds_read_b128 v[174:177], v208 offset:2048
	ds_read_b128 v[178:181], v208 offset:3072
	ds_read_b128 v[182:185], v208 offset:4096
	ds_read_b128 v[186:189], v208 offset:5120
	ds_read_b128 v[190:193], v208 offset:6144
	ds_read_b128 v[204:207], v208 offset:7168
	global_load_lds_dwordx4 v[194:195], off
	v_lshl_add_u64 v[194:195], s[64:65], 0, v[132:133]
	s_mov_b32 m0, s28
	s_nop 0
	global_load_lds_dwordx4 v[194:195], off
	s_waitcnt vmcnt(8)
	s_waitcnt lgkmcnt(0)
	s_barrier
	s_waitcnt lgkmcnt(0)
	v_mfma_f32_16x16x32_bf16 v[126:129], v[134:137], v[166:169], v[126:129]
	v_mfma_f32_16x16x32_bf16 v[122:125], v[142:145], v[166:169], v[122:125]
	v_mfma_f32_16x16x32_bf16 v[118:121], v[134:137], v[174:177], v[118:121]
	v_mfma_f32_16x16x32_bf16 v[114:117], v[142:145], v[174:177], v[114:117]
	v_mfma_f32_16x16x32_bf16 v[110:113], v[134:137], v[182:185], v[110:113]
	v_mfma_f32_16x16x32_bf16 v[106:109], v[142:145], v[182:185], v[106:109]
	v_mfma_f32_16x16x32_bf16 v[102:105], v[134:137], v[190:193], v[102:105]
	v_mfma_f32_16x16x32_bf16 v[98:101], v[142:145], v[190:193], v[98:101]
	v_mfma_f32_16x16x32_bf16 v[126:129], v[138:141], v[170:173], v[126:129]
	v_mfma_f32_16x16x32_bf16 v[122:125], v[146:149], v[170:173], v[122:125]
	v_mfma_f32_16x16x32_bf16 v[118:121], v[138:141], v[178:181], v[118:121]
	v_mfma_f32_16x16x32_bf16 v[114:117], v[146:149], v[178:181], v[114:117]
	v_mfma_f32_16x16x32_bf16 v[110:113], v[138:141], v[186:189], v[110:113]
	v_mfma_f32_16x16x32_bf16 v[106:109], v[146:149], v[186:189], v[106:109]
	v_mfma_f32_16x16x32_bf16 v[102:105], v[138:141], v[204:207], v[102:105]
	v_mfma_f32_16x16x32_bf16 v[98:101], v[146:149], v[204:207], v[98:101]
	v_mfma_f32_16x16x32_bf16 v[94:97], v[150:153], v[166:169], v[94:97]
	v_mfma_f32_16x16x32_bf16 v[90:93], v[158:161], v[166:169], v[90:93]
	v_mfma_f32_16x16x32_bf16 v[86:89], v[150:153], v[174:177], v[86:89]
	v_mfma_f32_16x16x32_bf16 v[82:85], v[158:161], v[174:177], v[82:85]
	v_mfma_f32_16x16x32_bf16 v[78:81], v[150:153], v[182:185], v[78:81]
	v_mfma_f32_16x16x32_bf16 v[74:77], v[158:161], v[182:185], v[74:77]
	v_mfma_f32_16x16x32_bf16 v[70:73], v[150:153], v[190:193], v[70:73]
	v_mfma_f32_16x16x32_bf16 v[66:69], v[158:161], v[190:193], v[66:69]
	v_mfma_f32_16x16x32_bf16 v[94:97], v[154:157], v[170:173], v[94:97]
	v_mfma_f32_16x16x32_bf16 v[90:93], v[162:165], v[170:173], v[90:93]
	v_mfma_f32_16x16x32_bf16 v[86:89], v[154:157], v[178:181], v[86:89]
	v_mfma_f32_16x16x32_bf16 v[82:85], v[162:165], v[178:181], v[82:85]
	v_mfma_f32_16x16x32_bf16 v[78:81], v[154:157], v[186:189], v[78:81]
	v_mfma_f32_16x16x32_bf16 v[74:77], v[162:165], v[186:189], v[74:77]
	v_mfma_f32_16x16x32_bf16 v[70:73], v[154:157], v[204:207], v[70:73]
	v_mfma_f32_16x16x32_bf16 v[66:69], v[162:165], v[204:207], v[66:69]
	s_barrier
	s_cselect_b32 s28, s82, s74
	s_add_i32 s16, s17, s91
	v_mad_u64_u32 v[194:195], s[14:15], v250, s28, v[214:215]
	s_mov_b32 m0, s16
	ds_read_b128 v[166:169], v208 offset:16384
	ds_read_b128 v[170:173], v208 offset:17408
	ds_read_b128 v[174:177], v208 offset:18432
	ds_read_b128 v[178:181], v208 offset:19456
	ds_read_b128 v[182:185], v208 offset:20480
	ds_read_b128 v[186:189], v208 offset:21504
	ds_read_b128 v[190:193], v208 offset:22528
	ds_read_b128 v[204:207], v208 offset:23552
	v_mov_b32_e32 v195, v1
	global_load_lds_dwordx4 v194, s[38:39]
	s_lshl_b64 s[14:15], s[28:29], 7
	s_add_i32 m0, s16, 0x2000
	v_lshl_add_u64 v[232:233], s[38:39], 0, v[194:195]
	s_add_u32 s16, s38, s83
	v_lshl_add_u64 v[234:235], v[232:233], 0, s[14:15]
	s_addc_u32 s17, s39, s13
	s_add_i32 s38, s75, s91
	global_load_lds_dwordx4 v[234:235], off
	s_mov_b32 m0, s38
	v_lshl_add_u64 v[236:237], s[16:17], 0, v[194:195]
	global_load_lds_dwordx4 v194, s[16:17]
	v_mad_u64_u32 v[238:239], s[16:17], s28, v215, v[214:215]
	v_lshl_add_u64 v[194:195], v[236:237], 0, s[14:15]
	s_add_i32 m0, s38, 0x2000
	v_mov_b32_e32 v239, v1
	global_load_lds_dwordx4 v[194:195], off
	v_lshl_add_u64 v[240:241], s[36:37], 0, v[238:239]
	s_mov_b32 m0, s53
	v_lshl_add_u64 v[242:243], v[240:241], 0, s[14:15]
	global_load_lds_dwordx4 v238, s[36:37]
	s_mov_b32 m0, s94
	s_nop 0
	global_load_lds_dwordx4 v[242:243], off
	s_waitcnt vmcnt(8)
	s_waitcnt lgkmcnt(0)
	s_barrier
; #define PG8_LDA(dst, b, h) do { _Pragma("unroll") for (int m = 0; m < 4; ++m) _Pragma("unroll") for (int k = 0; k < 2; ++k) dst[m][k] = *(const LAS bf16x8*)(lds + PG8_SA(b, h) + aoff + m * 2048 + k * 1024); } while (0)
; #define PG8_LDB(dst, b, h) do { _Pragma("unroll") for (int n = 0; n < 2; ++n) _Pragma("unroll") for (int k = 0; k < 2; ++k) dst[n][k] = *(const LAS bf16x8*)(lds + PG8_SB(b, h) + boff + n * 2048 + k * 1024); } while (0)
; #define PG8_MMA(ai, bj, At, Bt) do { __builtin_amdgcn_s_setprio(1); _Pragma("unroll") for (int m = 0; m < 4; ++m) _Pragma("unroll") for (int n = 0; n < 2; ++n) _Pragma("unroll") for (int k = 0; k < 2; ++k) \
;         acc[ai][bj][m][n] = __builtin_amdgcn_mfma_f32_16x16x32_bf16(Bt[n][k], At[m][k], acc[ai][bj][m][n], 0, 0, 0); __builtin_amdgcn_s_setprio(0); } while (0)
; #define PG8_WAIT_V(n) asm volatile("s_waitcnt vmcnt(" #n ")" ::: "memory")
; #define PG8_WAIT_L(n) asm volatile("s_waitcnt lgkmcnt(" #n ")" ::: "memory")
; #define PG8_BAR __builtin_amdgcn_s_barrier()
; #define PG8_SCHED __builtin_amdgcn_sched_barrier(0)
; #define GM_STAGE(bufoff, gbase, R2, ld_) do { _Pragma("unroll") for (int _i = 0; _i < 2; ++_i) \
;         __builtin_amdgcn_global_load_lds((const unsigned*)((const char*)(gbase) + (size_t)_i * 128 * (size_t)(ld_) + ((R2) * (unsigned)(ld_) + C2)), (LAS unsigned*)(lds + (bufoff) + ldsw + _i * 8192), 16, 0, 0); } while (0)
; #define PG8_LDA(dst, b, h) do { _Pragma("unroll") for (int m = 0; m < 4; ++m) _Pragma("unroll") for (int k = 0; k < 2; ++k) dst[m][k] = *(const LAS bf16x8*)(lds + PG8_SA(b, h) + aoff + m * 2048 + k * 1024); } while (0)
; #define PG8_LDB(dst, b, h) do { _Pragma("unroll") for (int n = 0; n < 2; ++n) _Pragma("unroll") for (int k = 0; k < 2; ++k) dst[n][k] = *(const LAS bf16x8*)(lds + PG8_SB(b, h) + boff + n * 2048 + k * 1024); } while (0)
; #define PG8_WAIT_V(n) asm volatile("s_waitcnt vmcnt(" #n ")" ::: "memory")
; DI void gemm_phase_gm(LAS unsigned char* lds, const GmArgs ga, const SchedGM& S) {
;     ...
;             PG8_WAIT_V(8); PG8_WAIT_L(0); PG8_BAR; PG8_MMA(1, 0, At, B0); PG8_MMA(1, 1, At, B1); PG8_BAR; PG8_SCHED;
;             PG8_LDB(B0, 1, 0); PG8_LDB(B1, 1, 1); PG8_SCHED; PG8_LDA(At, 1, 0); GM_STAGE(PG8_SA(0, 1), a2 + hs2, RA2, ld2);
;             PG8_WAIT_V(8); PG8_WAIT_L(0); PG8_BAR; PG8_MMA(0, 0, At, B0); PG8_MMA(0, 1, At, B1); PG8_BAR; PG8_SCHED;
	s_waitcnt lgkmcnt(0)
	v_mfma_f32_16x16x32_bf16 v[62:65], v[134:137], v[166:169], v[62:65]
	v_mfma_f32_16x16x32_bf16 v[58:61], v[142:145], v[166:169], v[58:61]
	v_mfma_f32_16x16x32_bf16 v[54:57], v[134:137], v[174:177], v[54:57]
	v_mfma_f32_16x16x32_bf16 v[50:53], v[142:145], v[174:177], v[50:53]
	v_mfma_f32_16x16x32_bf16 v[46:49], v[134:137], v[182:185], v[46:49]
	v_mfma_f32_16x16x32_bf16 v[42:45], v[142:145], v[182:185], v[42:45]
	v_mfma_f32_16x16x32_bf16 v[38:41], v[134:137], v[190:193], v[38:41]
	v_mfma_f32_16x16x32_bf16 v[34:37], v[142:145], v[190:193], v[34:37]
	v_mfma_f32_16x16x32_bf16 v[62:65], v[138:141], v[170:173], v[62:65]
	v_mfma_f32_16x16x32_bf16 v[58:61], v[146:149], v[170:173], v[58:61]
	v_mfma_f32_16x16x32_bf16 v[54:57], v[138:141], v[178:181], v[54:57]
	v_mfma_f32_16x16x32_bf16 v[50:53], v[146:149], v[178:181], v[50:53]
	v_mfma_f32_16x16x32_bf16 v[46:49], v[138:141], v[186:189], v[46:49]
	v_mfma_f32_16x16x32_bf16 v[42:45], v[146:149], v[186:189], v[42:45]
	v_mfma_f32_16x16x32_bf16 v[38:41], v[138:141], v[204:207], v[38:41]
	v_mfma_f32_16x16x32_bf16 v[34:37], v[146:149], v[204:207], v[34:37]
	v_mfma_f32_16x16x32_bf16 v[30:33], v[150:153], v[166:169], v[30:33]
	v_mfma_f32_16x16x32_bf16 v[26:29], v[158:161], v[166:169], v[26:29]
	v_mfma_f32_16x16x32_bf16 v[22:25], v[150:153], v[174:177], v[22:25]
	v_mfma_f32_16x16x32_bf16 v[18:21], v[158:161], v[174:177], v[18:21]
	v_mfma_f32_16x16x32_bf16 v[14:17], v[150:153], v[182:185], v[14:17]
	v_mfma_f32_16x16x32_bf16 v[10:13], v[158:161], v[182:185], v[10:13]
	v_mfma_f32_16x16x32_bf16 v[6:9], v[150:153], v[190:193], v[6:9]
	v_mfma_f32_16x16x32_bf16 v[2:5], v[158:161], v[190:193], v[2:5]
	v_mfma_f32_16x16x32_bf16 v[30:33], v[154:157], v[170:173], v[30:33]
	v_mfma_f32_16x16x32_bf16 v[26:29], v[162:165], v[170:173], v[26:29]
	v_mfma_f32_16x16x32_bf16 v[22:25], v[154:157], v[178:181], v[22:25]
	v_mfma_f32_16x16x32_bf16 v[18:21], v[162:165], v[178:181], v[18:21]
	v_mfma_f32_16x16x32_bf16 v[14:17], v[154:157], v[186:189], v[14:17]
	v_mfma_f32_16x16x32_bf16 v[10:13], v[162:165], v[186:189], v[10:13]
	v_mfma_f32_16x16x32_bf16 v[6:9], v[154:157], v[204:207], v[6:9]
	v_mfma_f32_16x16x32_bf16 v[2:5], v[162:165], v[204:207], v[2:5]
	s_barrier
	s_add_i32 s28, 0, 0x18000
	s_add_i32 s38, 0, 0x1c000
	v_add_u32_e32 v146, s28, v245
	v_add_u32_e32 v162, s38, v245
	ds_read_b128 v[134:137], v146
	ds_read_b128 v[138:141], v146 offset:1024
	ds_read_b128 v[142:145], v146 offset:2048
	ds_read_b128 v[146:149], v146 offset:3072
	ds_read_b128 v[150:153], v162
	ds_read_b128 v[154:157], v162 offset:1024
	ds_read_b128 v[158:161], v162 offset:2048
	ds_read_b128 v[162:165], v162 offset:3072
	s_add_u32 s16, s36, s83
	s_addc_u32 s17, s37, s13
	s_mov_b32 m0, s95
	v_lshl_add_u64 v[202:203], s[16:17], 0, v[238:239]
	ds_read_b128 v[166:169], v208 offset:32768
	ds_read_b128 v[170:173], v208 offset:33792
	ds_read_b128 v[174:177], v208 offset:34816
	ds_read_b128 v[178:181], v208 offset:35840
	ds_read_b128 v[182:185], v208 offset:36864
	ds_read_b128 v[186:189], v208 offset:37888
	ds_read_b128 v[190:193], v208 offset:38912
	ds_read_b128 v[204:207], v208 offset:39936
	global_load_lds_dwordx4 v238, s[16:17]
	v_lshl_add_u64 v[202:203], v[202:203], 0, s[14:15]
	s_mov_b32 m0, s92
	s_nop 0
	global_load_lds_dwordx4 v[202:203], off
	s_waitcnt vmcnt(8)
	s_waitcnt lgkmcnt(0)
	s_barrier
	s_waitcnt lgkmcnt(0)
	v_mfma_f32_16x16x32_bf16 v[126:129], v[134:137], v[166:169], v[126:129]
	v_mfma_f32_16x16x32_bf16 v[122:125], v[142:145], v[166:169], v[122:125]
	v_mfma_f32_16x16x32_bf16 v[118:121], v[134:137], v[174:177], v[118:121]
	v_mfma_f32_16x16x32_bf16 v[114:117], v[142:145], v[174:177], v[114:117]
	v_mfma_f32_16x16x32_bf16 v[110:113], v[134:137], v[182:185], v[110:113]
	v_mfma_f32_16x16x32_bf16 v[106:109], v[142:145], v[182:185], v[106:109]
	v_mfma_f32_16x16x32_bf16 v[102:105], v[134:137], v[190:193], v[102:105]
	v_mfma_f32_16x16x32_bf16 v[98:101], v[142:145], v[190:193], v[98:101]
	v_mfma_f32_16x16x32_bf16 v[126:129], v[138:141], v[170:173], v[126:129]
	v_mfma_f32_16x16x32_bf16 v[122:125], v[146:149], v[170:173], v[122:125]
	v_mfma_f32_16x16x32_bf16 v[118:121], v[138:141], v[178:181], v[118:121]
	v_mfma_f32_16x16x32_bf16 v[114:117], v[146:149], v[178:181], v[114:117]
	v_mfma_f32_16x16x32_bf16 v[110:113], v[138:141], v[186:189], v[110:113]
	v_mfma_f32_16x16x32_bf16 v[106:109], v[146:149], v[186:189], v[106:109]
	v_mfma_f32_16x16x32_bf16 v[102:105], v[138:141], v[204:207], v[102:105]
	v_mfma_f32_16x16x32_bf16 v[98:101], v[146:149], v[204:207], v[98:101]
	v_mfma_f32_16x16x32_bf16 v[94:97], v[150:153], v[166:169], v[94:97]
	v_mfma_f32_16x16x32_bf16 v[90:93], v[158:161], v[166:169], v[90:93]
	v_mfma_f32_16x16x32_bf16 v[86:89], v[150:153], v[174:177], v[86:89]
	v_mfma_f32_16x16x32_bf16 v[82:85], v[158:161], v[174:177], v[82:85]
	v_mfma_f32_16x16x32_bf16 v[78:81], v[150:153], v[182:185], v[78:81]
	v_mfma_f32_16x16x32_bf16 v[74:77], v[158:161], v[182:185], v[74:77]
	v_mfma_f32_16x16x32_bf16 v[70:73], v[150:153], v[190:193], v[70:73]
	v_mfma_f32_16x16x32_bf16 v[66:69], v[158:161], v[190:193], v[66:69]
	v_mfma_f32_16x16x32_bf16 v[94:97], v[154:157], v[170:173], v[94:97]
	v_mfma_f32_16x16x32_bf16 v[90:93], v[162:165], v[170:173], v[90:93]
	v_mfma_f32_16x16x32_bf16 v[86:89], v[154:157], v[178:181], v[86:89]
	v_mfma_f32_16x16x32_bf16 v[82:85], v[162:165], v[178:181], v[82:85]
	v_mfma_f32_16x16x32_bf16 v[78:81], v[154:157], v[186:189], v[78:81]
	v_mfma_f32_16x16x32_bf16 v[74:77], v[162:165], v[186:189], v[74:77]
	v_mfma_f32_16x16x32_bf16 v[70:73], v[154:157], v[204:207], v[70:73]
	v_mfma_f32_16x16x32_bf16 v[66:69], v[162:165], v[204:207], v[66:69]
	s_barrier
; #define PG8_LDA(dst, b, h) do { _Pragma("unroll") for (int m = 0; m < 4; ++m) _Pragma("unroll") for (int k = 0; k < 2; ++k) dst[m][k] = *(const LAS bf16x8*)(lds + PG8_SA(b, h) + aoff + m * 2048 + k * 1024); } while (0)
; #define PG8_MMA(ai, bj, At, Bt) do { __builtin_amdgcn_s_setprio(1); _Pragma("unroll") for (int m = 0; m < 4; ++m) _Pragma("unroll") for (int n = 0; n < 2; ++n) _Pragma("unroll") for (int k = 0; k < 2; ++k) \
;         acc[ai][bj][m][n] = __builtin_amdgcn_mfma_f32_16x16x32_bf16(Bt[n][k], At[m][k], acc[ai][bj][m][n], 0, 0, 0); __builtin_amdgcn_s_setprio(0); } while (0)
; #define PG8_WAIT_V(n) asm volatile("s_waitcnt vmcnt(" #n ")" ::: "memory")
; #define PG8_WAIT_L(n) asm volatile("s_waitcnt lgkmcnt(" #n ")" ::: "memory")
; #define PG8_BAR __builtin_amdgcn_s_barrier()
; #define PG8_SCHED __builtin_amdgcn_sched_barrier(0)
; #define GM_STAGE(bufoff, gbase, R2, ld_) do { _Pragma("unroll") for (int _i = 0; _i < 2; ++_i) \
;         __builtin_amdgcn_global_load_lds((const unsigned*)((const char*)(gbase) + (size_t)_i * 128 * (size_t)(ld_) + ((R2) * (unsigned)(ld_) + C2)), (LAS unsigned*)(lds + (bufoff) + ldsw + _i * 8192), 16, 0, 0); } while (0)
; #define PG8_LDA(dst, b, h) do { _Pragma("unroll") for (int m = 0; m < 4; ++m) _Pragma("unroll") for (int k = 0; k < 2; ++k) dst[m][k] = *(const LAS bf16x8*)(lds + PG8_SA(b, h) + aoff + m * 2048 + k * 1024); } while (0)
; #define PG8_MMA(ai, bj, At, Bt) do { __builtin_amdgcn_s_setprio(1); _Pragma("unroll") for (int m = 0; m < 4; ++m) _Pragma("unroll") for (int n = 0; n < 2; ++n) _Pragma("unroll") for (int k = 0; k < 2; ++k) \
;         acc[ai][bj][m][n] = __builtin_amdgcn_mfma_f32_16x16x32_bf16(Bt[n][k], At[m][k], acc[ai][bj][m][n], 0, 0, 0); __builtin_amdgcn_s_setprio(0); } while (0)
; #define PG8_WAIT_V(n) asm volatile("s_waitcnt vmcnt(" #n ")" ::: "memory")
; #define PG8_WAIT_L(n) asm volatile("s_waitcnt lgkmcnt(" #n ")" ::: "memory")
; #define PG8_BAR __builtin_amdgcn_s_barrier()
; DI void gemm_phase_gm(LAS unsigned char* lds, const GmArgs ga, const SchedGM& S) {
;     ...
;             PG8_LDA(At, 1, 1); GM_STAGE(PG8_SB(1, 0), b3, RB2, ld2); GM_STAGE(PG8_SB(1, 1), b3 + hs2, RB2, ld2); GM_STAGE(PG8_SA(1, 0), a3, RA2, ld2);
;             PG8_WAIT_V(8); PG8_WAIT_L(0); PG8_BAR; PG8_MMA(1, 0, At, B0); PG8_MMA(1, 1, At, B1); PG8_BAR; PG8_SCHED;
;         }
;         if (wr == 0) PG8_BAR;
	s_add_i32 s13, s28, s91
	v_lshl_add_u64 v[202:203], v[232:233], 0, s[26:27]
	s_mov_b32 m0, s13
	ds_read_b128 v[166:169], v208 offset:49152
	ds_read_b128 v[170:173], v208 offset:50176
	ds_read_b128 v[174:177], v208 offset:51200
	ds_read_b128 v[178:181], v208 offset:52224
	ds_read_b128 v[182:185], v208 offset:53248
	ds_read_b128 v[186:189], v208 offset:54272
	ds_read_b128 v[190:193], v208 offset:55296
	ds_read_b128 v[204:207], v208 offset:56320
	global_load_lds_dwordx4 v[202:203], off
	v_lshl_add_u64 v[202:203], v[234:235], 0, s[26:27]
	s_add_i32 m0, s13, 0x2000
	s_add_i32 s13, s38, s91
	global_load_lds_dwordx4 v[202:203], off
	v_lshl_add_u64 v[202:203], v[236:237], 0, s[26:27]
	s_mov_b32 m0, s13
	v_lshl_add_u64 v[194:195], v[194:195], 0, s[26:27]
	global_load_lds_dwordx4 v[202:203], off
	s_add_i32 m0, s13, 0x2000
	s_nop 0
	global_load_lds_dwordx4 v[194:195], off
	v_lshl_add_u64 v[194:195], v[240:241], 0, s[26:27]
	s_mov_b32 m0, s50
	s_nop 0
	global_load_lds_dwordx4 v[194:195], off
	v_lshl_add_u64 v[194:195], v[242:243], 0, s[26:27]
	s_mov_b32 m0, s51
	s_nop 0
	global_load_lds_dwordx4 v[194:195], off
	s_waitcnt vmcnt(8)
	s_waitcnt lgkmcnt(0)
	s_barrier
	s_waitcnt lgkmcnt(0)
	v_mfma_f32_16x16x32_bf16 v[62:65], v[134:137], v[166:169], v[62:65]
	v_mfma_f32_16x16x32_bf16 v[58:61], v[142:145], v[166:169], v[58:61]
	v_mfma_f32_16x16x32_bf16 v[54:57], v[134:137], v[174:177], v[54:57]
	v_mfma_f32_16x16x32_bf16 v[50:53], v[142:145], v[174:177], v[50:53]
	v_mfma_f32_16x16x32_bf16 v[46:49], v[134:137], v[182:185], v[46:49]
	v_mfma_f32_16x16x32_bf16 v[42:45], v[142:145], v[182:185], v[42:45]
	v_mfma_f32_16x16x32_bf16 v[38:41], v[134:137], v[190:193], v[38:41]
	v_mfma_f32_16x16x32_bf16 v[34:37], v[142:145], v[190:193], v[34:37]
	v_mfma_f32_16x16x32_bf16 v[62:65], v[138:141], v[170:173], v[62:65]
	v_mfma_f32_16x16x32_bf16 v[58:61], v[146:149], v[170:173], v[58:61]
	v_mfma_f32_16x16x32_bf16 v[54:57], v[138:141], v[178:181], v[54:57]
	v_mfma_f32_16x16x32_bf16 v[50:53], v[146:149], v[178:181], v[50:53]
	v_mfma_f32_16x16x32_bf16 v[46:49], v[138:141], v[186:189], v[46:49]
	v_mfma_f32_16x16x32_bf16 v[42:45], v[146:149], v[186:189], v[42:45]
	v_mfma_f32_16x16x32_bf16 v[38:41], v[138:141], v[204:207], v[38:41]
	v_mfma_f32_16x16x32_bf16 v[34:37], v[146:149], v[204:207], v[34:37]
	v_mfma_f32_16x16x32_bf16 v[30:33], v[150:153], v[166:169], v[30:33]
	v_mfma_f32_16x16x32_bf16 v[26:29], v[158:161], v[166:169], v[26:29]
	v_mfma_f32_16x16x32_bf16 v[22:25], v[150:153], v[174:177], v[22:25]
	v_mfma_f32_16x16x32_bf16 v[18:21], v[158:161], v[174:177], v[18:21]
	v_mfma_f32_16x16x32_bf16 v[14:17], v[150:153], v[182:185], v[14:17]
	v_mfma_f32_16x16x32_bf16 v[10:13], v[158:161], v[182:185], v[10:13]
	v_mfma_f32_16x16x32_bf16 v[6:9], v[150:153], v[190:193], v[6:9]
	v_mfma_f32_16x16x32_bf16 v[2:5], v[158:161], v[190:193], v[2:5]
	v_mfma_f32_16x16x32_bf16 v[30:33], v[154:157], v[170:173], v[30:33]
	v_mfma_f32_16x16x32_bf16 v[26:29], v[162:165], v[170:173], v[26:29]
	v_mfma_f32_16x16x32_bf16 v[22:25], v[154:157], v[178:181], v[22:25]
	v_mfma_f32_16x16x32_bf16 v[18:21], v[162:165], v[178:181], v[18:21]
	v_mfma_f32_16x16x32_bf16 v[14:17], v[154:157], v[186:189], v[14:17]
	v_mfma_f32_16x16x32_bf16 v[10:13], v[162:165], v[186:189], v[10:13]
	v_mfma_f32_16x16x32_bf16 v[6:9], v[154:157], v[204:207], v[6:9]
	v_mfma_f32_16x16x32_bf16 v[2:5], v[162:165], v[204:207], v[2:5]
	s_barrier
	s_add_i32 s13, s12, 2
	s_add_u32 s30, s30, 0x100
	s_addc_u32 s31, s31, 0
	v_lshl_add_u64 v[130:131], v[130:131], 0, s[58:59]
	v_lshl_add_u64 v[132:133], v[132:133], 0, s[58:59]
	s_cmp_ge_i32 s12, s93
	s_mov_b32 s12, s13
	s_cbranch_scc0 .LBB0_842
	s_and_b64 vcc, exec, s[72:73]
	s_cbranch_vccz .LBB0_845
	s_barrier

; #define PG8_STAGE(bufoff, gbase, voff) do { _Pragma("unroll") for (int _i = 0; _i < 2; ++_i) \
;         __builtin_amdgcn_global_load_lds((const unsigned*)((const char*)(gbase) + (voff)[_i]), (LAS unsigned*)(lds + (bufoff) + ldsw + _i * 8192), 16, 0, 0); } while (0)
; #define PG8_LDA(dst, b, h) do { _Pragma("unroll") for (int m = 0; m < 4; ++m) _Pragma("unroll") for (int k = 0; k < 2; ++k) dst[m][k] = *(const LAS bf16x8*)(lds + PG8_SA(b, h) + aoff + m * 2048 + k * 1024); } while (0)
; #define PG8_LDB(dst, b, h) do { _Pragma("unroll") for (int n = 0; n < 2; ++n) _Pragma("unroll") for (int k = 0; k < 2; ++k) dst[n][k] = *(const LAS bf16x8*)(lds + PG8_SB(b, h) + boff + n * 2048 + k * 1024); } while (0)
; #define PG8_MMA(ai, bj, At, Bt) do { __builtin_amdgcn_s_setprio(1); _Pragma("unroll") for (int m = 0; m < 4; ++m) _Pragma("unroll") for (int n = 0; n < 2; ++n) _Pragma("unroll") for (int k = 0; k < 2; ++k) \
;         acc[ai][bj][m][n] = __builtin_amdgcn_mfma_f32_16x16x32_bf16(Bt[n][k], At[m][k], acc[ai][bj][m][n], 0, 0, 0); __builtin_amdgcn_s_setprio(0); } while (0)
; #define PG8_WAIT_V(n) asm volatile("s_waitcnt vmcnt(" #n ")" ::: "memory")
; #define PG8_WAIT_L(n) asm volatile("s_waitcnt lgkmcnt(" #n ")" ::: "memory")
; #define PG8_BAR __builtin_amdgcn_s_barrier()
; #define PG8_SCHED __builtin_amdgcn_sched_barrier(0)
; #define PG8_LDA(dst, b, h) do { _Pragma("unroll") for (int m = 0; m < 4; ++m) _Pragma("unroll") for (int k = 0; k < 2; ++k) dst[m][k] = *(const LAS bf16x8*)(lds + PG8_SA(b, h) + aoff + m * 2048 + k * 1024); } while (0)
; #define PG8_LDB(dst, b, h) do { _Pragma("unroll") for (int n = 0; n < 2; ++n) _Pragma("unroll") for (int k = 0; k < 2; ++k) dst[n][k] = *(const LAS bf16x8*)(lds + PG8_SB(b, h) + boff + n * 2048 + k * 1024); } while (0)
; #define PG8_WAIT_V(n) asm volatile("s_waitcnt vmcnt(" #n ")" ::: "memory")
; template <class Epi, class Sched>
; DI void gemm_phase(LAS unsigned char* lds, const Gemm g, const Sched& S, const Epi& E) {
;     ...
;             PG8_LDB(B0, 0, 0); PG8_LDB(B1, 0, 1); PG8_SCHED; PG8_LDA(At, 0, 0); PG8_STAGE(PG8_SA(1, 1), a1 + hstepA, voffA);
;             PG8_WAIT_V(8); PG8_WAIT_L(0); PG8_BAR; PG8_MMA(0, 0, At, B0); PG8_MMA(0, 1, At, B1); PG8_BAR; PG8_SCHED;
;             PG8_LDA(At, 0, 1); PG8_STAGE(PG8_SB(0, 0), b2, voffB); PG8_STAGE(PG8_SB(0, 1), b2 + hstepB, voffB); PG8_STAGE(PG8_SA(0, 0), a2, voffA);
.LBB0_954:
	s_add_u32 s36, s44, 0xfffc0080
	s_addc_u32 s37, s45, -1
	s_add_i32 s89, 0, 0x10000
	s_cmp_eq_u32 s88, 12
	s_cselect_b32 s39, s28, s37
	s_cselect_b32 s38, s31, s36
	s_cselect_b32 s37, s40, s77
	s_cselect_b32 s36, s41, s75
	s_add_i32 s92, 0, 0x14000
	v_add_u32_e32 v98, s89, v181
	v_add_u32_e32 v158, s92, v181
	ds_read_b128 v[78:81], v98
	ds_read_b128 v[82:85], v98 offset:1024
	ds_read_b128 v[94:97], v98 offset:2048
	ds_read_b128 v[98:101], v98 offset:3072
	ds_read_b128 v[146:149], v158
	ds_read_b128 v[150:153], v158 offset:1024
	ds_read_b128 v[154:157], v158 offset:2048
	ds_read_b128 v[158:161], v158 offset:3072
	v_lshl_add_u64 v[202:203], s[44:45], 0, v[168:169]
	s_add_i32 m0, s17, 0xc000
	ds_read_b128 v[172:175], v183
	ds_read_b128 v[176:179], v183 offset:1024
	ds_read_b128 v[184:187], v183 offset:2048
	ds_read_b128 v[188:191], v183 offset:3072
	ds_read_b128 v[192:195], v183 offset:4096
	ds_read_b128 v[198:201], v183 offset:5120
	ds_read_b128 v[204:207], v183 offset:6144
	ds_read_b128 v[208:211], v183 offset:7168
	global_load_lds_dwordx4 v[202:203], off
	v_lshl_add_u64 v[202:203], s[44:45], 0, v[170:171]
	s_add_i32 m0, s17, 0xe000
	s_nop 0
	global_load_lds_dwordx4 v[202:203], off
	s_waitcnt vmcnt(8)
	s_waitcnt lgkmcnt(0)
	s_barrier
	s_waitcnt lgkmcnt(0)
	v_mfma_f32_16x16x32_bf16 v[142:145], v[78:81], v[172:175], v[142:145]
	v_mfma_f32_16x16x32_bf16 v[138:141], v[94:97], v[172:175], v[138:141]
	v_mfma_f32_16x16x32_bf16 v[126:129], v[78:81], v[184:187], v[126:129]
	v_mfma_f32_16x16x32_bf16 v[122:125], v[94:97], v[184:187], v[122:125]
	v_mfma_f32_16x16x32_bf16 v[110:113], v[78:81], v[192:195], v[110:113]
	v_mfma_f32_16x16x32_bf16 v[106:109], v[94:97], v[192:195], v[106:109]
	v_mfma_f32_16x16x32_bf16 v[86:89], v[78:81], v[204:207], v[86:89]
	v_mfma_f32_16x16x32_bf16 v[74:77], v[94:97], v[204:207], v[74:77]
	v_mfma_f32_16x16x32_bf16 v[142:145], v[82:85], v[176:179], v[142:145]
	v_mfma_f32_16x16x32_bf16 v[138:141], v[98:101], v[176:179], v[138:141]
	v_mfma_f32_16x16x32_bf16 v[126:129], v[82:85], v[188:191], v[126:129]
	v_mfma_f32_16x16x32_bf16 v[122:125], v[98:101], v[188:191], v[122:125]
	v_mfma_f32_16x16x32_bf16 v[110:113], v[82:85], v[198:201], v[110:113]
	v_mfma_f32_16x16x32_bf16 v[106:109], v[98:101], v[198:201], v[106:109]
	v_mfma_f32_16x16x32_bf16 v[86:89], v[82:85], v[208:211], v[86:89]
	v_mfma_f32_16x16x32_bf16 v[74:77], v[98:101], v[208:211], v[74:77]
	v_mfma_f32_16x16x32_bf16 v[134:137], v[146:149], v[172:175], v[134:137]
	v_mfma_f32_16x16x32_bf16 v[130:133], v[154:157], v[172:175], v[130:133]
	v_mfma_f32_16x16x32_bf16 v[118:121], v[146:149], v[184:187], v[118:121]
	v_mfma_f32_16x16x32_bf16 v[114:117], v[154:157], v[184:187], v[114:117]
	v_mfma_f32_16x16x32_bf16 v[102:105], v[146:149], v[192:195], v[102:105]
	v_mfma_f32_16x16x32_bf16 v[90:93], v[154:157], v[192:195], v[90:93]
	v_mfma_f32_16x16x32_bf16 v[70:73], v[146:149], v[204:207], v[70:73]
	v_mfma_f32_16x16x32_bf16 v[66:69], v[154:157], v[204:207], v[66:69]
	v_mfma_f32_16x16x32_bf16 v[134:137], v[150:153], v[176:179], v[134:137]
	v_mfma_f32_16x16x32_bf16 v[130:133], v[158:161], v[176:179], v[130:133]
	v_mfma_f32_16x16x32_bf16 v[118:121], v[150:153], v[188:191], v[118:121]
	v_mfma_f32_16x16x32_bf16 v[114:117], v[158:161], v[188:191], v[114:117]
	v_mfma_f32_16x16x32_bf16 v[102:105], v[150:153], v[198:201], v[102:105]
	v_mfma_f32_16x16x32_bf16 v[90:93], v[158:161], v[198:201], v[90:93]
	v_mfma_f32_16x16x32_bf16 v[70:73], v[150:153], v[208:211], v[70:73]
	v_mfma_f32_16x16x32_bf16 v[66:69], v[158:161], v[208:211], v[66:69]
	s_barrier
	s_add_i32 s89, s89, s16
	v_lshl_add_u64 v[202:203], s[36:37], 0, v[0:1]
	s_mov_b32 m0, s89
	ds_read_b128 v[172:175], v183 offset:16384
	ds_read_b128 v[176:179], v183 offset:17408
	ds_read_b128 v[184:187], v183 offset:18432
	ds_read_b128 v[188:191], v183 offset:19456
	ds_read_b128 v[192:195], v183 offset:20480
	ds_read_b128 v[198:201], v183 offset:21504
	ds_read_b128 v[204:207], v183 offset:22528
	ds_read_b128 v[208:211], v183 offset:23552
	global_load_lds_dwordx4 v[202:203], off
	s_add_i32 m0, s89, 0x2000
	s_add_u32 s90, s36, 0x40000
	v_lshl_add_u64 v[212:213], s[36:37], 0, v[166:167]
	s_addc_u32 s91, s37, 0
	s_add_i32 s89, s92, s16
	global_load_lds_dwordx4 v[212:213], off
	v_lshl_add_u64 v[214:215], s[90:91], 0, v[0:1]
	s_mov_b32 m0, s89
	v_lshl_add_u64 v[216:217], s[38:39], 0, v[164:165]
	global_load_lds_dwordx4 v[214:215], off
	v_lshl_add_u64 v[214:215], s[90:91], 0, v[166:167]
	s_add_i32 m0, s89, 0x2000
	s_nop 0
	global_load_lds_dwordx4 v[214:215], off
	v_lshl_add_u64 v[214:215], s[38:39], 0, v[162:163]
	s_mov_b32 m0, s17
	s_nop 0
	global_load_lds_dwordx4 v[214:215], off
	s_mov_b32 m0, s25
	s_nop 0
	global_load_lds_dwordx4 v[216:217], off
	s_waitcnt vmcnt(8)
	s_waitcnt lgkmcnt(0)
	s_barrier
; #define PG8_STAGE(bufoff, gbase, voff) do { _Pragma("unroll") for (int _i = 0; _i < 2; ++_i) \
;         __builtin_amdgcn_global_load_lds((const unsigned*)((const char*)(gbase) + (voff)[_i]), (LAS unsigned*)(lds + (bufoff) + ldsw + _i * 8192), 16, 0, 0); } while (0)
; #define PG8_LDA(dst, b, h) do { _Pragma("unroll") for (int m = 0; m < 4; ++m) _Pragma("unroll") for (int k = 0; k < 2; ++k) dst[m][k] = *(const LAS bf16x8*)(lds + PG8_SA(b, h) + aoff + m * 2048 + k * 1024); } while (0)
; #define PG8_LDB(dst, b, h) do { _Pragma("unroll") for (int n = 0; n < 2; ++n) _Pragma("unroll") for (int k = 0; k < 2; ++k) dst[n][k] = *(const LAS bf16x8*)(lds + PG8_SB(b, h) + boff + n * 2048 + k * 1024); } while (0)
; #define PG8_MMA(ai, bj, At, Bt) do { __builtin_amdgcn_s_setprio(1); _Pragma("unroll") for (int m = 0; m < 4; ++m) _Pragma("unroll") for (int n = 0; n < 2; ++n) _Pragma("unroll") for (int k = 0; k < 2; ++k) \
;         acc[ai][bj][m][n] = __builtin_amdgcn_mfma_f32_16x16x32_bf16(Bt[n][k], At[m][k], acc[ai][bj][m][n], 0, 0, 0); __builtin_amdgcn_s_setprio(0); } while (0)
; #define PG8_WAIT_V(n) asm volatile("s_waitcnt vmcnt(" #n ")" ::: "memory")
; #define PG8_WAIT_L(n) asm volatile("s_waitcnt lgkmcnt(" #n ")" ::: "memory")
; #define PG8_BAR __builtin_amdgcn_s_barrier()
; #define PG8_SCHED __builtin_amdgcn_sched_barrier(0)
; #define PG8_LDA(dst, b, h) do { _Pragma("unroll") for (int m = 0; m < 4; ++m) _Pragma("unroll") for (int k = 0; k < 2; ++k) dst[m][k] = *(const LAS bf16x8*)(lds + PG8_SA(b, h) + aoff + m * 2048 + k * 1024); } while (0)
; #define PG8_LDB(dst, b, h) do { _Pragma("unroll") for (int n = 0; n < 2; ++n) _Pragma("unroll") for (int k = 0; k < 2; ++k) dst[n][k] = *(const LAS bf16x8*)(lds + PG8_SB(b, h) + boff + n * 2048 + k * 1024); } while (0)
; #define PG8_WAIT_V(n) asm volatile("s_waitcnt vmcnt(" #n ")" ::: "memory")
; #define PG8_BAR __builtin_amdgcn_s_barrier()
; template <class Epi, class Sched>
; DI void gemm_phase(LAS unsigned char* lds, const Gemm g, const Sched& S, const Epi& E) {
;     ...
;             PG8_WAIT_V(8); PG8_WAIT_L(0); PG8_BAR; PG8_MMA(1, 0, At, B0); PG8_MMA(1, 1, At, B1); PG8_BAR; PG8_SCHED;
;             PG8_LDB(B0, 1, 0); PG8_LDB(B1, 1, 1); PG8_SCHED; PG8_LDA(At, 1, 0); PG8_STAGE(PG8_SA(0, 1), a2 + hstepA, voffA);
;             PG8_WAIT_V(8); PG8_WAIT_L(0); PG8_BAR; PG8_MMA(0, 0, At, B0); PG8_MMA(0, 1, At, B1); PG8_BAR; PG8_SCHED;
	s_waitcnt lgkmcnt(0)
	v_mfma_f32_16x16x32_bf16 v[62:65], v[78:81], v[172:175], v[62:65]
	v_mfma_f32_16x16x32_bf16 v[58:61], v[94:97], v[172:175], v[58:61]
	v_mfma_f32_16x16x32_bf16 v[46:49], v[78:81], v[184:187], v[46:49]
	v_mfma_f32_16x16x32_bf16 v[42:45], v[94:97], v[184:187], v[42:45]
	v_mfma_f32_16x16x32_bf16 v[30:33], v[78:81], v[192:195], v[30:33]
	v_mfma_f32_16x16x32_bf16 v[26:29], v[94:97], v[192:195], v[26:29]
	v_mfma_f32_16x16x32_bf16 v[14:17], v[78:81], v[204:207], v[14:17]
	v_mfma_f32_16x16x32_bf16 v[10:13], v[94:97], v[204:207], v[10:13]
	v_mfma_f32_16x16x32_bf16 v[62:65], v[82:85], v[176:179], v[62:65]
	v_mfma_f32_16x16x32_bf16 v[58:61], v[98:101], v[176:179], v[58:61]
	v_mfma_f32_16x16x32_bf16 v[46:49], v[82:85], v[188:191], v[46:49]
	v_mfma_f32_16x16x32_bf16 v[42:45], v[98:101], v[188:191], v[42:45]
	v_mfma_f32_16x16x32_bf16 v[30:33], v[82:85], v[198:201], v[30:33]
	v_mfma_f32_16x16x32_bf16 v[26:29], v[98:101], v[198:201], v[26:29]
	v_mfma_f32_16x16x32_bf16 v[14:17], v[82:85], v[208:211], v[14:17]
	v_mfma_f32_16x16x32_bf16 v[10:13], v[98:101], v[208:211], v[10:13]
	v_mfma_f32_16x16x32_bf16 v[54:57], v[146:149], v[172:175], v[54:57]
	v_mfma_f32_16x16x32_bf16 v[50:53], v[154:157], v[172:175], v[50:53]
	v_mfma_f32_16x16x32_bf16 v[38:41], v[146:149], v[184:187], v[38:41]
	v_mfma_f32_16x16x32_bf16 v[34:37], v[154:157], v[184:187], v[34:37]
	v_mfma_f32_16x16x32_bf16 v[22:25], v[146:149], v[192:195], v[22:25]
	v_mfma_f32_16x16x32_bf16 v[18:21], v[154:157], v[192:195], v[18:21]
	v_mfma_f32_16x16x32_bf16 v[6:9], v[146:149], v[204:207], v[6:9]
	v_mfma_f32_16x16x32_bf16 v[2:5], v[154:157], v[204:207], v[2:5]
	v_mfma_f32_16x16x32_bf16 v[54:57], v[150:153], v[176:179], v[54:57]
	v_mfma_f32_16x16x32_bf16 v[50:53], v[158:161], v[176:179], v[50:53]
	v_mfma_f32_16x16x32_bf16 v[38:41], v[150:153], v[188:191], v[38:41]
	v_mfma_f32_16x16x32_bf16 v[34:37], v[158:161], v[188:191], v[34:37]
	v_mfma_f32_16x16x32_bf16 v[22:25], v[150:153], v[198:201], v[22:25]
	v_mfma_f32_16x16x32_bf16 v[18:21], v[158:161], v[198:201], v[18:21]
	v_mfma_f32_16x16x32_bf16 v[6:9], v[150:153], v[208:211], v[6:9]
	v_mfma_f32_16x16x32_bf16 v[2:5], v[158:161], v[208:211], v[2:5]
	s_barrier
	s_add_i32 s89, 0, 0x18000
	s_add_i32 s90, 0, 0x1c000
	v_add_u32_e32 v98, s89, v181
	v_add_u32_e32 v158, s90, v181
	ds_read_b128 v[78:81], v98
	ds_read_b128 v[82:85], v98 offset:1024
	ds_read_b128 v[94:97], v98 offset:2048
	ds_read_b128 v[98:101], v98 offset:3072
	ds_read_b128 v[146:149], v158
	ds_read_b128 v[150:153], v158 offset:1024
	ds_read_b128 v[154:157], v158 offset:2048
	ds_read_b128 v[158:161], v158 offset:3072
	s_add_u32 s38, s38, 0x40000
	s_addc_u32 s39, s39, 0
	s_mov_b32 m0, s49
	v_lshl_add_u64 v[218:219], s[38:39], 0, v[162:163]
	ds_read_b128 v[172:175], v183 offset:32768
	ds_read_b128 v[176:179], v183 offset:33792
	ds_read_b128 v[184:187], v183 offset:34816
	ds_read_b128 v[188:191], v183 offset:35840
	ds_read_b128 v[192:195], v183 offset:36864
	ds_read_b128 v[198:201], v183 offset:37888
	ds_read_b128 v[204:207], v183 offset:38912
	ds_read_b128 v[208:211], v183 offset:39936
	global_load_lds_dwordx4 v[218:219], off
	v_lshl_add_u64 v[218:219], s[38:39], 0, v[164:165]
	s_mov_b32 m0, s83
	s_nop 0
	global_load_lds_dwordx4 v[218:219], off
	s_waitcnt vmcnt(8)
	s_waitcnt lgkmcnt(0)
	s_barrier
	s_waitcnt lgkmcnt(0)
	v_mfma_f32_16x16x32_bf16 v[142:145], v[78:81], v[172:175], v[142:145]
	v_mfma_f32_16x16x32_bf16 v[138:141], v[94:97], v[172:175], v[138:141]
	v_mfma_f32_16x16x32_bf16 v[126:129], v[78:81], v[184:187], v[126:129]
	v_mfma_f32_16x16x32_bf16 v[122:125], v[94:97], v[184:187], v[122:125]
	v_mfma_f32_16x16x32_bf16 v[110:113], v[78:81], v[192:195], v[110:113]
	v_mfma_f32_16x16x32_bf16 v[106:109], v[94:97], v[192:195], v[106:109]
	v_mfma_f32_16x16x32_bf16 v[86:89], v[78:81], v[204:207], v[86:89]
	v_mfma_f32_16x16x32_bf16 v[74:77], v[94:97], v[204:207], v[74:77]
	v_mfma_f32_16x16x32_bf16 v[142:145], v[82:85], v[176:179], v[142:145]
	v_mfma_f32_16x16x32_bf16 v[138:141], v[98:101], v[176:179], v[138:141]
	v_mfma_f32_16x16x32_bf16 v[126:129], v[82:85], v[188:191], v[126:129]
	v_mfma_f32_16x16x32_bf16 v[122:125], v[98:101], v[188:191], v[122:125]
	v_mfma_f32_16x16x32_bf16 v[110:113], v[82:85], v[198:201], v[110:113]
	v_mfma_f32_16x16x32_bf16 v[106:109], v[98:101], v[198:201], v[106:109]
	v_mfma_f32_16x16x32_bf16 v[86:89], v[82:85], v[208:211], v[86:89]
	v_mfma_f32_16x16x32_bf16 v[74:77], v[98:101], v[208:211], v[74:77]
	v_mfma_f32_16x16x32_bf16 v[134:137], v[146:149], v[172:175], v[134:137]
	v_mfma_f32_16x16x32_bf16 v[130:133], v[154:157], v[172:175], v[130:133]
	v_mfma_f32_16x16x32_bf16 v[118:121], v[146:149], v[184:187], v[118:121]
	v_mfma_f32_16x16x32_bf16 v[114:117], v[154:157], v[184:187], v[114:117]
	v_mfma_f32_16x16x32_bf16 v[102:105], v[146:149], v[192:195], v[102:105]
	v_mfma_f32_16x16x32_bf16 v[90:93], v[154:157], v[192:195], v[90:93]
	v_mfma_f32_16x16x32_bf16 v[70:73], v[146:149], v[204:207], v[70:73]
	v_mfma_f32_16x16x32_bf16 v[66:69], v[154:157], v[204:207], v[66:69]
	v_mfma_f32_16x16x32_bf16 v[134:137], v[150:153], v[176:179], v[134:137]
	v_mfma_f32_16x16x32_bf16 v[130:133], v[158:161], v[176:179], v[130:133]
	v_mfma_f32_16x16x32_bf16 v[118:121], v[150:153], v[188:191], v[118:121]
	v_mfma_f32_16x16x32_bf16 v[114:117], v[158:161], v[188:191], v[114:117]
	v_mfma_f32_16x16x32_bf16 v[102:105], v[150:153], v[198:201], v[102:105]
	v_mfma_f32_16x16x32_bf16 v[90:93], v[158:161], v[198:201], v[90:93]
	v_mfma_f32_16x16x32_bf16 v[70:73], v[150:153], v[208:211], v[70:73]
	v_mfma_f32_16x16x32_bf16 v[66:69], v[158:161], v[208:211], v[66:69]
	s_barrier
; #define PG8_STAGE(bufoff, gbase, voff) do { _Pragma("unroll") for (int _i = 0; _i < 2; ++_i) \
;         __builtin_amdgcn_global_load_lds((const unsigned*)((const char*)(gbase) + (voff)[_i]), (LAS unsigned*)(lds + (bufoff) + ldsw + _i * 8192), 16, 0, 0); } while (0)
; #define PG8_LDA(dst, b, h) do { _Pragma("unroll") for (int m = 0; m < 4; ++m) _Pragma("unroll") for (int k = 0; k < 2; ++k) dst[m][k] = *(const LAS bf16x8*)(lds + PG8_SA(b, h) + aoff + m * 2048 + k * 1024); } while (0)
; #define PG8_MMA(ai, bj, At, Bt) do { __builtin_amdgcn_s_setprio(1); _Pragma("unroll") for (int m = 0; m < 4; ++m) _Pragma("unroll") for (int n = 0; n < 2; ++n) _Pragma("unroll") for (int k = 0; k < 2; ++k) \
;         acc[ai][bj][m][n] = __builtin_amdgcn_mfma_f32_16x16x32_bf16(Bt[n][k], At[m][k], acc[ai][bj][m][n], 0, 0, 0); __builtin_amdgcn_s_setprio(0); } while (0)
; #define PG8_WAIT_V(n) asm volatile("s_waitcnt vmcnt(" #n ")" ::: "memory")
; #define PG8_WAIT_L(n) asm volatile("s_waitcnt lgkmcnt(" #n ")" ::: "memory")
; #define PG8_BAR __builtin_amdgcn_s_barrier()
; #define PG8_SCHED __builtin_amdgcn_sched_barrier(0)
; #define PG8_LDA(dst, b, h) do { _Pragma("unroll") for (int m = 0; m < 4; ++m) _Pragma("unroll") for (int k = 0; k < 2; ++k) dst[m][k] = *(const LAS bf16x8*)(lds + PG8_SA(b, h) + aoff + m * 2048 + k * 1024); } while (0)
; #define PG8_MMA(ai, bj, At, Bt) do { __builtin_amdgcn_s_setprio(1); _Pragma("unroll") for (int m = 0; m < 4; ++m) _Pragma("unroll") for (int n = 0; n < 2; ++n) _Pragma("unroll") for (int k = 0; k < 2; ++k) \
;         acc[ai][bj][m][n] = __builtin_amdgcn_mfma_f32_16x16x32_bf16(Bt[n][k], At[m][k], acc[ai][bj][m][n], 0, 0, 0); __builtin_amdgcn_s_setprio(0); } while (0)
; #define PG8_WAIT_V(n) asm volatile("s_waitcnt vmcnt(" #n ")" ::: "memory")
; #define PG8_WAIT_L(n) asm volatile("s_waitcnt lgkmcnt(" #n ")" ::: "memory")
; #define PG8_BAR __builtin_amdgcn_s_barrier()
; template <class Epi, class Sched>
; DI void gemm_phase(LAS unsigned char* lds, const Gemm g, const Sched& S, const Epi& E) {
;     ...
;             PG8_LDA(At, 1, 1); PG8_STAGE(PG8_SB(1, 0), b3, voffB); PG8_STAGE(PG8_SB(1, 1), b3 + hstepB, voffB); PG8_STAGE(PG8_SA(1, 0), a3, voffA);
;             PG8_WAIT_V(8); PG8_WAIT_L(0); PG8_BAR; PG8_MMA(1, 0, At, B0); PG8_MMA(1, 1, At, B1); PG8_BAR; PG8_SCHED;
;         }
;         if (wr == 0) PG8_BAR;
	s_add_i32 s38, s89, s16
	v_lshl_add_u64 v[202:203], v[202:203], 0, s[26:27]
	s_mov_b32 m0, s38
	ds_read_b128 v[172:175], v183 offset:49152
	ds_read_b128 v[176:179], v183 offset:50176
	ds_read_b128 v[184:187], v183 offset:51200
	ds_read_b128 v[188:191], v183 offset:52224
	ds_read_b128 v[192:195], v183 offset:53248
	ds_read_b128 v[198:201], v183 offset:54272
	ds_read_b128 v[204:207], v183 offset:55296
	ds_read_b128 v[208:211], v183 offset:56320
	global_load_lds_dwordx4 v[202:203], off
	s_add_i32 m0, s38, 0x2000
	s_add_u32 s36, s36, 0x40080
	v_lshl_add_u64 v[202:203], v[212:213], 0, s[26:27]
	s_addc_u32 s37, s37, 0
	s_add_i32 s38, s90, s16
	global_load_lds_dwordx4 v[202:203], off
	v_lshl_add_u64 v[202:203], s[36:37], 0, v[0:1]
	s_mov_b32 m0, s38
	s_nop 0
	global_load_lds_dwordx4 v[202:203], off
	v_lshl_add_u64 v[202:203], s[36:37], 0, v[166:167]
	s_add_i32 m0, s38, 0x2000
	s_nop 0
	global_load_lds_dwordx4 v[202:203], off
	v_lshl_add_u64 v[202:203], v[214:215], 0, s[26:27]
	s_mov_b32 m0, s51
	s_nop 0
	global_load_lds_dwordx4 v[202:203], off
	v_lshl_add_u64 v[202:203], v[216:217], 0, s[26:27]
	s_mov_b32 m0, s86
	s_nop 0
	global_load_lds_dwordx4 v[202:203], off
	s_waitcnt vmcnt(8)
	s_waitcnt lgkmcnt(0)
	s_barrier
	s_waitcnt lgkmcnt(0)
	v_mfma_f32_16x16x32_bf16 v[62:65], v[78:81], v[172:175], v[62:65]
	v_mfma_f32_16x16x32_bf16 v[58:61], v[94:97], v[172:175], v[58:61]
	v_mfma_f32_16x16x32_bf16 v[46:49], v[78:81], v[184:187], v[46:49]
	v_mfma_f32_16x16x32_bf16 v[42:45], v[94:97], v[184:187], v[42:45]
	v_mfma_f32_16x16x32_bf16 v[30:33], v[78:81], v[192:195], v[30:33]
	v_mfma_f32_16x16x32_bf16 v[26:29], v[94:97], v[192:195], v[26:29]
	v_mfma_f32_16x16x32_bf16 v[14:17], v[78:81], v[204:207], v[14:17]
	v_mfma_f32_16x16x32_bf16 v[10:13], v[94:97], v[204:207], v[10:13]
	v_mfma_f32_16x16x32_bf16 v[62:65], v[82:85], v[176:179], v[62:65]
	v_mfma_f32_16x16x32_bf16 v[58:61], v[98:101], v[176:179], v[58:61]
	v_mfma_f32_16x16x32_bf16 v[46:49], v[82:85], v[188:191], v[46:49]
	v_mfma_f32_16x16x32_bf16 v[42:45], v[98:101], v[188:191], v[42:45]
	v_mfma_f32_16x16x32_bf16 v[30:33], v[82:85], v[198:201], v[30:33]
	v_mfma_f32_16x16x32_bf16 v[26:29], v[98:101], v[198:201], v[26:29]
	v_mfma_f32_16x16x32_bf16 v[14:17], v[82:85], v[208:211], v[14:17]
	v_mfma_f32_16x16x32_bf16 v[10:13], v[98:101], v[208:211], v[10:13]
	v_mfma_f32_16x16x32_bf16 v[54:57], v[146:149], v[172:175], v[54:57]
	v_mfma_f32_16x16x32_bf16 v[50:53], v[154:157], v[172:175], v[50:53]
	v_mfma_f32_16x16x32_bf16 v[38:41], v[146:149], v[184:187], v[38:41]
	v_mfma_f32_16x16x32_bf16 v[34:37], v[154:157], v[184:187], v[34:37]
	v_mfma_f32_16x16x32_bf16 v[22:25], v[146:149], v[192:195], v[22:25]
	v_mfma_f32_16x16x32_bf16 v[18:21], v[154:157], v[192:195], v[18:21]
	v_mfma_f32_16x16x32_bf16 v[6:9], v[146:149], v[204:207], v[6:9]
	v_mfma_f32_16x16x32_bf16 v[2:5], v[154:157], v[204:207], v[2:5]
	v_mfma_f32_16x16x32_bf16 v[54:57], v[150:153], v[176:179], v[54:57]
	v_mfma_f32_16x16x32_bf16 v[50:53], v[158:161], v[176:179], v[50:53]
	v_mfma_f32_16x16x32_bf16 v[38:41], v[150:153], v[188:191], v[38:41]
	v_mfma_f32_16x16x32_bf16 v[34:37], v[158:161], v[188:191], v[34:37]
	v_mfma_f32_16x16x32_bf16 v[22:25], v[150:153], v[198:201], v[22:25]
	v_mfma_f32_16x16x32_bf16 v[18:21], v[158:161], v[198:201], v[18:21]
	v_mfma_f32_16x16x32_bf16 v[6:9], v[150:153], v[208:211], v[6:9]
	v_mfma_f32_16x16x32_bf16 v[2:5], v[158:161], v[208:211], v[2:5]
	s_barrier
	s_add_i32 s88, s88, 2
	s_add_u32 s44, s44, 0x100
	s_addc_u32 s45, s45, 0
	s_add_u32 s75, s75, 0x100
	s_addc_u32 s77, s77, 0
	s_cmp_gt_u32 s88, 13
	s_cbranch_scc0 .LBB0_954
	s_and_b64 vcc, exec, s[72:73]
	s_cbranch_vccz .LBB0_957
	s_barrier

; #define PG8_STAGE(bufoff, gbase, voff) do { _Pragma("unroll") for (int _i = 0; _i < 2; ++_i) \
;         __builtin_amdgcn_global_load_lds((const unsigned*)((const char*)(gbase) + (voff)[_i]), (LAS unsigned*)(lds + (bufoff) + ldsw + _i * 8192), 16, 0, 0); } while (0)
; #define PG8_LDA(dst, b, h) do { _Pragma("unroll") for (int m = 0; m < 4; ++m) _Pragma("unroll") for (int k = 0; k < 2; ++k) dst[m][k] = *(const LAS bf16x8*)(lds + PG8_SA(b, h) + aoff + m * 2048 + k * 1024); } while (0)
; #define PG8_LDB(dst, b, h) do { _Pragma("unroll") for (int n = 0; n < 2; ++n) _Pragma("unroll") for (int k = 0; k < 2; ++k) dst[n][k] = *(const LAS bf16x8*)(lds + PG8_SB(b, h) + boff + n * 2048 + k * 1024); } while (0)
; #define PG8_MMA(ai, bj, At, Bt) do { __builtin_amdgcn_s_setprio(1); _Pragma("unroll") for (int m = 0; m < 4; ++m) _Pragma("unroll") for (int n = 0; n < 2; ++n) _Pragma("unroll") for (int k = 0; k < 2; ++k) \
;         acc[ai][bj][m][n] = __builtin_amdgcn_mfma_f32_16x16x32_bf16(Bt[n][k], At[m][k], acc[ai][bj][m][n], 0, 0, 0); __builtin_amdgcn_s_setprio(0); } while (0)
; #define PG8_WAIT_V(n) asm volatile("s_waitcnt vmcnt(" #n ")" ::: "memory")
; #define PG8_WAIT_L(n) asm volatile("s_waitcnt lgkmcnt(" #n ")" ::: "memory")
; #define PG8_BAR __builtin_amdgcn_s_barrier()
; #define PG8_SCHED __builtin_amdgcn_sched_barrier(0)
; #define PG8_LDA(dst, b, h) do { _Pragma("unroll") for (int m = 0; m < 4; ++m) _Pragma("unroll") for (int k = 0; k < 2; ++k) dst[m][k] = *(const LAS bf16x8*)(lds + PG8_SA(b, h) + aoff + m * 2048 + k * 1024); } while (0)
; #define PG8_LDB(dst, b, h) do { _Pragma("unroll") for (int n = 0; n < 2; ++n) _Pragma("unroll") for (int k = 0; k < 2; ++k) dst[n][k] = *(const LAS bf16x8*)(lds + PG8_SB(b, h) + boff + n * 2048 + k * 1024); } while (0)
; #define PG8_WAIT_V(n) asm volatile("s_waitcnt vmcnt(" #n ")" ::: "memory")
; template <class Epi, class Sched>
; DI void gemm_phase(LAS unsigned char* lds, const Gemm g, const Sched& S, const Epi& E) {
;     ...
;             PG8_LDB(B0, 0, 0); PG8_LDB(B1, 0, 1); PG8_SCHED; PG8_LDA(At, 0, 0); PG8_STAGE(PG8_SA(1, 1), a1 + hstepA, voffA);
;             PG8_WAIT_V(8); PG8_WAIT_L(0); PG8_BAR; PG8_MMA(0, 0, At, B0); PG8_MMA(0, 1, At, B1); PG8_BAR; PG8_SCHED;
;             PG8_LDA(At, 0, 1); PG8_STAGE(PG8_SB(0, 0), b2, voffB); PG8_STAGE(PG8_SB(0, 1), b2 + hstepB, voffB); PG8_STAGE(PG8_SA(0, 0), a2, voffA);
.LBB0_1066:
	s_add_u32 s36, s72, s30
	s_addc_u32 s37, s73, s31
	s_add_u32 s36, s36, 0x100
	s_addc_u32 s37, s37, 0
	s_add_u32 s83, s50, s30
	s_addc_u32 s86, s51, s31
	s_add_i32 s87, 0, 0x10000
	s_cmpk_eq_i32 s30, 0x700
	s_cselect_b32 s39, s63, s37
	s_cselect_b32 s38, s65, s36
	v_add_u32_e32 v149, s87, v145
	s_cselect_b32 s37, s75, s86
	s_cselect_b32 s36, s77, s83
	s_add_i32 s83, 0, 0x14000
	ds_read_b128 v[150:153], v149
	ds_read_b128 v[154:157], v149 offset:1024
	ds_read_b128 v[158:161], v149 offset:2048
	ds_read_b128 v[162:165], v149 offset:3072
	v_add_u32_e32 v149, s83, v145
	ds_read_b128 v[166:169], v149
	ds_read_b128 v[170:173], v149 offset:1024
	ds_read_b128 v[174:177], v149 offset:2048
	ds_read_b128 v[178:181], v149 offset:3072
	v_lshl_add_u64 v[194:195], v[140:141], 0, s[30:31]
	s_add_i32 m0, s17, 0xc000
	ds_read_b128 v[182:185], v148
	ds_read_b128 v[186:189], v148 offset:1024
	ds_read_b128 v[190:193], v148 offset:2048
	ds_read_b128 v[198:201], v148 offset:3072
	ds_read_b128 v[204:207], v148 offset:4096
	ds_read_b128 v[208:211], v148 offset:5120
	ds_read_b128 v[212:215], v148 offset:6144
	ds_read_b128 v[216:219], v148 offset:7168
	global_load_lds_dwordx4 v[194:195], off
	v_lshl_add_u64 v[194:195], v[142:143], 0, s[30:31]
	s_add_i32 m0, s17, 0xe000
	s_nop 0
	global_load_lds_dwordx4 v[194:195], off
	s_waitcnt vmcnt(8)
	s_waitcnt lgkmcnt(0)
	s_barrier
	s_waitcnt lgkmcnt(0)
	v_mfma_f32_16x16x32_bf16 v[126:129], v[150:153], v[182:185], v[126:129]
	v_mfma_f32_16x16x32_bf16 v[122:125], v[158:161], v[182:185], v[122:125]
	v_mfma_f32_16x16x32_bf16 v[118:121], v[150:153], v[190:193], v[118:121]
	v_mfma_f32_16x16x32_bf16 v[114:117], v[158:161], v[190:193], v[114:117]
	v_mfma_f32_16x16x32_bf16 v[110:113], v[150:153], v[204:207], v[110:113]
	v_mfma_f32_16x16x32_bf16 v[106:109], v[158:161], v[204:207], v[106:109]
	v_mfma_f32_16x16x32_bf16 v[102:105], v[150:153], v[212:215], v[102:105]
	v_mfma_f32_16x16x32_bf16 v[98:101], v[158:161], v[212:215], v[98:101]
	v_mfma_f32_16x16x32_bf16 v[126:129], v[154:157], v[186:189], v[126:129]
	v_mfma_f32_16x16x32_bf16 v[122:125], v[162:165], v[186:189], v[122:125]
	v_mfma_f32_16x16x32_bf16 v[118:121], v[154:157], v[198:201], v[118:121]
	v_mfma_f32_16x16x32_bf16 v[114:117], v[162:165], v[198:201], v[114:117]
	v_mfma_f32_16x16x32_bf16 v[110:113], v[154:157], v[208:211], v[110:113]
	v_mfma_f32_16x16x32_bf16 v[106:109], v[162:165], v[208:211], v[106:109]
	v_mfma_f32_16x16x32_bf16 v[102:105], v[154:157], v[216:219], v[102:105]
	v_mfma_f32_16x16x32_bf16 v[98:101], v[162:165], v[216:219], v[98:101]
	v_mfma_f32_16x16x32_bf16 v[94:97], v[166:169], v[182:185], v[94:97]
	v_mfma_f32_16x16x32_bf16 v[90:93], v[174:177], v[182:185], v[90:93]
	v_mfma_f32_16x16x32_bf16 v[86:89], v[166:169], v[190:193], v[86:89]
	v_mfma_f32_16x16x32_bf16 v[82:85], v[174:177], v[190:193], v[82:85]
	v_mfma_f32_16x16x32_bf16 v[78:81], v[166:169], v[204:207], v[78:81]
	v_mfma_f32_16x16x32_bf16 v[74:77], v[174:177], v[204:207], v[74:77]
	v_mfma_f32_16x16x32_bf16 v[70:73], v[166:169], v[212:215], v[70:73]
	v_mfma_f32_16x16x32_bf16 v[66:69], v[174:177], v[212:215], v[66:69]
	v_mfma_f32_16x16x32_bf16 v[94:97], v[170:173], v[186:189], v[94:97]
	v_mfma_f32_16x16x32_bf16 v[90:93], v[178:181], v[186:189], v[90:93]
	v_mfma_f32_16x16x32_bf16 v[86:89], v[170:173], v[198:201], v[86:89]
	v_mfma_f32_16x16x32_bf16 v[82:85], v[178:181], v[198:201], v[82:85]
	v_mfma_f32_16x16x32_bf16 v[78:81], v[170:173], v[208:211], v[78:81]
	v_mfma_f32_16x16x32_bf16 v[74:77], v[178:181], v[208:211], v[74:77]
	v_mfma_f32_16x16x32_bf16 v[70:73], v[170:173], v[216:219], v[70:73]
	v_mfma_f32_16x16x32_bf16 v[66:69], v[178:181], v[216:219], v[66:69]
	s_barrier
	s_add_i32 s86, s87, s16
	v_lshl_add_u64 v[194:195], s[36:37], 0, v[0:1]
	s_mov_b32 m0, s86
	ds_read_b128 v[182:185], v148 offset:16384
	ds_read_b128 v[186:189], v148 offset:17408
	ds_read_b128 v[190:193], v148 offset:18432
	ds_read_b128 v[198:201], v148 offset:19456
	ds_read_b128 v[204:207], v148 offset:20480
	ds_read_b128 v[208:211], v148 offset:21504
	ds_read_b128 v[212:215], v148 offset:22528
	ds_read_b128 v[216:219], v148 offset:23552
	global_load_lds_dwordx4 v[194:195], off
	s_add_i32 m0, s86, 0x2000
	s_add_u32 s86, s36, 0x40000
	v_lshl_add_u64 v[202:203], s[36:37], 0, v[134:135]
	s_addc_u32 s87, s37, 0
	s_add_i32 s83, s83, s16
	global_load_lds_dwordx4 v[202:203], off
	v_lshl_add_u64 v[220:221], s[86:87], 0, v[0:1]
	s_mov_b32 m0, s83
	v_lshl_add_u64 v[222:223], s[38:39], 0, v[132:133]
	global_load_lds_dwordx4 v[220:221], off
	v_lshl_add_u64 v[220:221], s[86:87], 0, v[134:135]
	s_add_i32 m0, s83, 0x2000
	s_nop 0
	global_load_lds_dwordx4 v[220:221], off
	v_lshl_add_u64 v[220:221], s[38:39], 0, v[130:131]
	s_mov_b32 m0, s17
	s_nop 0
	global_load_lds_dwordx4 v[220:221], off
	s_mov_b32 m0, s25
	s_nop 0
	global_load_lds_dwordx4 v[222:223], off
	s_waitcnt vmcnt(8)
	s_waitcnt lgkmcnt(0)
	s_barrier
; #define PG8_STAGE(bufoff, gbase, voff) do { _Pragma("unroll") for (int _i = 0; _i < 2; ++_i) \
;         __builtin_amdgcn_global_load_lds((const unsigned*)((const char*)(gbase) + (voff)[_i]), (LAS unsigned*)(lds + (bufoff) + ldsw + _i * 8192), 16, 0, 0); } while (0)
; #define PG8_LDA(dst, b, h) do { _Pragma("unroll") for (int m = 0; m < 4; ++m) _Pragma("unroll") for (int k = 0; k < 2; ++k) dst[m][k] = *(const LAS bf16x8*)(lds + PG8_SA(b, h) + aoff + m * 2048 + k * 1024); } while (0)
; #define PG8_LDB(dst, b, h) do { _Pragma("unroll") for (int n = 0; n < 2; ++n) _Pragma("unroll") for (int k = 0; k < 2; ++k) dst[n][k] = *(const LAS bf16x8*)(lds + PG8_SB(b, h) + boff + n * 2048 + k * 1024); } while (0)
; #define PG8_MMA(ai, bj, At, Bt) do { __builtin_amdgcn_s_setprio(1); _Pragma("unroll") for (int m = 0; m < 4; ++m) _Pragma("unroll") for (int n = 0; n < 2; ++n) _Pragma("unroll") for (int k = 0; k < 2; ++k) \
;         acc[ai][bj][m][n] = __builtin_amdgcn_mfma_f32_16x16x32_bf16(Bt[n][k], At[m][k], acc[ai][bj][m][n], 0, 0, 0); __builtin_amdgcn_s_setprio(0); } while (0)
; #define PG8_WAIT_V(n) asm volatile("s_waitcnt vmcnt(" #n ")" ::: "memory")
; #define PG8_WAIT_L(n) asm volatile("s_waitcnt lgkmcnt(" #n ")" ::: "memory")
; #define PG8_BAR __builtin_amdgcn_s_barrier()
; #define PG8_SCHED __builtin_amdgcn_sched_barrier(0)
; #define PG8_LDA(dst, b, h) do { _Pragma("unroll") for (int m = 0; m < 4; ++m) _Pragma("unroll") for (int k = 0; k < 2; ++k) dst[m][k] = *(const LAS bf16x8*)(lds + PG8_SA(b, h) + aoff + m * 2048 + k * 1024); } while (0)
; #define PG8_LDB(dst, b, h) do { _Pragma("unroll") for (int n = 0; n < 2; ++n) _Pragma("unroll") for (int k = 0; k < 2; ++k) dst[n][k] = *(const LAS bf16x8*)(lds + PG8_SB(b, h) + boff + n * 2048 + k * 1024); } while (0)
; #define PG8_WAIT_V(n) asm volatile("s_waitcnt vmcnt(" #n ")" ::: "memory")
; #define PG8_BAR __builtin_amdgcn_s_barrier()
; template <class Epi, class Sched>
; DI void gemm_phase(LAS unsigned char* lds, const Gemm g, const Sched& S, const Epi& E) {
;     ...
;             PG8_WAIT_V(8); PG8_WAIT_L(0); PG8_BAR; PG8_MMA(1, 0, At, B0); PG8_MMA(1, 1, At, B1); PG8_BAR; PG8_SCHED;
;             PG8_LDB(B0, 1, 0); PG8_LDB(B1, 1, 1); PG8_SCHED; PG8_LDA(At, 1, 0); PG8_STAGE(PG8_SA(0, 1), a2 + hstepA, voffA);
;             PG8_WAIT_V(8); PG8_WAIT_L(0); PG8_BAR; PG8_MMA(0, 0, At, B0); PG8_MMA(0, 1, At, B1); PG8_BAR; PG8_SCHED;
	s_waitcnt lgkmcnt(0)
	v_mfma_f32_16x16x32_bf16 v[62:65], v[150:153], v[182:185], v[62:65]
	v_mfma_f32_16x16x32_bf16 v[58:61], v[158:161], v[182:185], v[58:61]
	v_mfma_f32_16x16x32_bf16 v[54:57], v[150:153], v[190:193], v[54:57]
	v_mfma_f32_16x16x32_bf16 v[50:53], v[158:161], v[190:193], v[50:53]
	v_mfma_f32_16x16x32_bf16 v[46:49], v[150:153], v[204:207], v[46:49]
	v_mfma_f32_16x16x32_bf16 v[42:45], v[158:161], v[204:207], v[42:45]
	v_mfma_f32_16x16x32_bf16 v[38:41], v[150:153], v[212:215], v[38:41]
	v_mfma_f32_16x16x32_bf16 v[34:37], v[158:161], v[212:215], v[34:37]
	v_mfma_f32_16x16x32_bf16 v[62:65], v[154:157], v[186:189], v[62:65]
	v_mfma_f32_16x16x32_bf16 v[58:61], v[162:165], v[186:189], v[58:61]
	v_mfma_f32_16x16x32_bf16 v[54:57], v[154:157], v[198:201], v[54:57]
	v_mfma_f32_16x16x32_bf16 v[50:53], v[162:165], v[198:201], v[50:53]
	v_mfma_f32_16x16x32_bf16 v[46:49], v[154:157], v[208:211], v[46:49]
	v_mfma_f32_16x16x32_bf16 v[42:45], v[162:165], v[208:211], v[42:45]
	v_mfma_f32_16x16x32_bf16 v[38:41], v[154:157], v[216:219], v[38:41]
	v_mfma_f32_16x16x32_bf16 v[34:37], v[162:165], v[216:219], v[34:37]
	v_mfma_f32_16x16x32_bf16 v[30:33], v[166:169], v[182:185], v[30:33]
	v_mfma_f32_16x16x32_bf16 v[26:29], v[174:177], v[182:185], v[26:29]
	v_mfma_f32_16x16x32_bf16 v[22:25], v[166:169], v[190:193], v[22:25]
	v_mfma_f32_16x16x32_bf16 v[18:21], v[174:177], v[190:193], v[18:21]
	v_mfma_f32_16x16x32_bf16 v[14:17], v[166:169], v[204:207], v[14:17]
	v_mfma_f32_16x16x32_bf16 v[10:13], v[174:177], v[204:207], v[10:13]
	v_mfma_f32_16x16x32_bf16 v[6:9], v[166:169], v[212:215], v[6:9]
	v_mfma_f32_16x16x32_bf16 v[2:5], v[174:177], v[212:215], v[2:5]
	v_mfma_f32_16x16x32_bf16 v[30:33], v[170:173], v[186:189], v[30:33]
	v_mfma_f32_16x16x32_bf16 v[26:29], v[178:181], v[186:189], v[26:29]
	v_mfma_f32_16x16x32_bf16 v[22:25], v[170:173], v[198:201], v[22:25]
	v_mfma_f32_16x16x32_bf16 v[18:21], v[178:181], v[198:201], v[18:21]
	v_mfma_f32_16x16x32_bf16 v[14:17], v[170:173], v[208:211], v[14:17]
	v_mfma_f32_16x16x32_bf16 v[10:13], v[178:181], v[208:211], v[10:13]
	v_mfma_f32_16x16x32_bf16 v[6:9], v[170:173], v[216:219], v[6:9]
	v_mfma_f32_16x16x32_bf16 v[2:5], v[178:181], v[216:219], v[2:5]
	s_barrier
	s_add_i32 s83, 0, 0x18000
	v_add_u32_e32 v149, s83, v145
	s_add_i32 s86, 0, 0x1c000
	ds_read_b128 v[150:153], v149
	ds_read_b128 v[154:157], v149 offset:1024
	ds_read_b128 v[158:161], v149 offset:2048
	ds_read_b128 v[162:165], v149 offset:3072
	v_add_u32_e32 v149, s86, v145
	ds_read_b128 v[166:169], v149
	ds_read_b128 v[170:173], v149 offset:1024
	ds_read_b128 v[174:177], v149 offset:2048
	ds_read_b128 v[178:181], v149 offset:3072
	s_add_u32 s38, s38, 0x40000
	s_addc_u32 s39, s39, 0
	s_mov_b32 m0, s28
	v_lshl_add_u64 v[224:225], s[38:39], 0, v[130:131]
	ds_read_b128 v[182:185], v148 offset:32768
	ds_read_b128 v[186:189], v148 offset:33792
	ds_read_b128 v[190:193], v148 offset:34816
	ds_read_b128 v[198:201], v148 offset:35840
	ds_read_b128 v[204:207], v148 offset:36864
	ds_read_b128 v[208:211], v148 offset:37888
	ds_read_b128 v[212:215], v148 offset:38912
	ds_read_b128 v[216:219], v148 offset:39936
	global_load_lds_dwordx4 v[224:225], off
	v_lshl_add_u64 v[224:225], s[38:39], 0, v[132:133]
	s_mov_b32 m0, s40
	s_nop 0
	global_load_lds_dwordx4 v[224:225], off
	s_waitcnt vmcnt(8)
	s_waitcnt lgkmcnt(0)
	s_barrier
	s_waitcnt lgkmcnt(0)
	v_mfma_f32_16x16x32_bf16 v[126:129], v[150:153], v[182:185], v[126:129]
	v_mfma_f32_16x16x32_bf16 v[122:125], v[158:161], v[182:185], v[122:125]
	v_mfma_f32_16x16x32_bf16 v[118:121], v[150:153], v[190:193], v[118:121]
	v_mfma_f32_16x16x32_bf16 v[114:117], v[158:161], v[190:193], v[114:117]
	v_mfma_f32_16x16x32_bf16 v[110:113], v[150:153], v[204:207], v[110:113]
	v_mfma_f32_16x16x32_bf16 v[106:109], v[158:161], v[204:207], v[106:109]
	v_mfma_f32_16x16x32_bf16 v[102:105], v[150:153], v[212:215], v[102:105]
	v_mfma_f32_16x16x32_bf16 v[98:101], v[158:161], v[212:215], v[98:101]
	v_mfma_f32_16x16x32_bf16 v[126:129], v[154:157], v[186:189], v[126:129]
	v_mfma_f32_16x16x32_bf16 v[122:125], v[162:165], v[186:189], v[122:125]
	v_mfma_f32_16x16x32_bf16 v[118:121], v[154:157], v[198:201], v[118:121]
	v_mfma_f32_16x16x32_bf16 v[114:117], v[162:165], v[198:201], v[114:117]
	v_mfma_f32_16x16x32_bf16 v[110:113], v[154:157], v[208:211], v[110:113]
	v_mfma_f32_16x16x32_bf16 v[106:109], v[162:165], v[208:211], v[106:109]
	v_mfma_f32_16x16x32_bf16 v[102:105], v[154:157], v[216:219], v[102:105]
	v_mfma_f32_16x16x32_bf16 v[98:101], v[162:165], v[216:219], v[98:101]
	v_mfma_f32_16x16x32_bf16 v[94:97], v[166:169], v[182:185], v[94:97]
	v_mfma_f32_16x16x32_bf16 v[90:93], v[174:177], v[182:185], v[90:93]
	v_mfma_f32_16x16x32_bf16 v[86:89], v[166:169], v[190:193], v[86:89]
	v_mfma_f32_16x16x32_bf16 v[82:85], v[174:177], v[190:193], v[82:85]
	v_mfma_f32_16x16x32_bf16 v[78:81], v[166:169], v[204:207], v[78:81]
	v_mfma_f32_16x16x32_bf16 v[74:77], v[174:177], v[204:207], v[74:77]
	v_mfma_f32_16x16x32_bf16 v[70:73], v[166:169], v[212:215], v[70:73]
	v_mfma_f32_16x16x32_bf16 v[66:69], v[174:177], v[212:215], v[66:69]
	v_mfma_f32_16x16x32_bf16 v[94:97], v[170:173], v[186:189], v[94:97]
	v_mfma_f32_16x16x32_bf16 v[90:93], v[178:181], v[186:189], v[90:93]
	v_mfma_f32_16x16x32_bf16 v[86:89], v[170:173], v[198:201], v[86:89]
	v_mfma_f32_16x16x32_bf16 v[82:85], v[178:181], v[198:201], v[82:85]
	v_mfma_f32_16x16x32_bf16 v[78:81], v[170:173], v[208:211], v[78:81]
	v_mfma_f32_16x16x32_bf16 v[74:77], v[178:181], v[208:211], v[74:77]
	v_mfma_f32_16x16x32_bf16 v[70:73], v[170:173], v[216:219], v[70:73]
	v_mfma_f32_16x16x32_bf16 v[66:69], v[178:181], v[216:219], v[66:69]
	s_barrier
; #define PG8_STAGE(bufoff, gbase, voff) do { _Pragma("unroll") for (int _i = 0; _i < 2; ++_i) \
;         __builtin_amdgcn_global_load_lds((const unsigned*)((const char*)(gbase) + (voff)[_i]), (LAS unsigned*)(lds + (bufoff) + ldsw + _i * 8192), 16, 0, 0); } while (0)
; #define PG8_LDA(dst, b, h) do { _Pragma("unroll") for (int m = 0; m < 4; ++m) _Pragma("unroll") for (int k = 0; k < 2; ++k) dst[m][k] = *(const LAS bf16x8*)(lds + PG8_SA(b, h) + aoff + m * 2048 + k * 1024); } while (0)
; #define PG8_MMA(ai, bj, At, Bt) do { __builtin_amdgcn_s_setprio(1); _Pragma("unroll") for (int m = 0; m < 4; ++m) _Pragma("unroll") for (int n = 0; n < 2; ++n) _Pragma("unroll") for (int k = 0; k < 2; ++k) \
;         acc[ai][bj][m][n] = __builtin_amdgcn_mfma_f32_16x16x32_bf16(Bt[n][k], At[m][k], acc[ai][bj][m][n], 0, 0, 0); __builtin_amdgcn_s_setprio(0); } while (0)
; #define PG8_WAIT_V(n) asm volatile("s_waitcnt vmcnt(" #n ")" ::: "memory")
; #define PG8_WAIT_L(n) asm volatile("s_waitcnt lgkmcnt(" #n ")" ::: "memory")
; #define PG8_BAR __builtin_amdgcn_s_barrier()
; #define PG8_SCHED __builtin_amdgcn_sched_barrier(0)
; #define PG8_LDA(dst, b, h) do { _Pragma("unroll") for (int m = 0; m < 4; ++m) _Pragma("unroll") for (int k = 0; k < 2; ++k) dst[m][k] = *(const LAS bf16x8*)(lds + PG8_SA(b, h) + aoff + m * 2048 + k * 1024); } while (0)
; #define PG8_MMA(ai, bj, At, Bt) do { __builtin_amdgcn_s_setprio(1); _Pragma("unroll") for (int m = 0; m < 4; ++m) _Pragma("unroll") for (int n = 0; n < 2; ++n) _Pragma("unroll") for (int k = 0; k < 2; ++k) \
;         acc[ai][bj][m][n] = __builtin_amdgcn_mfma_f32_16x16x32_bf16(Bt[n][k], At[m][k], acc[ai][bj][m][n], 0, 0, 0); __builtin_amdgcn_s_setprio(0); } while (0)
; #define PG8_WAIT_V(n) asm volatile("s_waitcnt vmcnt(" #n ")" ::: "memory")
; #define PG8_WAIT_L(n) asm volatile("s_waitcnt lgkmcnt(" #n ")" ::: "memory")
; #define PG8_BAR __builtin_amdgcn_s_barrier()
; template <class Epi, class Sched>
; DI void gemm_phase(LAS unsigned char* lds, const Gemm g, const Sched& S, const Epi& E) {
;     ...
;             PG8_LDA(At, 1, 1); PG8_STAGE(PG8_SB(1, 0), b3, voffB); PG8_STAGE(PG8_SB(1, 1), b3 + hstepB, voffB); PG8_STAGE(PG8_SA(1, 0), a3, voffA);
;             PG8_WAIT_V(8); PG8_WAIT_L(0); PG8_BAR; PG8_MMA(1, 0, At, B0); PG8_MMA(1, 1, At, B1); PG8_BAR; PG8_SCHED;
;         }
;         if (wr == 0) PG8_BAR;
	s_add_i32 s38, s83, s16
	v_lshl_add_u64 v[194:195], v[194:195], 0, s[26:27]
	s_mov_b32 m0, s38
	ds_read_b128 v[182:185], v148 offset:49152
	ds_read_b128 v[186:189], v148 offset:50176
	ds_read_b128 v[190:193], v148 offset:51200
	ds_read_b128 v[198:201], v148 offset:52224
	ds_read_b128 v[204:207], v148 offset:53248
	ds_read_b128 v[208:211], v148 offset:54272
	ds_read_b128 v[212:215], v148 offset:55296
	ds_read_b128 v[216:219], v148 offset:56320
	global_load_lds_dwordx4 v[194:195], off
	s_add_i32 m0, s38, 0x2000
	s_add_u32 s36, s36, 0x40080
	v_lshl_add_u64 v[194:195], v[202:203], 0, s[26:27]
	s_addc_u32 s37, s37, 0
	s_add_i32 s38, s86, s16
	global_load_lds_dwordx4 v[194:195], off
	v_lshl_add_u64 v[194:195], s[36:37], 0, v[0:1]
	s_mov_b32 m0, s38
	s_nop 0
	global_load_lds_dwordx4 v[194:195], off
	v_lshl_add_u64 v[194:195], s[36:37], 0, v[134:135]
	s_add_i32 m0, s38, 0x2000
	s_nop 0
	global_load_lds_dwordx4 v[194:195], off
	v_lshl_add_u64 v[194:195], v[220:221], 0, s[26:27]
	s_mov_b32 m0, s41
	s_nop 0
	global_load_lds_dwordx4 v[194:195], off
	v_lshl_add_u64 v[194:195], v[222:223], 0, s[26:27]
	s_mov_b32 m0, s44
	s_nop 0
	global_load_lds_dwordx4 v[194:195], off
	s_waitcnt vmcnt(8)
	s_waitcnt lgkmcnt(0)
	s_barrier
	s_waitcnt lgkmcnt(0)
	v_mfma_f32_16x16x32_bf16 v[62:65], v[150:153], v[182:185], v[62:65]
	v_mfma_f32_16x16x32_bf16 v[58:61], v[158:161], v[182:185], v[58:61]
	v_mfma_f32_16x16x32_bf16 v[54:57], v[150:153], v[190:193], v[54:57]
	v_mfma_f32_16x16x32_bf16 v[50:53], v[158:161], v[190:193], v[50:53]
	v_mfma_f32_16x16x32_bf16 v[46:49], v[150:153], v[204:207], v[46:49]
	v_mfma_f32_16x16x32_bf16 v[42:45], v[158:161], v[204:207], v[42:45]
	v_mfma_f32_16x16x32_bf16 v[38:41], v[150:153], v[212:215], v[38:41]
	v_mfma_f32_16x16x32_bf16 v[34:37], v[158:161], v[212:215], v[34:37]
	v_mfma_f32_16x16x32_bf16 v[62:65], v[154:157], v[186:189], v[62:65]
	v_mfma_f32_16x16x32_bf16 v[58:61], v[162:165], v[186:189], v[58:61]
	v_mfma_f32_16x16x32_bf16 v[54:57], v[154:157], v[198:201], v[54:57]
	v_mfma_f32_16x16x32_bf16 v[50:53], v[162:165], v[198:201], v[50:53]
	v_mfma_f32_16x16x32_bf16 v[46:49], v[154:157], v[208:211], v[46:49]
	v_mfma_f32_16x16x32_bf16 v[42:45], v[162:165], v[208:211], v[42:45]
	v_mfma_f32_16x16x32_bf16 v[38:41], v[154:157], v[216:219], v[38:41]
	v_mfma_f32_16x16x32_bf16 v[34:37], v[162:165], v[216:219], v[34:37]
	v_mfma_f32_16x16x32_bf16 v[30:33], v[166:169], v[182:185], v[30:33]
	v_mfma_f32_16x16x32_bf16 v[26:29], v[174:177], v[182:185], v[26:29]
	v_mfma_f32_16x16x32_bf16 v[22:25], v[166:169], v[190:193], v[22:25]
	v_mfma_f32_16x16x32_bf16 v[18:21], v[174:177], v[190:193], v[18:21]
	v_mfma_f32_16x16x32_bf16 v[14:17], v[166:169], v[204:207], v[14:17]
	v_mfma_f32_16x16x32_bf16 v[10:13], v[174:177], v[204:207], v[10:13]
	v_mfma_f32_16x16x32_bf16 v[6:9], v[166:169], v[212:215], v[6:9]
	v_mfma_f32_16x16x32_bf16 v[2:5], v[174:177], v[212:215], v[2:5]
	v_mfma_f32_16x16x32_bf16 v[30:33], v[170:173], v[186:189], v[30:33]
	v_mfma_f32_16x16x32_bf16 v[26:29], v[178:181], v[186:189], v[26:29]
	v_mfma_f32_16x16x32_bf16 v[22:25], v[170:173], v[198:201], v[22:25]
	v_mfma_f32_16x16x32_bf16 v[18:21], v[178:181], v[198:201], v[18:21]
	v_mfma_f32_16x16x32_bf16 v[14:17], v[170:173], v[208:211], v[14:17]
	v_mfma_f32_16x16x32_bf16 v[10:13], v[178:181], v[208:211], v[10:13]
	v_mfma_f32_16x16x32_bf16 v[6:9], v[170:173], v[216:219], v[6:9]
	v_mfma_f32_16x16x32_bf16 v[2:5], v[178:181], v[216:219], v[2:5]
	s_barrier
	s_add_i32 s82, s82, 2
	s_add_u32 s30, s30, 0x100
	s_addc_u32 s31, s31, 0
	s_cmp_gt_u32 s82, 13
	s_cbranch_scc0 .LBB0_1066
	s_and_b64 vcc, exec, s[70:71]
	s_cbranch_vccz .LBB0_1069
	s_barrier

; #define PG8_STAGE(bufoff, gbase, voff) do { _Pragma("unroll") for (int _i = 0; _i < 2; ++_i) \
;         __builtin_amdgcn_global_load_lds((const unsigned*)((const char*)(gbase) + (voff)[_i]), (LAS unsigned*)(lds + (bufoff) + ldsw + _i * 8192), 16, 0, 0); } while (0)
; #define PG8_LDA(dst, b, h) do { _Pragma("unroll") for (int m = 0; m < 4; ++m) _Pragma("unroll") for (int k = 0; k < 2; ++k) dst[m][k] = *(const LAS bf16x8*)(lds + PG8_SA(b, h) + aoff + m * 2048 + k * 1024); } while (0)
; #define PG8_LDB(dst, b, h) do { _Pragma("unroll") for (int n = 0; n < 2; ++n) _Pragma("unroll") for (int k = 0; k < 2; ++k) dst[n][k] = *(const LAS bf16x8*)(lds + PG8_SB(b, h) + boff + n * 2048 + k * 1024); } while (0)
; #define PG8_MMA(ai, bj, At, Bt) do { __builtin_amdgcn_s_setprio(1); _Pragma("unroll") for (int m = 0; m < 4; ++m) _Pragma("unroll") for (int n = 0; n < 2; ++n) _Pragma("unroll") for (int k = 0; k < 2; ++k) \
;         acc[ai][bj][m][n] = __builtin_amdgcn_mfma_f32_16x16x32_bf16(Bt[n][k], At[m][k], acc[ai][bj][m][n], 0, 0, 0); __builtin_amdgcn_s_setprio(0); } while (0)
; #define PG8_WAIT_V(n) asm volatile("s_waitcnt vmcnt(" #n ")" ::: "memory")
; #define PG8_WAIT_L(n) asm volatile("s_waitcnt lgkmcnt(" #n ")" ::: "memory")
; #define PG8_BAR __builtin_amdgcn_s_barrier()
; #define PG8_SCHED __builtin_amdgcn_sched_barrier(0)
; #define PG8_LDA(dst, b, h) do { _Pragma("unroll") for (int m = 0; m < 4; ++m) _Pragma("unroll") for (int k = 0; k < 2; ++k) dst[m][k] = *(const LAS bf16x8*)(lds + PG8_SA(b, h) + aoff + m * 2048 + k * 1024); } while (0)
; #define PG8_LDB(dst, b, h) do { _Pragma("unroll") for (int n = 0; n < 2; ++n) _Pragma("unroll") for (int k = 0; k < 2; ++k) dst[n][k] = *(const LAS bf16x8*)(lds + PG8_SB(b, h) + boff + n * 2048 + k * 1024); } while (0)
; #define PG8_WAIT_V(n) asm volatile("s_waitcnt vmcnt(" #n ")" ::: "memory")
; template <class Epi, class Sched>
; DI void gemm_phase(LAS unsigned char* lds, const Gemm g, const Sched& S, const Epi& E) {
;     ...
;             PG8_LDB(B0, 0, 0); PG8_LDB(B1, 0, 1); PG8_SCHED; PG8_LDA(At, 0, 0); PG8_STAGE(PG8_SA(1, 1), a1 + hstepA, voffA);
;             PG8_WAIT_V(8); PG8_WAIT_L(0); PG8_BAR; PG8_MMA(0, 0, At, B0); PG8_MMA(0, 1, At, B1); PG8_BAR; PG8_SCHED;
;             PG8_LDA(At, 0, 1); PG8_STAGE(PG8_SB(0, 0), b2, voffB); PG8_STAGE(PG8_SB(0, 1), b2 + hstepB, voffB); PG8_STAGE(PG8_SA(0, 0), a2, voffA);
.LBB0_1253:
	s_add_u32 s36, s50, 0xfffe0080
	s_addc_u32 s37, s51, -1
	s_add_i32 s88, 0, 0x10000
	s_cmp_eq_u32 s87, 4
	s_cselect_b32 s39, s28, s37
	s_cselect_b32 s38, s40, s36
	s_cselect_b32 s37, s41, s73
	s_cselect_b32 s36, s45, s71
	s_add_i32 s90, 0, 0x14000
	v_add_u32_e32 v98, s88, v181
	v_add_u32_e32 v158, s90, v181
	ds_read_b128 v[78:81], v98
	ds_read_b128 v[82:85], v98 offset:1024
	ds_read_b128 v[94:97], v98 offset:2048
	ds_read_b128 v[98:101], v98 offset:3072
	ds_read_b128 v[146:149], v158
	ds_read_b128 v[150:153], v158 offset:1024
	ds_read_b128 v[154:157], v158 offset:2048
	ds_read_b128 v[158:161], v158 offset:3072
	v_lshl_add_u64 v[202:203], s[50:51], 0, v[168:169]
	s_add_i32 m0, s17, 0xc000
	ds_read_b128 v[172:175], v183
	ds_read_b128 v[176:179], v183 offset:1024
	ds_read_b128 v[184:187], v183 offset:2048
	ds_read_b128 v[188:191], v183 offset:3072
	ds_read_b128 v[192:195], v183 offset:4096
	ds_read_b128 v[198:201], v183 offset:5120
	ds_read_b128 v[204:207], v183 offset:6144
	ds_read_b128 v[208:211], v183 offset:7168
	global_load_lds_dwordx4 v[202:203], off
	v_lshl_add_u64 v[202:203], s[50:51], 0, v[170:171]
	s_add_i32 m0, s17, 0xe000
	s_nop 0
	global_load_lds_dwordx4 v[202:203], off
	s_waitcnt vmcnt(8)
	s_waitcnt lgkmcnt(0)
	s_barrier
	s_waitcnt lgkmcnt(0)
	v_mfma_f32_16x16x32_bf16 v[142:145], v[78:81], v[172:175], v[142:145]
	v_mfma_f32_16x16x32_bf16 v[138:141], v[94:97], v[172:175], v[138:141]
	v_mfma_f32_16x16x32_bf16 v[126:129], v[78:81], v[184:187], v[126:129]
	v_mfma_f32_16x16x32_bf16 v[122:125], v[94:97], v[184:187], v[122:125]
	v_mfma_f32_16x16x32_bf16 v[110:113], v[78:81], v[192:195], v[110:113]
	v_mfma_f32_16x16x32_bf16 v[106:109], v[94:97], v[192:195], v[106:109]
	v_mfma_f32_16x16x32_bf16 v[86:89], v[78:81], v[204:207], v[86:89]
	v_mfma_f32_16x16x32_bf16 v[74:77], v[94:97], v[204:207], v[74:77]
	v_mfma_f32_16x16x32_bf16 v[142:145], v[82:85], v[176:179], v[142:145]
	v_mfma_f32_16x16x32_bf16 v[138:141], v[98:101], v[176:179], v[138:141]
	v_mfma_f32_16x16x32_bf16 v[126:129], v[82:85], v[188:191], v[126:129]
	v_mfma_f32_16x16x32_bf16 v[122:125], v[98:101], v[188:191], v[122:125]
	v_mfma_f32_16x16x32_bf16 v[110:113], v[82:85], v[198:201], v[110:113]
	v_mfma_f32_16x16x32_bf16 v[106:109], v[98:101], v[198:201], v[106:109]
	v_mfma_f32_16x16x32_bf16 v[86:89], v[82:85], v[208:211], v[86:89]
	v_mfma_f32_16x16x32_bf16 v[74:77], v[98:101], v[208:211], v[74:77]
	v_mfma_f32_16x16x32_bf16 v[134:137], v[146:149], v[172:175], v[134:137]
	v_mfma_f32_16x16x32_bf16 v[130:133], v[154:157], v[172:175], v[130:133]
	v_mfma_f32_16x16x32_bf16 v[118:121], v[146:149], v[184:187], v[118:121]
	v_mfma_f32_16x16x32_bf16 v[114:117], v[154:157], v[184:187], v[114:117]
	v_mfma_f32_16x16x32_bf16 v[102:105], v[146:149], v[192:195], v[102:105]
	v_mfma_f32_16x16x32_bf16 v[90:93], v[154:157], v[192:195], v[90:93]
	v_mfma_f32_16x16x32_bf16 v[70:73], v[146:149], v[204:207], v[70:73]
	v_mfma_f32_16x16x32_bf16 v[66:69], v[154:157], v[204:207], v[66:69]
	v_mfma_f32_16x16x32_bf16 v[134:137], v[150:153], v[176:179], v[134:137]
	v_mfma_f32_16x16x32_bf16 v[130:133], v[158:161], v[176:179], v[130:133]
	v_mfma_f32_16x16x32_bf16 v[118:121], v[150:153], v[188:191], v[118:121]
	v_mfma_f32_16x16x32_bf16 v[114:117], v[158:161], v[188:191], v[114:117]
	v_mfma_f32_16x16x32_bf16 v[102:105], v[150:153], v[198:201], v[102:105]
	v_mfma_f32_16x16x32_bf16 v[90:93], v[158:161], v[198:201], v[90:93]
	v_mfma_f32_16x16x32_bf16 v[70:73], v[150:153], v[208:211], v[70:73]
	v_mfma_f32_16x16x32_bf16 v[66:69], v[158:161], v[208:211], v[66:69]
	s_barrier
	s_add_i32 s88, s88, s16
	v_lshl_add_u64 v[202:203], s[36:37], 0, v[0:1]
	s_mov_b32 m0, s88
	ds_read_b128 v[172:175], v183 offset:16384
	ds_read_b128 v[176:179], v183 offset:17408
	ds_read_b128 v[184:187], v183 offset:18432
	ds_read_b128 v[188:191], v183 offset:19456
	ds_read_b128 v[192:195], v183 offset:20480
	ds_read_b128 v[198:201], v183 offset:21504
	ds_read_b128 v[204:207], v183 offset:22528
	ds_read_b128 v[208:211], v183 offset:23552
	global_load_lds_dwordx4 v[202:203], off
	s_add_i32 m0, s88, 0x2000
	s_add_u32 s88, s36, 0x20000
	v_lshl_add_u64 v[212:213], s[36:37], 0, v[166:167]
	s_addc_u32 s89, s37, 0
	s_add_i32 s90, s90, s16
	global_load_lds_dwordx4 v[212:213], off
	v_lshl_add_u64 v[214:215], s[88:89], 0, v[0:1]
	s_mov_b32 m0, s90
	v_lshl_add_u64 v[216:217], s[38:39], 0, v[164:165]
	global_load_lds_dwordx4 v[214:215], off
	v_lshl_add_u64 v[214:215], s[88:89], 0, v[166:167]
	s_add_i32 m0, s90, 0x2000
	s_nop 0
	global_load_lds_dwordx4 v[214:215], off
	v_lshl_add_u64 v[214:215], s[38:39], 0, v[162:163]
	s_mov_b32 m0, s17
	s_nop 0
	global_load_lds_dwordx4 v[214:215], off
	s_mov_b32 m0, s25
	s_nop 0
	global_load_lds_dwordx4 v[216:217], off
	s_waitcnt vmcnt(8)
	s_waitcnt lgkmcnt(0)
	s_barrier
; #define PG8_STAGE(bufoff, gbase, voff) do { _Pragma("unroll") for (int _i = 0; _i < 2; ++_i) \
;         __builtin_amdgcn_global_load_lds((const unsigned*)((const char*)(gbase) + (voff)[_i]), (LAS unsigned*)(lds + (bufoff) + ldsw + _i * 8192), 16, 0, 0); } while (0)
; #define PG8_LDA(dst, b, h) do { _Pragma("unroll") for (int m = 0; m < 4; ++m) _Pragma("unroll") for (int k = 0; k < 2; ++k) dst[m][k] = *(const LAS bf16x8*)(lds + PG8_SA(b, h) + aoff + m * 2048 + k * 1024); } while (0)
; #define PG8_LDB(dst, b, h) do { _Pragma("unroll") for (int n = 0; n < 2; ++n) _Pragma("unroll") for (int k = 0; k < 2; ++k) dst[n][k] = *(const LAS bf16x8*)(lds + PG8_SB(b, h) + boff + n * 2048 + k * 1024); } while (0)
; #define PG8_MMA(ai, bj, At, Bt) do { __builtin_amdgcn_s_setprio(1); _Pragma("unroll") for (int m = 0; m < 4; ++m) _Pragma("unroll") for (int n = 0; n < 2; ++n) _Pragma("unroll") for (int k = 0; k < 2; ++k) \
;         acc[ai][bj][m][n] = __builtin_amdgcn_mfma_f32_16x16x32_bf16(Bt[n][k], At[m][k], acc[ai][bj][m][n], 0, 0, 0); __builtin_amdgcn_s_setprio(0); } while (0)
; #define PG8_WAIT_V(n) asm volatile("s_waitcnt vmcnt(" #n ")" ::: "memory")
; #define PG8_WAIT_L(n) asm volatile("s_waitcnt lgkmcnt(" #n ")" ::: "memory")
; #define PG8_BAR __builtin_amdgcn_s_barrier()
; #define PG8_SCHED __builtin_amdgcn_sched_barrier(0)
; #define PG8_LDA(dst, b, h) do { _Pragma("unroll") for (int m = 0; m < 4; ++m) _Pragma("unroll") for (int k = 0; k < 2; ++k) dst[m][k] = *(const LAS bf16x8*)(lds + PG8_SA(b, h) + aoff + m * 2048 + k * 1024); } while (0)
; #define PG8_LDB(dst, b, h) do { _Pragma("unroll") for (int n = 0; n < 2; ++n) _Pragma("unroll") for (int k = 0; k < 2; ++k) dst[n][k] = *(const LAS bf16x8*)(lds + PG8_SB(b, h) + boff + n * 2048 + k * 1024); } while (0)
; #define PG8_WAIT_V(n) asm volatile("s_waitcnt vmcnt(" #n ")" ::: "memory")
; #define PG8_BAR __builtin_amdgcn_s_barrier()
; template <class Epi, class Sched>
; DI void gemm_phase(LAS unsigned char* lds, const Gemm g, const Sched& S, const Epi& E) {
;     ...
;             PG8_WAIT_V(8); PG8_WAIT_L(0); PG8_BAR; PG8_MMA(1, 0, At, B0); PG8_MMA(1, 1, At, B1); PG8_BAR; PG8_SCHED;
;             PG8_LDB(B0, 1, 0); PG8_LDB(B1, 1, 1); PG8_SCHED; PG8_LDA(At, 1, 0); PG8_STAGE(PG8_SA(0, 1), a2 + hstepA, voffA);
;             PG8_WAIT_V(8); PG8_WAIT_L(0); PG8_BAR; PG8_MMA(0, 0, At, B0); PG8_MMA(0, 1, At, B1); PG8_BAR; PG8_SCHED;
	s_waitcnt lgkmcnt(0)
	v_mfma_f32_16x16x32_bf16 v[62:65], v[78:81], v[172:175], v[62:65]
	v_mfma_f32_16x16x32_bf16 v[58:61], v[94:97], v[172:175], v[58:61]
	v_mfma_f32_16x16x32_bf16 v[46:49], v[78:81], v[184:187], v[46:49]
	v_mfma_f32_16x16x32_bf16 v[42:45], v[94:97], v[184:187], v[42:45]
	v_mfma_f32_16x16x32_bf16 v[30:33], v[78:81], v[192:195], v[30:33]
	v_mfma_f32_16x16x32_bf16 v[26:29], v[94:97], v[192:195], v[26:29]
	v_mfma_f32_16x16x32_bf16 v[14:17], v[78:81], v[204:207], v[14:17]
	v_mfma_f32_16x16x32_bf16 v[10:13], v[94:97], v[204:207], v[10:13]
	v_mfma_f32_16x16x32_bf16 v[62:65], v[82:85], v[176:179], v[62:65]
	v_mfma_f32_16x16x32_bf16 v[58:61], v[98:101], v[176:179], v[58:61]
	v_mfma_f32_16x16x32_bf16 v[46:49], v[82:85], v[188:191], v[46:49]
	v_mfma_f32_16x16x32_bf16 v[42:45], v[98:101], v[188:191], v[42:45]
	v_mfma_f32_16x16x32_bf16 v[30:33], v[82:85], v[198:201], v[30:33]
	v_mfma_f32_16x16x32_bf16 v[26:29], v[98:101], v[198:201], v[26:29]
	v_mfma_f32_16x16x32_bf16 v[14:17], v[82:85], v[208:211], v[14:17]
	v_mfma_f32_16x16x32_bf16 v[10:13], v[98:101], v[208:211], v[10:13]
	v_mfma_f32_16x16x32_bf16 v[54:57], v[146:149], v[172:175], v[54:57]
	v_mfma_f32_16x16x32_bf16 v[50:53], v[154:157], v[172:175], v[50:53]
	v_mfma_f32_16x16x32_bf16 v[38:41], v[146:149], v[184:187], v[38:41]
	v_mfma_f32_16x16x32_bf16 v[34:37], v[154:157], v[184:187], v[34:37]
	v_mfma_f32_16x16x32_bf16 v[22:25], v[146:149], v[192:195], v[22:25]
	v_mfma_f32_16x16x32_bf16 v[18:21], v[154:157], v[192:195], v[18:21]
	v_mfma_f32_16x16x32_bf16 v[6:9], v[146:149], v[204:207], v[6:9]
	v_mfma_f32_16x16x32_bf16 v[2:5], v[154:157], v[204:207], v[2:5]
	v_mfma_f32_16x16x32_bf16 v[54:57], v[150:153], v[176:179], v[54:57]
	v_mfma_f32_16x16x32_bf16 v[50:53], v[158:161], v[176:179], v[50:53]
	v_mfma_f32_16x16x32_bf16 v[38:41], v[150:153], v[188:191], v[38:41]
	v_mfma_f32_16x16x32_bf16 v[34:37], v[158:161], v[188:191], v[34:37]
	v_mfma_f32_16x16x32_bf16 v[22:25], v[150:153], v[198:201], v[22:25]
	v_mfma_f32_16x16x32_bf16 v[18:21], v[158:161], v[198:201], v[18:21]
	v_mfma_f32_16x16x32_bf16 v[6:9], v[150:153], v[208:211], v[6:9]
	v_mfma_f32_16x16x32_bf16 v[2:5], v[158:161], v[208:211], v[2:5]
	s_barrier
	s_add_i32 s88, 0, 0x18000
	s_add_i32 s89, 0, 0x1c000
	v_add_u32_e32 v98, s88, v181
	v_add_u32_e32 v158, s89, v181
	ds_read_b128 v[78:81], v98
	ds_read_b128 v[82:85], v98 offset:1024
	ds_read_b128 v[94:97], v98 offset:2048
	ds_read_b128 v[98:101], v98 offset:3072
	ds_read_b128 v[146:149], v158
	ds_read_b128 v[150:153], v158 offset:1024
	ds_read_b128 v[154:157], v158 offset:2048
	ds_read_b128 v[158:161], v158 offset:3072
	s_add_u32 s38, s38, 0x20000
	s_addc_u32 s39, s39, 0
	s_mov_b32 m0, s79
	v_lshl_add_u64 v[218:219], s[38:39], 0, v[162:163]
	ds_read_b128 v[172:175], v183 offset:32768
	ds_read_b128 v[176:179], v183 offset:33792
	ds_read_b128 v[184:187], v183 offset:34816
	ds_read_b128 v[188:191], v183 offset:35840
	ds_read_b128 v[192:195], v183 offset:36864
	ds_read_b128 v[198:201], v183 offset:37888
	ds_read_b128 v[204:207], v183 offset:38912
	ds_read_b128 v[208:211], v183 offset:39936
	global_load_lds_dwordx4 v[218:219], off
	v_lshl_add_u64 v[218:219], s[38:39], 0, v[164:165]
	s_mov_b32 m0, s80
	s_nop 0
	global_load_lds_dwordx4 v[218:219], off
	s_waitcnt vmcnt(8)
	s_waitcnt lgkmcnt(0)
	s_barrier
	s_waitcnt lgkmcnt(0)
	v_mfma_f32_16x16x32_bf16 v[142:145], v[78:81], v[172:175], v[142:145]
	v_mfma_f32_16x16x32_bf16 v[138:141], v[94:97], v[172:175], v[138:141]
	v_mfma_f32_16x16x32_bf16 v[126:129], v[78:81], v[184:187], v[126:129]
	v_mfma_f32_16x16x32_bf16 v[122:125], v[94:97], v[184:187], v[122:125]
	v_mfma_f32_16x16x32_bf16 v[110:113], v[78:81], v[192:195], v[110:113]
	v_mfma_f32_16x16x32_bf16 v[106:109], v[94:97], v[192:195], v[106:109]
	v_mfma_f32_16x16x32_bf16 v[86:89], v[78:81], v[204:207], v[86:89]
	v_mfma_f32_16x16x32_bf16 v[74:77], v[94:97], v[204:207], v[74:77]
	v_mfma_f32_16x16x32_bf16 v[142:145], v[82:85], v[176:179], v[142:145]
	v_mfma_f32_16x16x32_bf16 v[138:141], v[98:101], v[176:179], v[138:141]
	v_mfma_f32_16x16x32_bf16 v[126:129], v[82:85], v[188:191], v[126:129]
	v_mfma_f32_16x16x32_bf16 v[122:125], v[98:101], v[188:191], v[122:125]
	v_mfma_f32_16x16x32_bf16 v[110:113], v[82:85], v[198:201], v[110:113]
	v_mfma_f32_16x16x32_bf16 v[106:109], v[98:101], v[198:201], v[106:109]
	v_mfma_f32_16x16x32_bf16 v[86:89], v[82:85], v[208:211], v[86:89]
	v_mfma_f32_16x16x32_bf16 v[74:77], v[98:101], v[208:211], v[74:77]
	v_mfma_f32_16x16x32_bf16 v[134:137], v[146:149], v[172:175], v[134:137]
	v_mfma_f32_16x16x32_bf16 v[130:133], v[154:157], v[172:175], v[130:133]
	v_mfma_f32_16x16x32_bf16 v[118:121], v[146:149], v[184:187], v[118:121]
	v_mfma_f32_16x16x32_bf16 v[114:117], v[154:157], v[184:187], v[114:117]
	v_mfma_f32_16x16x32_bf16 v[102:105], v[146:149], v[192:195], v[102:105]
	v_mfma_f32_16x16x32_bf16 v[90:93], v[154:157], v[192:195], v[90:93]
	v_mfma_f32_16x16x32_bf16 v[70:73], v[146:149], v[204:207], v[70:73]
	v_mfma_f32_16x16x32_bf16 v[66:69], v[154:157], v[204:207], v[66:69]
	v_mfma_f32_16x16x32_bf16 v[134:137], v[150:153], v[176:179], v[134:137]
	v_mfma_f32_16x16x32_bf16 v[130:133], v[158:161], v[176:179], v[130:133]
	v_mfma_f32_16x16x32_bf16 v[118:121], v[150:153], v[188:191], v[118:121]
	v_mfma_f32_16x16x32_bf16 v[114:117], v[158:161], v[188:191], v[114:117]
	v_mfma_f32_16x16x32_bf16 v[102:105], v[150:153], v[198:201], v[102:105]
	v_mfma_f32_16x16x32_bf16 v[90:93], v[158:161], v[198:201], v[90:93]
	v_mfma_f32_16x16x32_bf16 v[70:73], v[150:153], v[208:211], v[70:73]
	v_mfma_f32_16x16x32_bf16 v[66:69], v[158:161], v[208:211], v[66:69]
	s_barrier
; #define PG8_STAGE(bufoff, gbase, voff) do { _Pragma("unroll") for (int _i = 0; _i < 2; ++_i) \
;         __builtin_amdgcn_global_load_lds((const unsigned*)((const char*)(gbase) + (voff)[_i]), (LAS unsigned*)(lds + (bufoff) + ldsw + _i * 8192), 16, 0, 0); } while (0)
; #define PG8_LDA(dst, b, h) do { _Pragma("unroll") for (int m = 0; m < 4; ++m) _Pragma("unroll") for (int k = 0; k < 2; ++k) dst[m][k] = *(const LAS bf16x8*)(lds + PG8_SA(b, h) + aoff + m * 2048 + k * 1024); } while (0)
; #define PG8_MMA(ai, bj, At, Bt) do { __builtin_amdgcn_s_setprio(1); _Pragma("unroll") for (int m = 0; m < 4; ++m) _Pragma("unroll") for (int n = 0; n < 2; ++n) _Pragma("unroll") for (int k = 0; k < 2; ++k) \
;         acc[ai][bj][m][n] = __builtin_amdgcn_mfma_f32_16x16x32_bf16(Bt[n][k], At[m][k], acc[ai][bj][m][n], 0, 0, 0); __builtin_amdgcn_s_setprio(0); } while (0)
; #define PG8_WAIT_V(n) asm volatile("s_waitcnt vmcnt(" #n ")" ::: "memory")
; #define PG8_WAIT_L(n) asm volatile("s_waitcnt lgkmcnt(" #n ")" ::: "memory")
; #define PG8_BAR __builtin_amdgcn_s_barrier()
; #define PG8_SCHED __builtin_amdgcn_sched_barrier(0)
; #define PG8_LDA(dst, b, h) do { _Pragma("unroll") for (int m = 0; m < 4; ++m) _Pragma("unroll") for (int k = 0; k < 2; ++k) dst[m][k] = *(const LAS bf16x8*)(lds + PG8_SA(b, h) + aoff + m * 2048 + k * 1024); } while (0)
; #define PG8_MMA(ai, bj, At, Bt) do { __builtin_amdgcn_s_setprio(1); _Pragma("unroll") for (int m = 0; m < 4; ++m) _Pragma("unroll") for (int n = 0; n < 2; ++n) _Pragma("unroll") for (int k = 0; k < 2; ++k) \
;         acc[ai][bj][m][n] = __builtin_amdgcn_mfma_f32_16x16x32_bf16(Bt[n][k], At[m][k], acc[ai][bj][m][n], 0, 0, 0); __builtin_amdgcn_s_setprio(0); } while (0)
; #define PG8_WAIT_V(n) asm volatile("s_waitcnt vmcnt(" #n ")" ::: "memory")
; #define PG8_WAIT_L(n) asm volatile("s_waitcnt lgkmcnt(" #n ")" ::: "memory")
; #define PG8_BAR __builtin_amdgcn_s_barrier()
; template <class Epi, class Sched>
; DI void gemm_phase(LAS unsigned char* lds, const Gemm g, const Sched& S, const Epi& E) {
;     ...
;             PG8_LDA(At, 1, 1); PG8_STAGE(PG8_SB(1, 0), b3, voffB); PG8_STAGE(PG8_SB(1, 1), b3 + hstepB, voffB); PG8_STAGE(PG8_SA(1, 0), a3, voffA);
;             PG8_WAIT_V(8); PG8_WAIT_L(0); PG8_BAR; PG8_MMA(1, 0, At, B0); PG8_MMA(1, 1, At, B1); PG8_BAR; PG8_SCHED;
;         }
;         if (wr == 0) PG8_BAR;
	s_add_i32 s38, s88, s16
	v_lshl_add_u64 v[202:203], v[202:203], 0, s[26:27]
	s_mov_b32 m0, s38
	ds_read_b128 v[172:175], v183 offset:49152
	ds_read_b128 v[176:179], v183 offset:50176
	ds_read_b128 v[184:187], v183 offset:51200
	ds_read_b128 v[188:191], v183 offset:52224
	ds_read_b128 v[192:195], v183 offset:53248
	ds_read_b128 v[198:201], v183 offset:54272
	ds_read_b128 v[204:207], v183 offset:55296
	ds_read_b128 v[208:211], v183 offset:56320
	global_load_lds_dwordx4 v[202:203], off
	s_add_i32 m0, s38, 0x2000
	s_add_u32 s36, s36, 0x20080
	v_lshl_add_u64 v[202:203], v[212:213], 0, s[26:27]
	s_addc_u32 s37, s37, 0
	s_add_i32 s38, s89, s16
	global_load_lds_dwordx4 v[202:203], off
	v_lshl_add_u64 v[202:203], s[36:37], 0, v[0:1]
	s_mov_b32 m0, s38
	s_nop 0
	global_load_lds_dwordx4 v[202:203], off
	v_lshl_add_u64 v[202:203], s[36:37], 0, v[166:167]
	s_add_i32 m0, s38, 0x2000
	s_nop 0
	global_load_lds_dwordx4 v[202:203], off
	v_lshl_add_u64 v[202:203], v[214:215], 0, s[26:27]
	s_mov_b32 m0, s82
	s_nop 0
	global_load_lds_dwordx4 v[202:203], off
	v_lshl_add_u64 v[202:203], v[216:217], 0, s[26:27]
	s_mov_b32 m0, s83
	s_nop 0
	global_load_lds_dwordx4 v[202:203], off
	s_waitcnt vmcnt(8)
	s_waitcnt lgkmcnt(0)
	s_barrier
	s_waitcnt lgkmcnt(0)
	v_mfma_f32_16x16x32_bf16 v[62:65], v[78:81], v[172:175], v[62:65]
	v_mfma_f32_16x16x32_bf16 v[58:61], v[94:97], v[172:175], v[58:61]
	v_mfma_f32_16x16x32_bf16 v[46:49], v[78:81], v[184:187], v[46:49]
	v_mfma_f32_16x16x32_bf16 v[42:45], v[94:97], v[184:187], v[42:45]
	v_mfma_f32_16x16x32_bf16 v[30:33], v[78:81], v[192:195], v[30:33]
	v_mfma_f32_16x16x32_bf16 v[26:29], v[94:97], v[192:195], v[26:29]
	v_mfma_f32_16x16x32_bf16 v[14:17], v[78:81], v[204:207], v[14:17]
	v_mfma_f32_16x16x32_bf16 v[10:13], v[94:97], v[204:207], v[10:13]
	v_mfma_f32_16x16x32_bf16 v[62:65], v[82:85], v[176:179], v[62:65]
	v_mfma_f32_16x16x32_bf16 v[58:61], v[98:101], v[176:179], v[58:61]
	v_mfma_f32_16x16x32_bf16 v[46:49], v[82:85], v[188:191], v[46:49]
	v_mfma_f32_16x16x32_bf16 v[42:45], v[98:101], v[188:191], v[42:45]
	v_mfma_f32_16x16x32_bf16 v[30:33], v[82:85], v[198:201], v[30:33]
	v_mfma_f32_16x16x32_bf16 v[26:29], v[98:101], v[198:201], v[26:29]
	v_mfma_f32_16x16x32_bf16 v[14:17], v[82:85], v[208:211], v[14:17]
	v_mfma_f32_16x16x32_bf16 v[10:13], v[98:101], v[208:211], v[10:13]
	v_mfma_f32_16x16x32_bf16 v[54:57], v[146:149], v[172:175], v[54:57]
	v_mfma_f32_16x16x32_bf16 v[50:53], v[154:157], v[172:175], v[50:53]
	v_mfma_f32_16x16x32_bf16 v[38:41], v[146:149], v[184:187], v[38:41]
	v_mfma_f32_16x16x32_bf16 v[34:37], v[154:157], v[184:187], v[34:37]
	v_mfma_f32_16x16x32_bf16 v[22:25], v[146:149], v[192:195], v[22:25]
	v_mfma_f32_16x16x32_bf16 v[18:21], v[154:157], v[192:195], v[18:21]
	v_mfma_f32_16x16x32_bf16 v[6:9], v[146:149], v[204:207], v[6:9]
	v_mfma_f32_16x16x32_bf16 v[2:5], v[154:157], v[204:207], v[2:5]
	v_mfma_f32_16x16x32_bf16 v[54:57], v[150:153], v[176:179], v[54:57]
	v_mfma_f32_16x16x32_bf16 v[50:53], v[158:161], v[176:179], v[50:53]
	v_mfma_f32_16x16x32_bf16 v[38:41], v[150:153], v[188:191], v[38:41]
	v_mfma_f32_16x16x32_bf16 v[34:37], v[158:161], v[188:191], v[34:37]
	v_mfma_f32_16x16x32_bf16 v[22:25], v[150:153], v[198:201], v[22:25]
	v_mfma_f32_16x16x32_bf16 v[18:21], v[158:161], v[198:201], v[18:21]
	v_mfma_f32_16x16x32_bf16 v[6:9], v[150:153], v[208:211], v[6:9]
	v_mfma_f32_16x16x32_bf16 v[2:5], v[158:161], v[208:211], v[2:5]
	s_barrier
	s_add_i32 s87, s87, 2
	s_add_u32 s50, s50, 0x100
	s_addc_u32 s51, s51, 0
	s_add_u32 s71, s71, 0x100
	s_addc_u32 s73, s73, 0
	s_cmp_gt_u32 s87, 5
	s_cbranch_scc0 .LBB0_1253
	s_and_b64 vcc, exec, s[68:69]
	s_cbranch_vccz .LBB0_1256
	s_barrier

; #define PG8_STAGE(bufoff, gbase, voff) do { _Pragma("unroll") for (int _i = 0; _i < 2; ++_i) \
;         __builtin_amdgcn_global_load_lds((const unsigned*)((const char*)(gbase) + (voff)[_i]), (LAS unsigned*)(lds + (bufoff) + ldsw + _i * 8192), 16, 0, 0); } while (0)
; #define PG8_LDA(dst, b, h) do { _Pragma("unroll") for (int m = 0; m < 4; ++m) _Pragma("unroll") for (int k = 0; k < 2; ++k) dst[m][k] = *(const LAS bf16x8*)(lds + PG8_SA(b, h) + aoff + m * 2048 + k * 1024); } while (0)
; #define PG8_LDB(dst, b, h) do { _Pragma("unroll") for (int n = 0; n < 2; ++n) _Pragma("unroll") for (int k = 0; k < 2; ++k) dst[n][k] = *(const LAS bf16x8*)(lds + PG8_SB(b, h) + boff + n * 2048 + k * 1024); } while (0)
; #define PG8_MMA(ai, bj, At, Bt) do { __builtin_amdgcn_s_setprio(1); _Pragma("unroll") for (int m = 0; m < 4; ++m) _Pragma("unroll") for (int n = 0; n < 2; ++n) _Pragma("unroll") for (int k = 0; k < 2; ++k) \
;         acc[ai][bj][m][n] = __builtin_amdgcn_mfma_f32_16x16x32_bf16(Bt[n][k], At[m][k], acc[ai][bj][m][n], 0, 0, 0); __builtin_amdgcn_s_setprio(0); } while (0)
; #define PG8_WAIT_V(n) asm volatile("s_waitcnt vmcnt(" #n ")" ::: "memory")
; #define PG8_WAIT_L(n) asm volatile("s_waitcnt lgkmcnt(" #n ")" ::: "memory")
; #define PG8_BAR __builtin_amdgcn_s_barrier()
; #define PG8_SCHED __builtin_amdgcn_sched_barrier(0)
; #define PG8_LDA(dst, b, h) do { _Pragma("unroll") for (int m = 0; m < 4; ++m) _Pragma("unroll") for (int k = 0; k < 2; ++k) dst[m][k] = *(const LAS bf16x8*)(lds + PG8_SA(b, h) + aoff + m * 2048 + k * 1024); } while (0)
; #define PG8_LDB(dst, b, h) do { _Pragma("unroll") for (int n = 0; n < 2; ++n) _Pragma("unroll") for (int k = 0; k < 2; ++k) dst[n][k] = *(const LAS bf16x8*)(lds + PG8_SB(b, h) + boff + n * 2048 + k * 1024); } while (0)
; #define PG8_WAIT_V(n) asm volatile("s_waitcnt vmcnt(" #n ")" ::: "memory")
; template <class Epi, class Sched>
; DI void gemm_phase(LAS unsigned char* lds, const Gemm g, const Sched& S, const Epi& E) {
;     ...
;             PG8_LDB(B0, 0, 0); PG8_LDB(B1, 0, 1); PG8_SCHED; PG8_LDA(At, 0, 0); PG8_STAGE(PG8_SA(1, 1), a1 + hstepA, voffA);
;             PG8_WAIT_V(8); PG8_WAIT_L(0); PG8_BAR; PG8_MMA(0, 0, At, B0); PG8_MMA(0, 1, At, B1); PG8_BAR; PG8_SCHED;
;             PG8_LDA(At, 0, 1); PG8_STAGE(PG8_SB(0, 0), b2, voffB); PG8_STAGE(PG8_SB(0, 1), b2 + hstepB, voffB); PG8_STAGE(PG8_SA(0, 0), a2, voffA);
.LBB0_1365:
	s_add_u32 s36, s66, s44
	s_addc_u32 s37, s67, s45
	s_add_u32 s36, s36, 0x100
	s_addc_u32 s37, s37, 0
	s_add_u32 s80, s51, s44
	s_addc_u32 s81, s76, s45
	s_add_i32 s82, 0, 0x10000
	s_cmpk_eq_i32 s44, 0x700
	s_cselect_b32 s39, s71, s37
	s_cselect_b32 s38, s77, s36
	v_add_u32_e32 v149, s82, v145
	s_cselect_b32 s37, s69, s81
	s_cselect_b32 s36, s78, s80
	s_add_i32 s83, 0, 0x14000
	ds_read_b128 v[150:153], v149
	ds_read_b128 v[154:157], v149 offset:1024
	ds_read_b128 v[158:161], v149 offset:2048
	ds_read_b128 v[162:165], v149 offset:3072
	v_add_u32_e32 v149, s83, v145
	ds_read_b128 v[166:169], v149
	ds_read_b128 v[170:173], v149 offset:1024
	ds_read_b128 v[174:177], v149 offset:2048
	ds_read_b128 v[178:181], v149 offset:3072
	v_lshl_add_u64 v[194:195], v[140:141], 0, s[44:45]
	s_add_i32 m0, s17, 0xc000
	ds_read_b128 v[182:185], v148
	ds_read_b128 v[186:189], v148 offset:1024
	ds_read_b128 v[190:193], v148 offset:2048
	ds_read_b128 v[198:201], v148 offset:3072
	ds_read_b128 v[204:207], v148 offset:4096
	ds_read_b128 v[208:211], v148 offset:5120
	ds_read_b128 v[212:215], v148 offset:6144
	ds_read_b128 v[216:219], v148 offset:7168
	global_load_lds_dwordx4 v[194:195], off
	v_lshl_add_u64 v[194:195], v[142:143], 0, s[44:45]
	s_add_i32 m0, s17, 0xe000
	s_nop 0
	global_load_lds_dwordx4 v[194:195], off
	s_waitcnt vmcnt(8)
	s_waitcnt lgkmcnt(0)
	s_barrier
	s_waitcnt lgkmcnt(0)
	v_mfma_f32_16x16x32_bf16 v[126:129], v[150:153], v[182:185], v[126:129]
	v_mfma_f32_16x16x32_bf16 v[122:125], v[158:161], v[182:185], v[122:125]
	v_mfma_f32_16x16x32_bf16 v[118:121], v[150:153], v[190:193], v[118:121]
	v_mfma_f32_16x16x32_bf16 v[114:117], v[158:161], v[190:193], v[114:117]
	v_mfma_f32_16x16x32_bf16 v[110:113], v[150:153], v[204:207], v[110:113]
	v_mfma_f32_16x16x32_bf16 v[106:109], v[158:161], v[204:207], v[106:109]
	v_mfma_f32_16x16x32_bf16 v[102:105], v[150:153], v[212:215], v[102:105]
	v_mfma_f32_16x16x32_bf16 v[98:101], v[158:161], v[212:215], v[98:101]
	v_mfma_f32_16x16x32_bf16 v[126:129], v[154:157], v[186:189], v[126:129]
	v_mfma_f32_16x16x32_bf16 v[122:125], v[162:165], v[186:189], v[122:125]
	v_mfma_f32_16x16x32_bf16 v[118:121], v[154:157], v[198:201], v[118:121]
	v_mfma_f32_16x16x32_bf16 v[114:117], v[162:165], v[198:201], v[114:117]
	v_mfma_f32_16x16x32_bf16 v[110:113], v[154:157], v[208:211], v[110:113]
	v_mfma_f32_16x16x32_bf16 v[106:109], v[162:165], v[208:211], v[106:109]
	v_mfma_f32_16x16x32_bf16 v[102:105], v[154:157], v[216:219], v[102:105]
	v_mfma_f32_16x16x32_bf16 v[98:101], v[162:165], v[216:219], v[98:101]
	v_mfma_f32_16x16x32_bf16 v[94:97], v[166:169], v[182:185], v[94:97]
	v_mfma_f32_16x16x32_bf16 v[90:93], v[174:177], v[182:185], v[90:93]
	v_mfma_f32_16x16x32_bf16 v[86:89], v[166:169], v[190:193], v[86:89]
	v_mfma_f32_16x16x32_bf16 v[82:85], v[174:177], v[190:193], v[82:85]
	v_mfma_f32_16x16x32_bf16 v[78:81], v[166:169], v[204:207], v[78:81]
	v_mfma_f32_16x16x32_bf16 v[74:77], v[174:177], v[204:207], v[74:77]
	v_mfma_f32_16x16x32_bf16 v[70:73], v[166:169], v[212:215], v[70:73]
	v_mfma_f32_16x16x32_bf16 v[66:69], v[174:177], v[212:215], v[66:69]
	v_mfma_f32_16x16x32_bf16 v[94:97], v[170:173], v[186:189], v[94:97]
	v_mfma_f32_16x16x32_bf16 v[90:93], v[178:181], v[186:189], v[90:93]
	v_mfma_f32_16x16x32_bf16 v[86:89], v[170:173], v[198:201], v[86:89]
	v_mfma_f32_16x16x32_bf16 v[82:85], v[178:181], v[198:201], v[82:85]
	v_mfma_f32_16x16x32_bf16 v[78:81], v[170:173], v[208:211], v[78:81]
	v_mfma_f32_16x16x32_bf16 v[74:77], v[178:181], v[208:211], v[74:77]
	v_mfma_f32_16x16x32_bf16 v[70:73], v[170:173], v[216:219], v[70:73]
	v_mfma_f32_16x16x32_bf16 v[66:69], v[178:181], v[216:219], v[66:69]
	s_barrier
	s_add_i32 s80, s82, s16
	v_lshl_add_u64 v[194:195], s[36:37], 0, v[0:1]
	s_mov_b32 m0, s80
	ds_read_b128 v[182:185], v148 offset:16384
	ds_read_b128 v[186:189], v148 offset:17408
	ds_read_b128 v[190:193], v148 offset:18432
	ds_read_b128 v[198:201], v148 offset:19456
	ds_read_b128 v[204:207], v148 offset:20480
	ds_read_b128 v[208:211], v148 offset:21504
	ds_read_b128 v[212:215], v148 offset:22528
	ds_read_b128 v[216:219], v148 offset:23552
	global_load_lds_dwordx4 v[194:195], off
	s_add_i32 m0, s80, 0x2000
	s_add_u32 s80, s36, 0x40000
	v_lshl_add_u64 v[202:203], s[36:37], 0, v[134:135]
	s_addc_u32 s81, s37, 0
	s_add_i32 s82, s83, s16
	global_load_lds_dwordx4 v[202:203], off
	v_lshl_add_u64 v[220:221], s[80:81], 0, v[0:1]
	s_mov_b32 m0, s82
	v_lshl_add_u64 v[222:223], s[38:39], 0, v[132:133]
	global_load_lds_dwordx4 v[220:221], off
	v_lshl_add_u64 v[220:221], s[80:81], 0, v[134:135]
	s_add_i32 m0, s82, 0x2000
	s_nop 0
	global_load_lds_dwordx4 v[220:221], off
	v_lshl_add_u64 v[220:221], s[38:39], 0, v[130:131]
	s_mov_b32 m0, s17
	s_nop 0
	global_load_lds_dwordx4 v[220:221], off
	s_mov_b32 m0, s25
	s_nop 0
	global_load_lds_dwordx4 v[222:223], off
	s_waitcnt vmcnt(8)
	s_waitcnt lgkmcnt(0)
	s_barrier
; #define PG8_STAGE(bufoff, gbase, voff) do { _Pragma("unroll") for (int _i = 0; _i < 2; ++_i) \
;         __builtin_amdgcn_global_load_lds((const unsigned*)((const char*)(gbase) + (voff)[_i]), (LAS unsigned*)(lds + (bufoff) + ldsw + _i * 8192), 16, 0, 0); } while (0)
; #define PG8_LDA(dst, b, h) do { _Pragma("unroll") for (int m = 0; m < 4; ++m) _Pragma("unroll") for (int k = 0; k < 2; ++k) dst[m][k] = *(const LAS bf16x8*)(lds + PG8_SA(b, h) + aoff + m * 2048 + k * 1024); } while (0)
; #define PG8_LDB(dst, b, h) do { _Pragma("unroll") for (int n = 0; n < 2; ++n) _Pragma("unroll") for (int k = 0; k < 2; ++k) dst[n][k] = *(const LAS bf16x8*)(lds + PG8_SB(b, h) + boff + n * 2048 + k * 1024); } while (0)
; #define PG8_MMA(ai, bj, At, Bt) do { __builtin_amdgcn_s_setprio(1); _Pragma("unroll") for (int m = 0; m < 4; ++m) _Pragma("unroll") for (int n = 0; n < 2; ++n) _Pragma("unroll") for (int k = 0; k < 2; ++k) \
;         acc[ai][bj][m][n] = __builtin_amdgcn_mfma_f32_16x16x32_bf16(Bt[n][k], At[m][k], acc[ai][bj][m][n], 0, 0, 0); __builtin_amdgcn_s_setprio(0); } while (0)
; #define PG8_WAIT_V(n) asm volatile("s_waitcnt vmcnt(" #n ")" ::: "memory")
; #define PG8_WAIT_L(n) asm volatile("s_waitcnt lgkmcnt(" #n ")" ::: "memory")
; #define PG8_BAR __builtin_amdgcn_s_barrier()
; #define PG8_SCHED __builtin_amdgcn_sched_barrier(0)
; #define PG8_LDA(dst, b, h) do { _Pragma("unroll") for (int m = 0; m < 4; ++m) _Pragma("unroll") for (int k = 0; k < 2; ++k) dst[m][k] = *(const LAS bf16x8*)(lds + PG8_SA(b, h) + aoff + m * 2048 + k * 1024); } while (0)
; #define PG8_LDB(dst, b, h) do { _Pragma("unroll") for (int n = 0; n < 2; ++n) _Pragma("unroll") for (int k = 0; k < 2; ++k) dst[n][k] = *(const LAS bf16x8*)(lds + PG8_SB(b, h) + boff + n * 2048 + k * 1024); } while (0)
; #define PG8_WAIT_V(n) asm volatile("s_waitcnt vmcnt(" #n ")" ::: "memory")
; #define PG8_BAR __builtin_amdgcn_s_barrier()
; template <class Epi, class Sched>
; DI void gemm_phase(LAS unsigned char* lds, const Gemm g, const Sched& S, const Epi& E) {
;     ...
;             PG8_WAIT_V(8); PG8_WAIT_L(0); PG8_BAR; PG8_MMA(1, 0, At, B0); PG8_MMA(1, 1, At, B1); PG8_BAR; PG8_SCHED;
;             PG8_LDB(B0, 1, 0); PG8_LDB(B1, 1, 1); PG8_SCHED; PG8_LDA(At, 1, 0); PG8_STAGE(PG8_SA(0, 1), a2 + hstepA, voffA);
;             PG8_WAIT_V(8); PG8_WAIT_L(0); PG8_BAR; PG8_MMA(0, 0, At, B0); PG8_MMA(0, 1, At, B1); PG8_BAR; PG8_SCHED;
	s_waitcnt lgkmcnt(0)
	v_mfma_f32_16x16x32_bf16 v[62:65], v[150:153], v[182:185], v[62:65]
	v_mfma_f32_16x16x32_bf16 v[58:61], v[158:161], v[182:185], v[58:61]
	v_mfma_f32_16x16x32_bf16 v[54:57], v[150:153], v[190:193], v[54:57]
	v_mfma_f32_16x16x32_bf16 v[50:53], v[158:161], v[190:193], v[50:53]
	v_mfma_f32_16x16x32_bf16 v[46:49], v[150:153], v[204:207], v[46:49]
	v_mfma_f32_16x16x32_bf16 v[42:45], v[158:161], v[204:207], v[42:45]
	v_mfma_f32_16x16x32_bf16 v[38:41], v[150:153], v[212:215], v[38:41]
	v_mfma_f32_16x16x32_bf16 v[34:37], v[158:161], v[212:215], v[34:37]
	v_mfma_f32_16x16x32_bf16 v[62:65], v[154:157], v[186:189], v[62:65]
	v_mfma_f32_16x16x32_bf16 v[58:61], v[162:165], v[186:189], v[58:61]
	v_mfma_f32_16x16x32_bf16 v[54:57], v[154:157], v[198:201], v[54:57]
	v_mfma_f32_16x16x32_bf16 v[50:53], v[162:165], v[198:201], v[50:53]
	v_mfma_f32_16x16x32_bf16 v[46:49], v[154:157], v[208:211], v[46:49]
	v_mfma_f32_16x16x32_bf16 v[42:45], v[162:165], v[208:211], v[42:45]
	v_mfma_f32_16x16x32_bf16 v[38:41], v[154:157], v[216:219], v[38:41]
	v_mfma_f32_16x16x32_bf16 v[34:37], v[162:165], v[216:219], v[34:37]
	v_mfma_f32_16x16x32_bf16 v[30:33], v[166:169], v[182:185], v[30:33]
	v_mfma_f32_16x16x32_bf16 v[26:29], v[174:177], v[182:185], v[26:29]
	v_mfma_f32_16x16x32_bf16 v[22:25], v[166:169], v[190:193], v[22:25]
	v_mfma_f32_16x16x32_bf16 v[18:21], v[174:177], v[190:193], v[18:21]
	v_mfma_f32_16x16x32_bf16 v[14:17], v[166:169], v[204:207], v[14:17]
	v_mfma_f32_16x16x32_bf16 v[10:13], v[174:177], v[204:207], v[10:13]
	v_mfma_f32_16x16x32_bf16 v[6:9], v[166:169], v[212:215], v[6:9]
	v_mfma_f32_16x16x32_bf16 v[2:5], v[174:177], v[212:215], v[2:5]
	v_mfma_f32_16x16x32_bf16 v[30:33], v[170:173], v[186:189], v[30:33]
	v_mfma_f32_16x16x32_bf16 v[26:29], v[178:181], v[186:189], v[26:29]
	v_mfma_f32_16x16x32_bf16 v[22:25], v[170:173], v[198:201], v[22:25]
	v_mfma_f32_16x16x32_bf16 v[18:21], v[178:181], v[198:201], v[18:21]
	v_mfma_f32_16x16x32_bf16 v[14:17], v[170:173], v[208:211], v[14:17]
	v_mfma_f32_16x16x32_bf16 v[10:13], v[178:181], v[208:211], v[10:13]
	v_mfma_f32_16x16x32_bf16 v[6:9], v[170:173], v[216:219], v[6:9]
	v_mfma_f32_16x16x32_bf16 v[2:5], v[178:181], v[216:219], v[2:5]
	s_barrier
	s_add_i32 s80, 0, 0x18000
	v_add_u32_e32 v149, s80, v145
	s_add_i32 s81, 0, 0x1c000
	ds_read_b128 v[150:153], v149
	ds_read_b128 v[154:157], v149 offset:1024
	ds_read_b128 v[158:161], v149 offset:2048
	ds_read_b128 v[162:165], v149 offset:3072
	v_add_u32_e32 v149, s81, v145
	ds_read_b128 v[166:169], v149
	ds_read_b128 v[170:173], v149 offset:1024
	ds_read_b128 v[174:177], v149 offset:2048
	ds_read_b128 v[178:181], v149 offset:3072
	s_add_u32 s38, s38, 0x40000
	s_addc_u32 s39, s39, 0
	s_mov_b32 m0, s28
	v_lshl_add_u64 v[224:225], s[38:39], 0, v[130:131]
	ds_read_b128 v[182:185], v148 offset:32768
	ds_read_b128 v[186:189], v148 offset:33792
	ds_read_b128 v[190:193], v148 offset:34816
	ds_read_b128 v[198:201], v148 offset:35840
	ds_read_b128 v[204:207], v148 offset:36864
	ds_read_b128 v[208:211], v148 offset:37888
	ds_read_b128 v[212:215], v148 offset:38912
	ds_read_b128 v[216:219], v148 offset:39936
	global_load_lds_dwordx4 v[224:225], off
	v_lshl_add_u64 v[224:225], s[38:39], 0, v[132:133]
	s_mov_b32 m0, s31
	s_nop 0
	global_load_lds_dwordx4 v[224:225], off
	s_waitcnt vmcnt(8)
	s_waitcnt lgkmcnt(0)
	s_barrier
	s_waitcnt lgkmcnt(0)
	v_mfma_f32_16x16x32_bf16 v[126:129], v[150:153], v[182:185], v[126:129]
	v_mfma_f32_16x16x32_bf16 v[122:125], v[158:161], v[182:185], v[122:125]
	v_mfma_f32_16x16x32_bf16 v[118:121], v[150:153], v[190:193], v[118:121]
	v_mfma_f32_16x16x32_bf16 v[114:117], v[158:161], v[190:193], v[114:117]
	v_mfma_f32_16x16x32_bf16 v[110:113], v[150:153], v[204:207], v[110:113]
	v_mfma_f32_16x16x32_bf16 v[106:109], v[158:161], v[204:207], v[106:109]
	v_mfma_f32_16x16x32_bf16 v[102:105], v[150:153], v[212:215], v[102:105]
	v_mfma_f32_16x16x32_bf16 v[98:101], v[158:161], v[212:215], v[98:101]
	v_mfma_f32_16x16x32_bf16 v[126:129], v[154:157], v[186:189], v[126:129]
	v_mfma_f32_16x16x32_bf16 v[122:125], v[162:165], v[186:189], v[122:125]
	v_mfma_f32_16x16x32_bf16 v[118:121], v[154:157], v[198:201], v[118:121]
	v_mfma_f32_16x16x32_bf16 v[114:117], v[162:165], v[198:201], v[114:117]
	v_mfma_f32_16x16x32_bf16 v[110:113], v[154:157], v[208:211], v[110:113]
	v_mfma_f32_16x16x32_bf16 v[106:109], v[162:165], v[208:211], v[106:109]
	v_mfma_f32_16x16x32_bf16 v[102:105], v[154:157], v[216:219], v[102:105]
	v_mfma_f32_16x16x32_bf16 v[98:101], v[162:165], v[216:219], v[98:101]
	v_mfma_f32_16x16x32_bf16 v[94:97], v[166:169], v[182:185], v[94:97]
	v_mfma_f32_16x16x32_bf16 v[90:93], v[174:177], v[182:185], v[90:93]
	v_mfma_f32_16x16x32_bf16 v[86:89], v[166:169], v[190:193], v[86:89]
	v_mfma_f32_16x16x32_bf16 v[82:85], v[174:177], v[190:193], v[82:85]
	v_mfma_f32_16x16x32_bf16 v[78:81], v[166:169], v[204:207], v[78:81]
	v_mfma_f32_16x16x32_bf16 v[74:77], v[174:177], v[204:207], v[74:77]
	v_mfma_f32_16x16x32_bf16 v[70:73], v[166:169], v[212:215], v[70:73]
	v_mfma_f32_16x16x32_bf16 v[66:69], v[174:177], v[212:215], v[66:69]
	v_mfma_f32_16x16x32_bf16 v[94:97], v[170:173], v[186:189], v[94:97]
	v_mfma_f32_16x16x32_bf16 v[90:93], v[178:181], v[186:189], v[90:93]
	v_mfma_f32_16x16x32_bf16 v[86:89], v[170:173], v[198:201], v[86:89]
	v_mfma_f32_16x16x32_bf16 v[82:85], v[178:181], v[198:201], v[82:85]
	v_mfma_f32_16x16x32_bf16 v[78:81], v[170:173], v[208:211], v[78:81]
	v_mfma_f32_16x16x32_bf16 v[74:77], v[178:181], v[208:211], v[74:77]
	v_mfma_f32_16x16x32_bf16 v[70:73], v[170:173], v[216:219], v[70:73]
	v_mfma_f32_16x16x32_bf16 v[66:69], v[178:181], v[216:219], v[66:69]
	s_barrier
; #define PG8_STAGE(bufoff, gbase, voff) do { _Pragma("unroll") for (int _i = 0; _i < 2; ++_i) \
;         __builtin_amdgcn_global_load_lds((const unsigned*)((const char*)(gbase) + (voff)[_i]), (LAS unsigned*)(lds + (bufoff) + ldsw + _i * 8192), 16, 0, 0); } while (0)
; #define PG8_LDA(dst, b, h) do { _Pragma("unroll") for (int m = 0; m < 4; ++m) _Pragma("unroll") for (int k = 0; k < 2; ++k) dst[m][k] = *(const LAS bf16x8*)(lds + PG8_SA(b, h) + aoff + m * 2048 + k * 1024); } while (0)
; #define PG8_MMA(ai, bj, At, Bt) do { __builtin_amdgcn_s_setprio(1); _Pragma("unroll") for (int m = 0; m < 4; ++m) _Pragma("unroll") for (int n = 0; n < 2; ++n) _Pragma("unroll") for (int k = 0; k < 2; ++k) \
;         acc[ai][bj][m][n] = __builtin_amdgcn_mfma_f32_16x16x32_bf16(Bt[n][k], At[m][k], acc[ai][bj][m][n], 0, 0, 0); __builtin_amdgcn_s_setprio(0); } while (0)
; #define PG8_WAIT_V(n) asm volatile("s_waitcnt vmcnt(" #n ")" ::: "memory")
; #define PG8_WAIT_L(n) asm volatile("s_waitcnt lgkmcnt(" #n ")" ::: "memory")
; #define PG8_BAR __builtin_amdgcn_s_barrier()
; #define PG8_SCHED __builtin_amdgcn_sched_barrier(0)
; #define PG8_LDA(dst, b, h) do { _Pragma("unroll") for (int m = 0; m < 4; ++m) _Pragma("unroll") for (int k = 0; k < 2; ++k) dst[m][k] = *(const LAS bf16x8*)(lds + PG8_SA(b, h) + aoff + m * 2048 + k * 1024); } while (0)
; #define PG8_MMA(ai, bj, At, Bt) do { __builtin_amdgcn_s_setprio(1); _Pragma("unroll") for (int m = 0; m < 4; ++m) _Pragma("unroll") for (int n = 0; n < 2; ++n) _Pragma("unroll") for (int k = 0; k < 2; ++k) \
;         acc[ai][bj][m][n] = __builtin_amdgcn_mfma_f32_16x16x32_bf16(Bt[n][k], At[m][k], acc[ai][bj][m][n], 0, 0, 0); __builtin_amdgcn_s_setprio(0); } while (0)
; #define PG8_WAIT_V(n) asm volatile("s_waitcnt vmcnt(" #n ")" ::: "memory")
; #define PG8_WAIT_L(n) asm volatile("s_waitcnt lgkmcnt(" #n ")" ::: "memory")
; #define PG8_BAR __builtin_amdgcn_s_barrier()
; template <class Epi, class Sched>
; DI void gemm_phase(LAS unsigned char* lds, const Gemm g, const Sched& S, const Epi& E) {
;     ...
;             PG8_LDA(At, 1, 1); PG8_STAGE(PG8_SB(1, 0), b3, voffB); PG8_STAGE(PG8_SB(1, 1), b3 + hstepB, voffB); PG8_STAGE(PG8_SA(1, 0), a3, voffA);
;             PG8_WAIT_V(8); PG8_WAIT_L(0); PG8_BAR; PG8_MMA(1, 0, At, B0); PG8_MMA(1, 1, At, B1); PG8_BAR; PG8_SCHED;
;         }
;         if (wr == 0) PG8_BAR;
	s_add_i32 s38, s80, s16
	v_lshl_add_u64 v[194:195], v[194:195], 0, s[26:27]
	s_mov_b32 m0, s38
	ds_read_b128 v[182:185], v148 offset:49152
	ds_read_b128 v[186:189], v148 offset:50176
	ds_read_b128 v[190:193], v148 offset:51200
	ds_read_b128 v[198:201], v148 offset:52224
	ds_read_b128 v[204:207], v148 offset:53248
	ds_read_b128 v[208:211], v148 offset:54272
	ds_read_b128 v[212:215], v148 offset:55296
	ds_read_b128 v[216:219], v148 offset:56320
	global_load_lds_dwordx4 v[194:195], off
	s_add_i32 m0, s38, 0x2000
	s_add_u32 s36, s36, 0x40080
	v_lshl_add_u64 v[194:195], v[202:203], 0, s[26:27]
	s_addc_u32 s37, s37, 0
	s_add_i32 s38, s81, s16
	global_load_lds_dwordx4 v[194:195], off
	v_lshl_add_u64 v[194:195], s[36:37], 0, v[0:1]
	s_mov_b32 m0, s38
	s_nop 0
	global_load_lds_dwordx4 v[194:195], off
	v_lshl_add_u64 v[194:195], s[36:37], 0, v[134:135]
	s_add_i32 m0, s38, 0x2000
	s_nop 0
	global_load_lds_dwordx4 v[194:195], off
	v_lshl_add_u64 v[194:195], v[220:221], 0, s[26:27]
	s_mov_b32 m0, s40
	s_nop 0
	global_load_lds_dwordx4 v[194:195], off
	v_lshl_add_u64 v[194:195], v[222:223], 0, s[26:27]
	s_mov_b32 m0, s41
	s_nop 0
	global_load_lds_dwordx4 v[194:195], off
	s_waitcnt vmcnt(8)
	s_waitcnt lgkmcnt(0)
	s_barrier
	s_waitcnt lgkmcnt(0)
	v_mfma_f32_16x16x32_bf16 v[62:65], v[150:153], v[182:185], v[62:65]
	v_mfma_f32_16x16x32_bf16 v[58:61], v[158:161], v[182:185], v[58:61]
	v_mfma_f32_16x16x32_bf16 v[54:57], v[150:153], v[190:193], v[54:57]
	v_mfma_f32_16x16x32_bf16 v[50:53], v[158:161], v[190:193], v[50:53]
	v_mfma_f32_16x16x32_bf16 v[46:49], v[150:153], v[204:207], v[46:49]
	v_mfma_f32_16x16x32_bf16 v[42:45], v[158:161], v[204:207], v[42:45]
	v_mfma_f32_16x16x32_bf16 v[38:41], v[150:153], v[212:215], v[38:41]
	v_mfma_f32_16x16x32_bf16 v[34:37], v[158:161], v[212:215], v[34:37]
	v_mfma_f32_16x16x32_bf16 v[62:65], v[154:157], v[186:189], v[62:65]
	v_mfma_f32_16x16x32_bf16 v[58:61], v[162:165], v[186:189], v[58:61]
	v_mfma_f32_16x16x32_bf16 v[54:57], v[154:157], v[198:201], v[54:57]
	v_mfma_f32_16x16x32_bf16 v[50:53], v[162:165], v[198:201], v[50:53]
	v_mfma_f32_16x16x32_bf16 v[46:49], v[154:157], v[208:211], v[46:49]
	v_mfma_f32_16x16x32_bf16 v[42:45], v[162:165], v[208:211], v[42:45]
	v_mfma_f32_16x16x32_bf16 v[38:41], v[154:157], v[216:219], v[38:41]
	v_mfma_f32_16x16x32_bf16 v[34:37], v[162:165], v[216:219], v[34:37]
	v_mfma_f32_16x16x32_bf16 v[30:33], v[166:169], v[182:185], v[30:33]
	v_mfma_f32_16x16x32_bf16 v[26:29], v[174:177], v[182:185], v[26:29]
	v_mfma_f32_16x16x32_bf16 v[22:25], v[166:169], v[190:193], v[22:25]
	v_mfma_f32_16x16x32_bf16 v[18:21], v[174:177], v[190:193], v[18:21]
	v_mfma_f32_16x16x32_bf16 v[14:17], v[166:169], v[204:207], v[14:17]
	v_mfma_f32_16x16x32_bf16 v[10:13], v[174:177], v[204:207], v[10:13]
	v_mfma_f32_16x16x32_bf16 v[6:9], v[166:169], v[212:215], v[6:9]
	v_mfma_f32_16x16x32_bf16 v[2:5], v[174:177], v[212:215], v[2:5]
	v_mfma_f32_16x16x32_bf16 v[30:33], v[170:173], v[186:189], v[30:33]
	v_mfma_f32_16x16x32_bf16 v[26:29], v[178:181], v[186:189], v[26:29]
	v_mfma_f32_16x16x32_bf16 v[22:25], v[170:173], v[198:201], v[22:25]
	v_mfma_f32_16x16x32_bf16 v[18:21], v[178:181], v[198:201], v[18:21]
	v_mfma_f32_16x16x32_bf16 v[14:17], v[170:173], v[208:211], v[14:17]
	v_mfma_f32_16x16x32_bf16 v[10:13], v[178:181], v[208:211], v[10:13]
	v_mfma_f32_16x16x32_bf16 v[6:9], v[170:173], v[216:219], v[6:9]
	v_mfma_f32_16x16x32_bf16 v[2:5], v[178:181], v[216:219], v[2:5]
	s_barrier
	s_add_i32 s79, s79, 2
	s_add_u32 s44, s44, 0x100
	s_addc_u32 s45, s45, 0
	s_cmp_gt_u32 s79, 13
	s_cbranch_scc0 .LBB0_1365
	s_and_b64 vcc, exec, s[64:65]
	s_cbranch_vccz .LBB0_1368
	s_barrier

; #define PG8_STAGE(bufoff, gbase, voff) do { _Pragma("unroll") for (int _i = 0; _i < 2; ++_i) \
;         __builtin_amdgcn_global_load_lds((const unsigned*)((const char*)(gbase) + (voff)[_i]), (LAS unsigned*)(lds + (bufoff) + ldsw + _i * 8192), 16, 0, 0); } while (0)
; #define PG8_LDA(dst, b, h) do { _Pragma("unroll") for (int m = 0; m < 4; ++m) _Pragma("unroll") for (int k = 0; k < 2; ++k) dst[m][k] = *(const LAS bf16x8*)(lds + PG8_SA(b, h) + aoff + m * 2048 + k * 1024); } while (0)
; #define PG8_LDB(dst, b, h) do { _Pragma("unroll") for (int n = 0; n < 2; ++n) _Pragma("unroll") for (int k = 0; k < 2; ++k) dst[n][k] = *(const LAS bf16x8*)(lds + PG8_SB(b, h) + boff + n * 2048 + k * 1024); } while (0)
; #define PG8_MMA(ai, bj, At, Bt) do { __builtin_amdgcn_s_setprio(1); _Pragma("unroll") for (int m = 0; m < 4; ++m) _Pragma("unroll") for (int n = 0; n < 2; ++n) _Pragma("unroll") for (int k = 0; k < 2; ++k) \
;         acc[ai][bj][m][n] = __builtin_amdgcn_mfma_f32_16x16x32_bf16(Bt[n][k], At[m][k], acc[ai][bj][m][n], 0, 0, 0); __builtin_amdgcn_s_setprio(0); } while (0)
; #define PG8_WAIT_V(n) asm volatile("s_waitcnt vmcnt(" #n ")" ::: "memory")
; #define PG8_WAIT_L(n) asm volatile("s_waitcnt lgkmcnt(" #n ")" ::: "memory")
; #define PG8_BAR __builtin_amdgcn_s_barrier()
; #define PG8_SCHED __builtin_amdgcn_sched_barrier(0)
; #define PG8_LDA(dst, b, h) do { _Pragma("unroll") for (int m = 0; m < 4; ++m) _Pragma("unroll") for (int k = 0; k < 2; ++k) dst[m][k] = *(const LAS bf16x8*)(lds + PG8_SA(b, h) + aoff + m * 2048 + k * 1024); } while (0)
; #define PG8_LDB(dst, b, h) do { _Pragma("unroll") for (int n = 0; n < 2; ++n) _Pragma("unroll") for (int k = 0; k < 2; ++k) dst[n][k] = *(const LAS bf16x8*)(lds + PG8_SB(b, h) + boff + n * 2048 + k * 1024); } while (0)
; #define PG8_WAIT_V(n) asm volatile("s_waitcnt vmcnt(" #n ")" ::: "memory")
; template <class Epi, class Sched>
; DI void gemm_phase(LAS unsigned char* lds, const Gemm g, const Sched& S, const Epi& E) {
;     ...
;             PG8_LDB(B0, 0, 0); PG8_LDB(B1, 0, 1); PG8_SCHED; PG8_LDA(At, 0, 0); PG8_STAGE(PG8_SA(1, 1), a1 + hstepA, voffA);
;             PG8_WAIT_V(8); PG8_WAIT_L(0); PG8_BAR; PG8_MMA(0, 0, At, B0); PG8_MMA(0, 1, At, B1); PG8_BAR; PG8_SCHED;
;             PG8_LDA(At, 0, 1); PG8_STAGE(PG8_SB(0, 0), b2, voffB); PG8_STAGE(PG8_SB(0, 1), b2 + hstepB, voffB); PG8_STAGE(PG8_SA(0, 0), a2, voffA);
.LBB0_1440:
	s_add_u32 s36, s50, 0xfff00080
	s_addc_u32 s37, s51, -1
	s_add_i32 s88, 0, 0x10000
	s_cmp_eq_u32 s87, 60
	s_cselect_b32 s39, s28, s37
	s_cselect_b32 s38, s40, s36
	s_cselect_b32 s37, s41, s73
	s_cselect_b32 s36, s45, s71
	s_add_i32 s90, 0, 0x14000
	v_add_u32_e32 v98, s88, v181
	v_add_u32_e32 v158, s90, v181
	ds_read_b128 v[78:81], v98
	ds_read_b128 v[82:85], v98 offset:1024
	ds_read_b128 v[94:97], v98 offset:2048
	ds_read_b128 v[98:101], v98 offset:3072
	ds_read_b128 v[146:149], v158
	ds_read_b128 v[150:153], v158 offset:1024
	ds_read_b128 v[154:157], v158 offset:2048
	ds_read_b128 v[158:161], v158 offset:3072
	v_lshl_add_u64 v[202:203], s[50:51], 0, v[168:169]
	s_add_i32 m0, s17, 0xc000
	ds_read_b128 v[172:175], v183
	ds_read_b128 v[176:179], v183 offset:1024
	ds_read_b128 v[184:187], v183 offset:2048
	ds_read_b128 v[188:191], v183 offset:3072
	ds_read_b128 v[192:195], v183 offset:4096
	ds_read_b128 v[198:201], v183 offset:5120
	ds_read_b128 v[204:207], v183 offset:6144
	ds_read_b128 v[208:211], v183 offset:7168
	global_load_lds_dwordx4 v[202:203], off
	v_lshl_add_u64 v[202:203], s[50:51], 0, v[170:171]
	s_add_i32 m0, s17, 0xe000
	s_nop 0
	global_load_lds_dwordx4 v[202:203], off
	s_waitcnt vmcnt(8)
	s_waitcnt lgkmcnt(0)
	s_barrier
	s_waitcnt lgkmcnt(0)
	v_mfma_f32_16x16x32_bf16 v[142:145], v[78:81], v[172:175], v[142:145]
	v_mfma_f32_16x16x32_bf16 v[138:141], v[94:97], v[172:175], v[138:141]
	v_mfma_f32_16x16x32_bf16 v[126:129], v[78:81], v[184:187], v[126:129]
	v_mfma_f32_16x16x32_bf16 v[122:125], v[94:97], v[184:187], v[122:125]
	v_mfma_f32_16x16x32_bf16 v[110:113], v[78:81], v[192:195], v[110:113]
	v_mfma_f32_16x16x32_bf16 v[106:109], v[94:97], v[192:195], v[106:109]
	v_mfma_f32_16x16x32_bf16 v[86:89], v[78:81], v[204:207], v[86:89]
	v_mfma_f32_16x16x32_bf16 v[74:77], v[94:97], v[204:207], v[74:77]
	v_mfma_f32_16x16x32_bf16 v[142:145], v[82:85], v[176:179], v[142:145]
	v_mfma_f32_16x16x32_bf16 v[138:141], v[98:101], v[176:179], v[138:141]
	v_mfma_f32_16x16x32_bf16 v[126:129], v[82:85], v[188:191], v[126:129]
	v_mfma_f32_16x16x32_bf16 v[122:125], v[98:101], v[188:191], v[122:125]
	v_mfma_f32_16x16x32_bf16 v[110:113], v[82:85], v[198:201], v[110:113]
	v_mfma_f32_16x16x32_bf16 v[106:109], v[98:101], v[198:201], v[106:109]
	v_mfma_f32_16x16x32_bf16 v[86:89], v[82:85], v[208:211], v[86:89]
	v_mfma_f32_16x16x32_bf16 v[74:77], v[98:101], v[208:211], v[74:77]
	v_mfma_f32_16x16x32_bf16 v[134:137], v[146:149], v[172:175], v[134:137]
	v_mfma_f32_16x16x32_bf16 v[130:133], v[154:157], v[172:175], v[130:133]
	v_mfma_f32_16x16x32_bf16 v[118:121], v[146:149], v[184:187], v[118:121]
	v_mfma_f32_16x16x32_bf16 v[114:117], v[154:157], v[184:187], v[114:117]
	v_mfma_f32_16x16x32_bf16 v[102:105], v[146:149], v[192:195], v[102:105]
	v_mfma_f32_16x16x32_bf16 v[90:93], v[154:157], v[192:195], v[90:93]
	v_mfma_f32_16x16x32_bf16 v[70:73], v[146:149], v[204:207], v[70:73]
	v_mfma_f32_16x16x32_bf16 v[66:69], v[154:157], v[204:207], v[66:69]
	v_mfma_f32_16x16x32_bf16 v[134:137], v[150:153], v[176:179], v[134:137]
	v_mfma_f32_16x16x32_bf16 v[130:133], v[158:161], v[176:179], v[130:133]
	v_mfma_f32_16x16x32_bf16 v[118:121], v[150:153], v[188:191], v[118:121]
	v_mfma_f32_16x16x32_bf16 v[114:117], v[158:161], v[188:191], v[114:117]
	v_mfma_f32_16x16x32_bf16 v[102:105], v[150:153], v[198:201], v[102:105]
	v_mfma_f32_16x16x32_bf16 v[90:93], v[158:161], v[198:201], v[90:93]
	v_mfma_f32_16x16x32_bf16 v[70:73], v[150:153], v[208:211], v[70:73]
	v_mfma_f32_16x16x32_bf16 v[66:69], v[158:161], v[208:211], v[66:69]
	s_barrier
	s_add_i32 s88, s88, s16
	v_lshl_add_u64 v[202:203], s[36:37], 0, v[0:1]
	s_mov_b32 m0, s88
	ds_read_b128 v[172:175], v183 offset:16384
	ds_read_b128 v[176:179], v183 offset:17408
	ds_read_b128 v[184:187], v183 offset:18432
	ds_read_b128 v[188:191], v183 offset:19456
	ds_read_b128 v[192:195], v183 offset:20480
	ds_read_b128 v[198:201], v183 offset:21504
	ds_read_b128 v[204:207], v183 offset:22528
	ds_read_b128 v[208:211], v183 offset:23552
	global_load_lds_dwordx4 v[202:203], off
	s_add_i32 m0, s88, 0x2000
	s_add_u32 s88, s36, 0x100000
	v_lshl_add_u64 v[212:213], s[36:37], 0, v[166:167]
	s_addc_u32 s89, s37, 0
	s_add_i32 s90, s90, s16
	global_load_lds_dwordx4 v[212:213], off
	v_lshl_add_u64 v[214:215], s[88:89], 0, v[0:1]
	s_mov_b32 m0, s90
	v_lshl_add_u64 v[216:217], s[38:39], 0, v[164:165]
	global_load_lds_dwordx4 v[214:215], off
	v_lshl_add_u64 v[214:215], s[88:89], 0, v[166:167]
	s_add_i32 m0, s90, 0x2000
	s_nop 0
	global_load_lds_dwordx4 v[214:215], off
	v_lshl_add_u64 v[214:215], s[38:39], 0, v[162:163]
	s_mov_b32 m0, s17
	s_nop 0
	global_load_lds_dwordx4 v[214:215], off
	s_mov_b32 m0, s25
	s_nop 0
	global_load_lds_dwordx4 v[216:217], off
	s_waitcnt vmcnt(8)
	s_waitcnt lgkmcnt(0)
	s_barrier
; #define PG8_STAGE(bufoff, gbase, voff) do { _Pragma("unroll") for (int _i = 0; _i < 2; ++_i) \
;         __builtin_amdgcn_global_load_lds((const unsigned*)((const char*)(gbase) + (voff)[_i]), (LAS unsigned*)(lds + (bufoff) + ldsw + _i * 8192), 16, 0, 0); } while (0)
; #define PG8_LDA(dst, b, h) do { _Pragma("unroll") for (int m = 0; m < 4; ++m) _Pragma("unroll") for (int k = 0; k < 2; ++k) dst[m][k] = *(const LAS bf16x8*)(lds + PG8_SA(b, h) + aoff + m * 2048 + k * 1024); } while (0)
; #define PG8_LDB(dst, b, h) do { _Pragma("unroll") for (int n = 0; n < 2; ++n) _Pragma("unroll") for (int k = 0; k < 2; ++k) dst[n][k] = *(const LAS bf16x8*)(lds + PG8_SB(b, h) + boff + n * 2048 + k * 1024); } while (0)
; #define PG8_MMA(ai, bj, At, Bt) do { __builtin_amdgcn_s_setprio(1); _Pragma("unroll") for (int m = 0; m < 4; ++m) _Pragma("unroll") for (int n = 0; n < 2; ++n) _Pragma("unroll") for (int k = 0; k < 2; ++k) \
;         acc[ai][bj][m][n] = __builtin_amdgcn_mfma_f32_16x16x32_bf16(Bt[n][k], At[m][k], acc[ai][bj][m][n], 0, 0, 0); __builtin_amdgcn_s_setprio(0); } while (0)
; #define PG8_WAIT_V(n) asm volatile("s_waitcnt vmcnt(" #n ")" ::: "memory")
; #define PG8_WAIT_L(n) asm volatile("s_waitcnt lgkmcnt(" #n ")" ::: "memory")
; #define PG8_BAR __builtin_amdgcn_s_barrier()
; #define PG8_SCHED __builtin_amdgcn_sched_barrier(0)
; #define PG8_LDA(dst, b, h) do { _Pragma("unroll") for (int m = 0; m < 4; ++m) _Pragma("unroll") for (int k = 0; k < 2; ++k) dst[m][k] = *(const LAS bf16x8*)(lds + PG8_SA(b, h) + aoff + m * 2048 + k * 1024); } while (0)
; #define PG8_LDB(dst, b, h) do { _Pragma("unroll") for (int n = 0; n < 2; ++n) _Pragma("unroll") for (int k = 0; k < 2; ++k) dst[n][k] = *(const LAS bf16x8*)(lds + PG8_SB(b, h) + boff + n * 2048 + k * 1024); } while (0)
; #define PG8_WAIT_V(n) asm volatile("s_waitcnt vmcnt(" #n ")" ::: "memory")
; #define PG8_BAR __builtin_amdgcn_s_barrier()
; template <class Epi, class Sched>
; DI void gemm_phase(LAS unsigned char* lds, const Gemm g, const Sched& S, const Epi& E) {
;     ...
;             PG8_WAIT_V(8); PG8_WAIT_L(0); PG8_BAR; PG8_MMA(1, 0, At, B0); PG8_MMA(1, 1, At, B1); PG8_BAR; PG8_SCHED;
;             PG8_LDB(B0, 1, 0); PG8_LDB(B1, 1, 1); PG8_SCHED; PG8_LDA(At, 1, 0); PG8_STAGE(PG8_SA(0, 1), a2 + hstepA, voffA);
;             PG8_WAIT_V(8); PG8_WAIT_L(0); PG8_BAR; PG8_MMA(0, 0, At, B0); PG8_MMA(0, 1, At, B1); PG8_BAR; PG8_SCHED;
	s_waitcnt lgkmcnt(0)
	v_mfma_f32_16x16x32_bf16 v[62:65], v[78:81], v[172:175], v[62:65]
	v_mfma_f32_16x16x32_bf16 v[58:61], v[94:97], v[172:175], v[58:61]
	v_mfma_f32_16x16x32_bf16 v[46:49], v[78:81], v[184:187], v[46:49]
	v_mfma_f32_16x16x32_bf16 v[42:45], v[94:97], v[184:187], v[42:45]
	v_mfma_f32_16x16x32_bf16 v[30:33], v[78:81], v[192:195], v[30:33]
	v_mfma_f32_16x16x32_bf16 v[26:29], v[94:97], v[192:195], v[26:29]
	v_mfma_f32_16x16x32_bf16 v[14:17], v[78:81], v[204:207], v[14:17]
	v_mfma_f32_16x16x32_bf16 v[10:13], v[94:97], v[204:207], v[10:13]
	v_mfma_f32_16x16x32_bf16 v[62:65], v[82:85], v[176:179], v[62:65]
	v_mfma_f32_16x16x32_bf16 v[58:61], v[98:101], v[176:179], v[58:61]
	v_mfma_f32_16x16x32_bf16 v[46:49], v[82:85], v[188:191], v[46:49]
	v_mfma_f32_16x16x32_bf16 v[42:45], v[98:101], v[188:191], v[42:45]
	v_mfma_f32_16x16x32_bf16 v[30:33], v[82:85], v[198:201], v[30:33]
	v_mfma_f32_16x16x32_bf16 v[26:29], v[98:101], v[198:201], v[26:29]
	v_mfma_f32_16x16x32_bf16 v[14:17], v[82:85], v[208:211], v[14:17]
	v_mfma_f32_16x16x32_bf16 v[10:13], v[98:101], v[208:211], v[10:13]
	v_mfma_f32_16x16x32_bf16 v[54:57], v[146:149], v[172:175], v[54:57]
	v_mfma_f32_16x16x32_bf16 v[50:53], v[154:157], v[172:175], v[50:53]
	v_mfma_f32_16x16x32_bf16 v[38:41], v[146:149], v[184:187], v[38:41]
	v_mfma_f32_16x16x32_bf16 v[34:37], v[154:157], v[184:187], v[34:37]
	v_mfma_f32_16x16x32_bf16 v[22:25], v[146:149], v[192:195], v[22:25]
	v_mfma_f32_16x16x32_bf16 v[18:21], v[154:157], v[192:195], v[18:21]
	v_mfma_f32_16x16x32_bf16 v[6:9], v[146:149], v[204:207], v[6:9]
	v_mfma_f32_16x16x32_bf16 v[2:5], v[154:157], v[204:207], v[2:5]
	v_mfma_f32_16x16x32_bf16 v[54:57], v[150:153], v[176:179], v[54:57]
	v_mfma_f32_16x16x32_bf16 v[50:53], v[158:161], v[176:179], v[50:53]
	v_mfma_f32_16x16x32_bf16 v[38:41], v[150:153], v[188:191], v[38:41]
	v_mfma_f32_16x16x32_bf16 v[34:37], v[158:161], v[188:191], v[34:37]
	v_mfma_f32_16x16x32_bf16 v[22:25], v[150:153], v[198:201], v[22:25]
	v_mfma_f32_16x16x32_bf16 v[18:21], v[158:161], v[198:201], v[18:21]
	v_mfma_f32_16x16x32_bf16 v[6:9], v[150:153], v[208:211], v[6:9]
	v_mfma_f32_16x16x32_bf16 v[2:5], v[158:161], v[208:211], v[2:5]
	s_barrier
	s_add_i32 s88, 0, 0x18000
	s_add_i32 s89, 0, 0x1c000
	v_add_u32_e32 v98, s88, v181
	v_add_u32_e32 v158, s89, v181
	ds_read_b128 v[78:81], v98
	ds_read_b128 v[82:85], v98 offset:1024
	ds_read_b128 v[94:97], v98 offset:2048
	ds_read_b128 v[98:101], v98 offset:3072
	ds_read_b128 v[146:149], v158
	ds_read_b128 v[150:153], v158 offset:1024
	ds_read_b128 v[154:157], v158 offset:2048
	ds_read_b128 v[158:161], v158 offset:3072
	s_add_u32 s38, s38, 0x100000
	s_addc_u32 s39, s39, 0
	s_mov_b32 m0, s79
	v_lshl_add_u64 v[218:219], s[38:39], 0, v[162:163]
	ds_read_b128 v[172:175], v183 offset:32768
	ds_read_b128 v[176:179], v183 offset:33792
	ds_read_b128 v[184:187], v183 offset:34816
	ds_read_b128 v[188:191], v183 offset:35840
	ds_read_b128 v[192:195], v183 offset:36864
	ds_read_b128 v[198:201], v183 offset:37888
	ds_read_b128 v[204:207], v183 offset:38912
	ds_read_b128 v[208:211], v183 offset:39936
	global_load_lds_dwordx4 v[218:219], off
	v_lshl_add_u64 v[218:219], s[38:39], 0, v[164:165]
	s_mov_b32 m0, s80
	s_nop 0
	global_load_lds_dwordx4 v[218:219], off
	s_waitcnt vmcnt(8)
	s_waitcnt lgkmcnt(0)
	s_barrier
	s_waitcnt lgkmcnt(0)
	v_mfma_f32_16x16x32_bf16 v[142:145], v[78:81], v[172:175], v[142:145]
	v_mfma_f32_16x16x32_bf16 v[138:141], v[94:97], v[172:175], v[138:141]
	v_mfma_f32_16x16x32_bf16 v[126:129], v[78:81], v[184:187], v[126:129]
	v_mfma_f32_16x16x32_bf16 v[122:125], v[94:97], v[184:187], v[122:125]
	v_mfma_f32_16x16x32_bf16 v[110:113], v[78:81], v[192:195], v[110:113]
	v_mfma_f32_16x16x32_bf16 v[106:109], v[94:97], v[192:195], v[106:109]
	v_mfma_f32_16x16x32_bf16 v[86:89], v[78:81], v[204:207], v[86:89]
	v_mfma_f32_16x16x32_bf16 v[74:77], v[94:97], v[204:207], v[74:77]
	v_mfma_f32_16x16x32_bf16 v[142:145], v[82:85], v[176:179], v[142:145]
	v_mfma_f32_16x16x32_bf16 v[138:141], v[98:101], v[176:179], v[138:141]
	v_mfma_f32_16x16x32_bf16 v[126:129], v[82:85], v[188:191], v[126:129]
	v_mfma_f32_16x16x32_bf16 v[122:125], v[98:101], v[188:191], v[122:125]
	v_mfma_f32_16x16x32_bf16 v[110:113], v[82:85], v[198:201], v[110:113]
	v_mfma_f32_16x16x32_bf16 v[106:109], v[98:101], v[198:201], v[106:109]
	v_mfma_f32_16x16x32_bf16 v[86:89], v[82:85], v[208:211], v[86:89]
	v_mfma_f32_16x16x32_bf16 v[74:77], v[98:101], v[208:211], v[74:77]
	v_mfma_f32_16x16x32_bf16 v[134:137], v[146:149], v[172:175], v[134:137]
	v_mfma_f32_16x16x32_bf16 v[130:133], v[154:157], v[172:175], v[130:133]
	v_mfma_f32_16x16x32_bf16 v[118:121], v[146:149], v[184:187], v[118:121]
	v_mfma_f32_16x16x32_bf16 v[114:117], v[154:157], v[184:187], v[114:117]
	v_mfma_f32_16x16x32_bf16 v[102:105], v[146:149], v[192:195], v[102:105]
	v_mfma_f32_16x16x32_bf16 v[90:93], v[154:157], v[192:195], v[90:93]
	v_mfma_f32_16x16x32_bf16 v[70:73], v[146:149], v[204:207], v[70:73]
	v_mfma_f32_16x16x32_bf16 v[66:69], v[154:157], v[204:207], v[66:69]
	v_mfma_f32_16x16x32_bf16 v[134:137], v[150:153], v[176:179], v[134:137]
	v_mfma_f32_16x16x32_bf16 v[130:133], v[158:161], v[176:179], v[130:133]
	v_mfma_f32_16x16x32_bf16 v[118:121], v[150:153], v[188:191], v[118:121]
	v_mfma_f32_16x16x32_bf16 v[114:117], v[158:161], v[188:191], v[114:117]
	v_mfma_f32_16x16x32_bf16 v[102:105], v[150:153], v[198:201], v[102:105]
	v_mfma_f32_16x16x32_bf16 v[90:93], v[158:161], v[198:201], v[90:93]
	v_mfma_f32_16x16x32_bf16 v[70:73], v[150:153], v[208:211], v[70:73]
	v_mfma_f32_16x16x32_bf16 v[66:69], v[158:161], v[208:211], v[66:69]
	s_barrier
; #define PG8_STAGE(bufoff, gbase, voff) do { _Pragma("unroll") for (int _i = 0; _i < 2; ++_i) \
;         __builtin_amdgcn_global_load_lds((const unsigned*)((const char*)(gbase) + (voff)[_i]), (LAS unsigned*)(lds + (bufoff) + ldsw + _i * 8192), 16, 0, 0); } while (0)
; #define PG8_LDA(dst, b, h) do { _Pragma("unroll") for (int m = 0; m < 4; ++m) _Pragma("unroll") for (int k = 0; k < 2; ++k) dst[m][k] = *(const LAS bf16x8*)(lds + PG8_SA(b, h) + aoff + m * 2048 + k * 1024); } while (0)
; #define PG8_MMA(ai, bj, At, Bt) do { __builtin_amdgcn_s_setprio(1); _Pragma("unroll") for (int m = 0; m < 4; ++m) _Pragma("unroll") for (int n = 0; n < 2; ++n) _Pragma("unroll") for (int k = 0; k < 2; ++k) \
;         acc[ai][bj][m][n] = __builtin_amdgcn_mfma_f32_16x16x32_bf16(Bt[n][k], At[m][k], acc[ai][bj][m][n], 0, 0, 0); __builtin_amdgcn_s_setprio(0); } while (0)
; #define PG8_WAIT_V(n) asm volatile("s_waitcnt vmcnt(" #n ")" ::: "memory")
; #define PG8_WAIT_L(n) asm volatile("s_waitcnt lgkmcnt(" #n ")" ::: "memory")
; #define PG8_BAR __builtin_amdgcn_s_barrier()
; #define PG8_SCHED __builtin_amdgcn_sched_barrier(0)
; #define PG8_LDA(dst, b, h) do { _Pragma("unroll") for (int m = 0; m < 4; ++m) _Pragma("unroll") for (int k = 0; k < 2; ++k) dst[m][k] = *(const LAS bf16x8*)(lds + PG8_SA(b, h) + aoff + m * 2048 + k * 1024); } while (0)
; #define PG8_MMA(ai, bj, At, Bt) do { __builtin_amdgcn_s_setprio(1); _Pragma("unroll") for (int m = 0; m < 4; ++m) _Pragma("unroll") for (int n = 0; n < 2; ++n) _Pragma("unroll") for (int k = 0; k < 2; ++k) \
;         acc[ai][bj][m][n] = __builtin_amdgcn_mfma_f32_16x16x32_bf16(Bt[n][k], At[m][k], acc[ai][bj][m][n], 0, 0, 0); __builtin_amdgcn_s_setprio(0); } while (0)
; #define PG8_WAIT_V(n) asm volatile("s_waitcnt vmcnt(" #n ")" ::: "memory")
; #define PG8_WAIT_L(n) asm volatile("s_waitcnt lgkmcnt(" #n ")" ::: "memory")
; #define PG8_BAR __builtin_amdgcn_s_barrier()
; template <class Epi, class Sched>
; DI void gemm_phase(LAS unsigned char* lds, const Gemm g, const Sched& S, const Epi& E) {
;     ...
;             PG8_LDA(At, 1, 1); PG8_STAGE(PG8_SB(1, 0), b3, voffB); PG8_STAGE(PG8_SB(1, 1), b3 + hstepB, voffB); PG8_STAGE(PG8_SA(1, 0), a3, voffA);
;             PG8_WAIT_V(8); PG8_WAIT_L(0); PG8_BAR; PG8_MMA(1, 0, At, B0); PG8_MMA(1, 1, At, B1); PG8_BAR; PG8_SCHED;
;         }
;         if (wr == 0) PG8_BAR;
	s_add_i32 s38, s88, s16
	v_lshl_add_u64 v[202:203], v[202:203], 0, s[26:27]
	s_mov_b32 m0, s38
	ds_read_b128 v[172:175], v183 offset:49152
	ds_read_b128 v[176:179], v183 offset:50176
	ds_read_b128 v[184:187], v183 offset:51200
	ds_read_b128 v[188:191], v183 offset:52224
	ds_read_b128 v[192:195], v183 offset:53248
	ds_read_b128 v[198:201], v183 offset:54272
	ds_read_b128 v[204:207], v183 offset:55296
	ds_read_b128 v[208:211], v183 offset:56320
	global_load_lds_dwordx4 v[202:203], off
	s_add_i32 m0, s38, 0x2000
	s_add_u32 s36, s36, 0x100080
	v_lshl_add_u64 v[202:203], v[212:213], 0, s[26:27]
	s_addc_u32 s37, s37, 0
	s_add_i32 s38, s89, s16
	global_load_lds_dwordx4 v[202:203], off
	v_lshl_add_u64 v[202:203], s[36:37], 0, v[0:1]
	s_mov_b32 m0, s38
	s_nop 0
	global_load_lds_dwordx4 v[202:203], off
	v_lshl_add_u64 v[202:203], s[36:37], 0, v[166:167]
	s_add_i32 m0, s38, 0x2000
	s_nop 0
	global_load_lds_dwordx4 v[202:203], off
	v_lshl_add_u64 v[202:203], v[214:215], 0, s[26:27]
	s_mov_b32 m0, s82
	s_nop 0
	global_load_lds_dwordx4 v[202:203], off
	v_lshl_add_u64 v[202:203], v[216:217], 0, s[26:27]
	s_mov_b32 m0, s83
	s_nop 0
	global_load_lds_dwordx4 v[202:203], off
	s_waitcnt vmcnt(8)
	s_waitcnt lgkmcnt(0)
	s_barrier
	s_waitcnt lgkmcnt(0)
	v_mfma_f32_16x16x32_bf16 v[62:65], v[78:81], v[172:175], v[62:65]
	v_mfma_f32_16x16x32_bf16 v[58:61], v[94:97], v[172:175], v[58:61]
	v_mfma_f32_16x16x32_bf16 v[46:49], v[78:81], v[184:187], v[46:49]
	v_mfma_f32_16x16x32_bf16 v[42:45], v[94:97], v[184:187], v[42:45]
	v_mfma_f32_16x16x32_bf16 v[30:33], v[78:81], v[192:195], v[30:33]
	v_mfma_f32_16x16x32_bf16 v[26:29], v[94:97], v[192:195], v[26:29]
	v_mfma_f32_16x16x32_bf16 v[14:17], v[78:81], v[204:207], v[14:17]
	v_mfma_f32_16x16x32_bf16 v[10:13], v[94:97], v[204:207], v[10:13]
	v_mfma_f32_16x16x32_bf16 v[62:65], v[82:85], v[176:179], v[62:65]
	v_mfma_f32_16x16x32_bf16 v[58:61], v[98:101], v[176:179], v[58:61]
	v_mfma_f32_16x16x32_bf16 v[46:49], v[82:85], v[188:191], v[46:49]
	v_mfma_f32_16x16x32_bf16 v[42:45], v[98:101], v[188:191], v[42:45]
	v_mfma_f32_16x16x32_bf16 v[30:33], v[82:85], v[198:201], v[30:33]
	v_mfma_f32_16x16x32_bf16 v[26:29], v[98:101], v[198:201], v[26:29]
	v_mfma_f32_16x16x32_bf16 v[14:17], v[82:85], v[208:211], v[14:17]
	v_mfma_f32_16x16x32_bf16 v[10:13], v[98:101], v[208:211], v[10:13]
	v_mfma_f32_16x16x32_bf16 v[54:57], v[146:149], v[172:175], v[54:57]
	v_mfma_f32_16x16x32_bf16 v[50:53], v[154:157], v[172:175], v[50:53]
	v_mfma_f32_16x16x32_bf16 v[38:41], v[146:149], v[184:187], v[38:41]
	v_mfma_f32_16x16x32_bf16 v[34:37], v[154:157], v[184:187], v[34:37]
	v_mfma_f32_16x16x32_bf16 v[22:25], v[146:149], v[192:195], v[22:25]
	v_mfma_f32_16x16x32_bf16 v[18:21], v[154:157], v[192:195], v[18:21]
	v_mfma_f32_16x16x32_bf16 v[6:9], v[146:149], v[204:207], v[6:9]
	v_mfma_f32_16x16x32_bf16 v[2:5], v[154:157], v[204:207], v[2:5]
	v_mfma_f32_16x16x32_bf16 v[54:57], v[150:153], v[176:179], v[54:57]
	v_mfma_f32_16x16x32_bf16 v[50:53], v[158:161], v[176:179], v[50:53]
	v_mfma_f32_16x16x32_bf16 v[38:41], v[150:153], v[188:191], v[38:41]
	v_mfma_f32_16x16x32_bf16 v[34:37], v[158:161], v[188:191], v[34:37]
	v_mfma_f32_16x16x32_bf16 v[22:25], v[150:153], v[198:201], v[22:25]
	v_mfma_f32_16x16x32_bf16 v[18:21], v[158:161], v[198:201], v[18:21]
	v_mfma_f32_16x16x32_bf16 v[6:9], v[150:153], v[208:211], v[6:9]
	v_mfma_f32_16x16x32_bf16 v[2:5], v[158:161], v[208:211], v[2:5]
	s_barrier
	s_add_i32 s87, s87, 2
	s_add_u32 s50, s50, 0x100
	s_addc_u32 s51, s51, 0
	s_add_u32 s71, s71, 0x100
	s_addc_u32 s73, s73, 0
	s_cmp_gt_u32 s87, 61
	s_cbranch_scc0 .LBB0_1440
	s_and_b64 vcc, exec, s[68:69]
	s_cbranch_vccz .LBB0_1443
	s_barrier
